# phase 20 final norm rewritten with all row loads up front; sqrt denorm-scaling and max canonicalize folded in gates epilogue
# baseline (speedup 1.0000x reference)
.LBB0_92:
	s_andn2_b64 vcc, exec, s[0:1]
	s_cbranch_vccnz .LBB0_97
	v_mov_b32_e32 v16, v163
	s_waitcnt vmcnt(0)
	v_mov_b32_e32 v0, v163
	v_readlane_b32 s0, v250, 7
	v_ashrrev_i32_e32 v0, 6, v0
	s_nop 0
	v_add_u32_e32 v40, s0, v0
	v_cmp_gt_i32_e32 vcc, s47, v40
	s_and_saveexec_b64 s[0:1], vcc
	v_readlane_b32 s6, v254, 2
	v_readlane_b32 s8, v254, 4
	v_readlane_b32 s7, v254, 3
	v_readlane_b32 s9, v254, 5
	s_movk_i32 s5, 0x1000
	s_movk_i32 s10, 0x3000
	s_cbranch_execz .LBB0_96
	v_readlane_b32 s4, v249, 14
	v_readlane_b32 s5, v249, 15
	v_readlane_b32 s6, v249, 12
	v_readlane_b32 s7, v249, 13
	v_readlane_b32 s8, v249, 6
	v_readlane_b32 s9, v249, 7
	v_readlane_b32 s10, v250, 7
	v_readlane_b32 s12, v255, 4
	v_lshrrev_b32_e32 v164, 6, v163
	v_and_b32_e32 v165, 63, v163
	v_readfirstlane_b32 s18, v164
	v_lshlrev_b32_e32 v150, 4, v165
	v_lshlrev_b32_e32 v151, 5, v165
	v_xor_b32_e32 v144, 32, v165
	v_lshlrev_b32_e32 v144, 2, v144
	v_xor_b32_e32 v145, 16, v165
	v_lshlrev_b32_e32 v145, 2, v145
	v_xor_b32_e32 v146, 8, v165
	v_lshlrev_b32_e32 v146, 2, v146
	v_xor_b32_e32 v147, 4, v165
	v_lshlrev_b32_e32 v147, 2, v147
	v_xor_b32_e32 v148, 2, v165
	v_lshlrev_b32_e32 v148, 2, v148
	v_xor_b32_e32 v149, 1, v165
	v_lshlrev_b32_e32 v149, 2, v149
	s_add_u32 s10, s10, s18
	global_load_dwordx4 v[128:131], v151, s[8:9] offset:0
	global_load_dwordx4 v[132:135], v151, s[8:9] offset:16
	global_load_dwordx4 v[136:139], v151, s[8:9] offset:2048
	global_load_dwordx4 v[140:143], v151, s[8:9] offset:2064
	s_cmp_lt_u32 s10, 0x800
	s_cbranch_scc0 .Lp20_done
.Lp20_group:
	s_lshl_b32 s18, s10, 15
	s_add_u32 s18, s18, 0x18001000
	s_add_u32 s14, s4, s18
	s_addc_u32 s15, s5, 0
	s_lshl_b32 s18, s10, 16
	s_add_u32 s18, s18, 0x1000
	s_add_u32 s16, s6, s18
	s_addc_u32 s17, s7, 0
	global_load_dwordx4 v[0:3], v150, s[14:15] offset:-4096 nt
	global_load_dwordx4 v[4:7], v150, s[14:15] offset:-3072 nt
	global_load_dwordx4 v[8:11], v150, s[14:15] offset:-2048 nt
	global_load_dwordx4 v[12:15], v150, s[14:15] offset:-1024 nt
	global_load_dwordx4 v[16:19], v150, s[14:15] offset:0 nt
	global_load_dwordx4 v[20:23], v150, s[14:15] offset:1024 nt
	global_load_dwordx4 v[24:27], v150, s[14:15] offset:2048 nt
	global_load_dwordx4 v[28:31], v150, s[14:15] offset:3072 nt
	s_add_u32 s14, s14, 0x2000
	s_addc_u32 s15, s15, 0
	global_load_dwordx4 v[32:35], v150, s[14:15] offset:-4096 nt
	global_load_dwordx4 v[36:39], v150, s[14:15] offset:-3072 nt
	global_load_dwordx4 v[40:43], v150, s[14:15] offset:-2048 nt
	global_load_dwordx4 v[44:47], v150, s[14:15] offset:-1024 nt
	global_load_dwordx4 v[48:51], v150, s[14:15] offset:0 nt
	global_load_dwordx4 v[52:55], v150, s[14:15] offset:1024 nt
	global_load_dwordx4 v[56:59], v150, s[14:15] offset:2048 nt
	global_load_dwordx4 v[60:63], v150, s[14:15] offset:3072 nt
	s_add_u32 s14, s14, 0x2000
	s_addc_u32 s15, s15, 0
	global_load_dwordx4 v[64:67], v150, s[14:15] offset:-4096 nt
	global_load_dwordx4 v[68:71], v150, s[14:15] offset:-3072 nt
	global_load_dwordx4 v[72:75], v150, s[14:15] offset:-2048 nt
	global_load_dwordx4 v[76:79], v150, s[14:15] offset:-1024 nt
	global_load_dwordx4 v[80:83], v150, s[14:15] offset:0 nt
	global_load_dwordx4 v[84:87], v150, s[14:15] offset:1024 nt
	global_load_dwordx4 v[88:91], v150, s[14:15] offset:2048 nt
	global_load_dwordx4 v[92:95], v150, s[14:15] offset:3072 nt
	s_add_u32 s14, s14, 0x2000
	s_addc_u32 s15, s15, 0
	global_load_dwordx4 v[96:99], v150, s[14:15] offset:-4096 nt
	global_load_dwordx4 v[100:103], v150, s[14:15] offset:-3072 nt
	global_load_dwordx4 v[104:107], v150, s[14:15] offset:-2048 nt
	global_load_dwordx4 v[108:111], v150, s[14:15] offset:-1024 nt
	global_load_dwordx4 v[112:115], v150, s[14:15] offset:0 nt
	global_load_dwordx4 v[116:119], v150, s[14:15] offset:1024 nt
	global_load_dwordx4 v[120:123], v150, s[14:15] offset:2048 nt
	global_load_dwordx4 v[124:127], v150, s[14:15] offset:3072 nt
	s_waitcnt vmcnt(30)
	v_lshlrev_b32_e32 v164, 16, v0
	v_and_b32_e32 v165, 0xffff0000, v0
	v_lshlrev_b32_e32 v166, 16, v1
	v_and_b32_e32 v167, 0xffff0000, v1
	v_lshlrev_b32_e32 v168, 16, v2
	v_and_b32_e32 v169, 0xffff0000, v2
	v_lshlrev_b32_e32 v170, 16, v3
	v_and_b32_e32 v171, 0xffff0000, v3
	v_lshlrev_b32_e32 v172, 16, v4
	v_and_b32_e32 v173, 0xffff0000, v4
	v_lshlrev_b32_e32 v174, 16, v5
	v_and_b32_e32 v175, 0xffff0000, v5
	v_lshlrev_b32_e32 v176, 16, v6
	v_and_b32_e32 v177, 0xffff0000, v6
	v_lshlrev_b32_e32 v178, 16, v7
	v_and_b32_e32 v179, 0xffff0000, v7
	s_waitcnt vmcnt(28)
	v_lshlrev_b32_e32 v180, 16, v8
	v_and_b32_e32 v181, 0xffff0000, v8
	v_lshlrev_b32_e32 v182, 16, v9
	v_and_b32_e32 v183, 0xffff0000, v9
	v_lshlrev_b32_e32 v184, 16, v10
	v_and_b32_e32 v185, 0xffff0000, v10
	v_lshlrev_b32_e32 v186, 16, v11
	v_and_b32_e32 v187, 0xffff0000, v11
	v_lshlrev_b32_e32 v188, 16, v12
	v_and_b32_e32 v189, 0xffff0000, v12
	v_lshlrev_b32_e32 v190, 16, v13
	v_and_b32_e32 v191, 0xffff0000, v13
	v_lshlrev_b32_e32 v192, 16, v14
	v_and_b32_e32 v193, 0xffff0000, v14
	v_lshlrev_b32_e32 v194, 16, v15
	v_and_b32_e32 v195, 0xffff0000, v15
	v_pk_mul_f32 v[196:197], v[164:165], v[164:165]
	v_pk_mul_f32 v[198:199], v[180:181], v[180:181]
	v_pk_fma_f32 v[196:197], v[166:167], v[166:167], v[196:197]
	v_pk_fma_f32 v[198:199], v[182:183], v[182:183], v[198:199]
	v_pk_fma_f32 v[196:197], v[168:169], v[168:169], v[196:197]
	v_pk_fma_f32 v[198:199], v[184:185], v[184:185], v[198:199]
	v_pk_fma_f32 v[196:197], v[170:171], v[170:171], v[196:197]
	v_pk_fma_f32 v[198:199], v[186:187], v[186:187], v[198:199]
	v_pk_fma_f32 v[196:197], v[172:173], v[172:173], v[196:197]
	v_pk_fma_f32 v[198:199], v[188:189], v[188:189], v[198:199]
	v_pk_fma_f32 v[196:197], v[174:175], v[174:175], v[196:197]
	v_pk_fma_f32 v[198:199], v[190:191], v[190:191], v[198:199]
	v_pk_fma_f32 v[196:197], v[176:177], v[176:177], v[196:197]
	v_pk_fma_f32 v[198:199], v[192:193], v[192:193], v[198:199]
	v_pk_fma_f32 v[196:197], v[178:179], v[178:179], v[196:197]
	v_pk_fma_f32 v[198:199], v[194:195], v[194:195], v[198:199]
	v_add_f32_e32 v196, v196, v197
	v_add_f32_e32 v198, v198, v199
	ds_bpermute_b32 v200, v144, v196
	ds_bpermute_b32 v201, v144, v198
	s_waitcnt lgkmcnt(1)
	v_add_f32_e32 v196, v196, v200
	s_waitcnt lgkmcnt(0)
	v_add_f32_e32 v198, v198, v201
	ds_bpermute_b32 v200, v145, v196
	ds_bpermute_b32 v201, v145, v198
	s_waitcnt lgkmcnt(1)
	v_add_f32_e32 v196, v196, v200
	s_waitcnt lgkmcnt(0)
	v_add_f32_e32 v198, v198, v201
	ds_bpermute_b32 v200, v146, v196
	ds_bpermute_b32 v201, v146, v198
	s_waitcnt lgkmcnt(1)
	v_add_f32_e32 v196, v196, v200
	s_waitcnt lgkmcnt(0)
	v_add_f32_e32 v198, v198, v201
	ds_bpermute_b32 v200, v147, v196
	ds_bpermute_b32 v201, v147, v198
	s_waitcnt lgkmcnt(1)
	v_add_f32_e32 v196, v196, v200
	s_waitcnt lgkmcnt(0)
	v_add_f32_e32 v198, v198, v201
	ds_bpermute_b32 v200, v148, v196
	ds_bpermute_b32 v201, v148, v198
	s_waitcnt lgkmcnt(1)
	v_add_f32_e32 v196, v196, v200
	s_waitcnt lgkmcnt(0)
	v_add_f32_e32 v198, v198, v201
	ds_bpermute_b32 v200, v149, v196
	ds_bpermute_b32 v201, v149, v198
	s_waitcnt lgkmcnt(1)
	v_add_f32_e32 v196, v196, v200
	s_waitcnt lgkmcnt(0)
	v_add_f32_e32 v198, v198, v201
	v_mov_b32_e32 v200, 0x358637bd
	v_fmamk_f32 v196, v196, 0x3a800000, v200
	v_fmamk_f32 v198, v198, 0x3a800000, v200
	v_rsq_f32_e32 v202, v196
	v_rsq_f32_e32 v204, v198
	v_pk_mul_f32 v[164:165], v[164:165], v[202:203] op_sel_hi:[1,0]
	v_pk_mul_f32 v[166:167], v[166:167], v[202:203] op_sel_hi:[1,0]
	v_pk_mul_f32 v[168:169], v[168:169], v[202:203] op_sel_hi:[1,0]
	v_pk_mul_f32 v[170:171], v[170:171], v[202:203] op_sel_hi:[1,0]
	v_pk_mul_f32 v[172:173], v[172:173], v[202:203] op_sel_hi:[1,0]
	v_pk_mul_f32 v[174:175], v[174:175], v[202:203] op_sel_hi:[1,0]
	v_pk_mul_f32 v[176:177], v[176:177], v[202:203] op_sel_hi:[1,0]
	v_pk_mul_f32 v[178:179], v[178:179], v[202:203] op_sel_hi:[1,0]
	v_pk_mul_f32 v[164:165], v[128:129], v[164:165]
	v_pk_mul_f32 v[166:167], v[130:131], v[166:167]
	v_pk_mul_f32 v[168:169], v[132:133], v[168:169]
	v_pk_mul_f32 v[170:171], v[134:135], v[170:171]
	v_pk_mul_f32 v[172:173], v[136:137], v[172:173]
	v_pk_mul_f32 v[174:175], v[138:139], v[174:175]
	v_pk_mul_f32 v[176:177], v[140:141], v[176:177]
	v_pk_mul_f32 v[178:179], v[142:143], v[178:179]
	global_store_dwordx4 v151, v[164:167], s[16:17] offset:-4096
	global_store_dwordx4 v151, v[168:171], s[16:17] offset:-4080
	global_store_dwordx4 v151, v[172:175], s[16:17] offset:-2048
	global_store_dwordx4 v151, v[176:179], s[16:17] offset:-2032
	v_pk_mul_f32 v[180:181], v[180:181], v[204:205] op_sel_hi:[1,0]
	v_pk_mul_f32 v[182:183], v[182:183], v[204:205] op_sel_hi:[1,0]
	v_pk_mul_f32 v[184:185], v[184:185], v[204:205] op_sel_hi:[1,0]
	v_pk_mul_f32 v[186:187], v[186:187], v[204:205] op_sel_hi:[1,0]
	v_pk_mul_f32 v[188:189], v[188:189], v[204:205] op_sel_hi:[1,0]
	v_pk_mul_f32 v[190:191], v[190:191], v[204:205] op_sel_hi:[1,0]
	v_pk_mul_f32 v[192:193], v[192:193], v[204:205] op_sel_hi:[1,0]
	v_pk_mul_f32 v[194:195], v[194:195], v[204:205] op_sel_hi:[1,0]
	v_pk_mul_f32 v[180:181], v[128:129], v[180:181]
	v_pk_mul_f32 v[182:183], v[130:131], v[182:183]
	v_pk_mul_f32 v[184:185], v[132:133], v[184:185]
	v_pk_mul_f32 v[186:187], v[134:135], v[186:187]
	v_pk_mul_f32 v[188:189], v[136:137], v[188:189]
	v_pk_mul_f32 v[190:191], v[138:139], v[190:191]
	v_pk_mul_f32 v[192:193], v[140:141], v[192:193]
	v_pk_mul_f32 v[194:195], v[142:143], v[194:195]
	global_store_dwordx4 v151, v[180:183], s[16:17] offset:0
	global_store_dwordx4 v151, v[184:187], s[16:17] offset:16
	global_store_dwordx4 v151, v[188:191], s[16:17] offset:2048
	global_store_dwordx4 v151, v[192:195], s[16:17] offset:2064
	s_waitcnt vmcnt(34)
	v_lshlrev_b32_e32 v164, 16, v16
	v_and_b32_e32 v165, 0xffff0000, v16
	v_lshlrev_b32_e32 v166, 16, v17
	v_and_b32_e32 v167, 0xffff0000, v17
	v_lshlrev_b32_e32 v168, 16, v18
	v_and_b32_e32 v169, 0xffff0000, v18
	v_lshlrev_b32_e32 v170, 16, v19
	v_and_b32_e32 v171, 0xffff0000, v19
	v_lshlrev_b32_e32 v172, 16, v20
	v_and_b32_e32 v173, 0xffff0000, v20
	v_lshlrev_b32_e32 v174, 16, v21
	v_and_b32_e32 v175, 0xffff0000, v21
	v_lshlrev_b32_e32 v176, 16, v22
	v_and_b32_e32 v177, 0xffff0000, v22
	v_lshlrev_b32_e32 v178, 16, v23
	v_and_b32_e32 v179, 0xffff0000, v23
	s_waitcnt vmcnt(32)
	v_lshlrev_b32_e32 v180, 16, v24
	v_and_b32_e32 v181, 0xffff0000, v24
	v_lshlrev_b32_e32 v182, 16, v25
	v_and_b32_e32 v183, 0xffff0000, v25
	v_lshlrev_b32_e32 v184, 16, v26
	v_and_b32_e32 v185, 0xffff0000, v26
	v_lshlrev_b32_e32 v186, 16, v27
	v_and_b32_e32 v187, 0xffff0000, v27
	v_lshlrev_b32_e32 v188, 16, v28
	v_and_b32_e32 v189, 0xffff0000, v28
	v_lshlrev_b32_e32 v190, 16, v29
	v_and_b32_e32 v191, 0xffff0000, v29
	v_lshlrev_b32_e32 v192, 16, v30
	v_and_b32_e32 v193, 0xffff0000, v30
	v_lshlrev_b32_e32 v194, 16, v31
	v_and_b32_e32 v195, 0xffff0000, v31
	v_pk_mul_f32 v[196:197], v[164:165], v[164:165]
	v_pk_mul_f32 v[198:199], v[180:181], v[180:181]
	v_pk_fma_f32 v[196:197], v[166:167], v[166:167], v[196:197]
	v_pk_fma_f32 v[198:199], v[182:183], v[182:183], v[198:199]
	v_pk_fma_f32 v[196:197], v[168:169], v[168:169], v[196:197]
	v_pk_fma_f32 v[198:199], v[184:185], v[184:185], v[198:199]
	v_pk_fma_f32 v[196:197], v[170:171], v[170:171], v[196:197]
	v_pk_fma_f32 v[198:199], v[186:187], v[186:187], v[198:199]
	v_pk_fma_f32 v[196:197], v[172:173], v[172:173], v[196:197]
	v_pk_fma_f32 v[198:199], v[188:189], v[188:189], v[198:199]
	v_pk_fma_f32 v[196:197], v[174:175], v[174:175], v[196:197]
	v_pk_fma_f32 v[198:199], v[190:191], v[190:191], v[198:199]
	v_pk_fma_f32 v[196:197], v[176:177], v[176:177], v[196:197]
	v_pk_fma_f32 v[198:199], v[192:193], v[192:193], v[198:199]
	v_pk_fma_f32 v[196:197], v[178:179], v[178:179], v[196:197]
	v_pk_fma_f32 v[198:199], v[194:195], v[194:195], v[198:199]
	v_add_f32_e32 v196, v196, v197
	v_add_f32_e32 v198, v198, v199
	ds_bpermute_b32 v200, v144, v196
	ds_bpermute_b32 v201, v144, v198
	s_waitcnt lgkmcnt(1)
	v_add_f32_e32 v196, v196, v200
	s_waitcnt lgkmcnt(0)
	v_add_f32_e32 v198, v198, v201
	ds_bpermute_b32 v200, v145, v196
	ds_bpermute_b32 v201, v145, v198
	s_waitcnt lgkmcnt(1)
	v_add_f32_e32 v196, v196, v200
	s_waitcnt lgkmcnt(0)
	v_add_f32_e32 v198, v198, v201
	ds_bpermute_b32 v200, v146, v196
	ds_bpermute_b32 v201, v146, v198
	s_waitcnt lgkmcnt(1)
	v_add_f32_e32 v196, v196, v200
	s_waitcnt lgkmcnt(0)
	v_add_f32_e32 v198, v198, v201
	ds_bpermute_b32 v200, v147, v196
	ds_bpermute_b32 v201, v147, v198
	s_waitcnt lgkmcnt(1)
	v_add_f32_e32 v196, v196, v200
	s_waitcnt lgkmcnt(0)
	v_add_f32_e32 v198, v198, v201
	ds_bpermute_b32 v200, v148, v196
	ds_bpermute_b32 v201, v148, v198
	s_waitcnt lgkmcnt(1)
	v_add_f32_e32 v196, v196, v200
	s_waitcnt lgkmcnt(0)
	v_add_f32_e32 v198, v198, v201
	ds_bpermute_b32 v200, v149, v196
	ds_bpermute_b32 v201, v149, v198
	s_waitcnt lgkmcnt(1)
	v_add_f32_e32 v196, v196, v200
	s_waitcnt lgkmcnt(0)
	v_add_f32_e32 v198, v198, v201
	v_mov_b32_e32 v200, 0x358637bd
	v_fmamk_f32 v196, v196, 0x3a800000, v200
	v_fmamk_f32 v198, v198, 0x3a800000, v200
	v_rsq_f32_e32 v202, v196
	v_rsq_f32_e32 v204, v198
	s_add_u32 s16, s16, 0x2000
	s_addc_u32 s17, s17, 0
	v_pk_mul_f32 v[164:165], v[164:165], v[202:203] op_sel_hi:[1,0]
	v_pk_mul_f32 v[166:167], v[166:167], v[202:203] op_sel_hi:[1,0]
	v_pk_mul_f32 v[168:169], v[168:169], v[202:203] op_sel_hi:[1,0]
	v_pk_mul_f32 v[170:171], v[170:171], v[202:203] op_sel_hi:[1,0]
	v_pk_mul_f32 v[172:173], v[172:173], v[202:203] op_sel_hi:[1,0]
	v_pk_mul_f32 v[174:175], v[174:175], v[202:203] op_sel_hi:[1,0]
	v_pk_mul_f32 v[176:177], v[176:177], v[202:203] op_sel_hi:[1,0]
	v_pk_mul_f32 v[178:179], v[178:179], v[202:203] op_sel_hi:[1,0]
	v_pk_mul_f32 v[164:165], v[128:129], v[164:165]
	v_pk_mul_f32 v[166:167], v[130:131], v[166:167]
	v_pk_mul_f32 v[168:169], v[132:133], v[168:169]
	v_pk_mul_f32 v[170:171], v[134:135], v[170:171]
	v_pk_mul_f32 v[172:173], v[136:137], v[172:173]
	v_pk_mul_f32 v[174:175], v[138:139], v[174:175]
	v_pk_mul_f32 v[176:177], v[140:141], v[176:177]
	v_pk_mul_f32 v[178:179], v[142:143], v[178:179]
	global_store_dwordx4 v151, v[164:167], s[16:17] offset:-4096
	global_store_dwordx4 v151, v[168:171], s[16:17] offset:-4080
	global_store_dwordx4 v151, v[172:175], s[16:17] offset:-2048
	global_store_dwordx4 v151, v[176:179], s[16:17] offset:-2032
	v_pk_mul_f32 v[180:181], v[180:181], v[204:205] op_sel_hi:[1,0]
	v_pk_mul_f32 v[182:183], v[182:183], v[204:205] op_sel_hi:[1,0]
	v_pk_mul_f32 v[184:185], v[184:185], v[204:205] op_sel_hi:[1,0]
	v_pk_mul_f32 v[186:187], v[186:187], v[204:205] op_sel_hi:[1,0]
	v_pk_mul_f32 v[188:189], v[188:189], v[204:205] op_sel_hi:[1,0]
	v_pk_mul_f32 v[190:191], v[190:191], v[204:205] op_sel_hi:[1,0]
	v_pk_mul_f32 v[192:193], v[192:193], v[204:205] op_sel_hi:[1,0]
	v_pk_mul_f32 v[194:195], v[194:195], v[204:205] op_sel_hi:[1,0]
	v_pk_mul_f32 v[180:181], v[128:129], v[180:181]
	v_pk_mul_f32 v[182:183], v[130:131], v[182:183]
	v_pk_mul_f32 v[184:185], v[132:133], v[184:185]
	v_pk_mul_f32 v[186:187], v[134:135], v[186:187]
	v_pk_mul_f32 v[188:189], v[136:137], v[188:189]
	v_pk_mul_f32 v[190:191], v[138:139], v[190:191]
	v_pk_mul_f32 v[192:193], v[140:141], v[192:193]
	v_pk_mul_f32 v[194:195], v[142:143], v[194:195]
	global_store_dwordx4 v151, v[180:183], s[16:17] offset:0
	global_store_dwordx4 v151, v[184:187], s[16:17] offset:16
	global_store_dwordx4 v151, v[188:191], s[16:17] offset:2048
	global_store_dwordx4 v151, v[192:195], s[16:17] offset:2064
	s_waitcnt vmcnt(38)
	v_lshlrev_b32_e32 v164, 16, v32
	v_and_b32_e32 v165, 0xffff0000, v32
	v_lshlrev_b32_e32 v166, 16, v33
	v_and_b32_e32 v167, 0xffff0000, v33
	v_lshlrev_b32_e32 v168, 16, v34
	v_and_b32_e32 v169, 0xffff0000, v34
	v_lshlrev_b32_e32 v170, 16, v35
	v_and_b32_e32 v171, 0xffff0000, v35
	v_lshlrev_b32_e32 v172, 16, v36
	v_and_b32_e32 v173, 0xffff0000, v36
	v_lshlrev_b32_e32 v174, 16, v37
	v_and_b32_e32 v175, 0xffff0000, v37
	v_lshlrev_b32_e32 v176, 16, v38
	v_and_b32_e32 v177, 0xffff0000, v38
	v_lshlrev_b32_e32 v178, 16, v39
	v_and_b32_e32 v179, 0xffff0000, v39
	s_waitcnt vmcnt(36)
	v_lshlrev_b32_e32 v180, 16, v40
	v_and_b32_e32 v181, 0xffff0000, v40
	v_lshlrev_b32_e32 v182, 16, v41
	v_and_b32_e32 v183, 0xffff0000, v41
	v_lshlrev_b32_e32 v184, 16, v42
	v_and_b32_e32 v185, 0xffff0000, v42
	v_lshlrev_b32_e32 v186, 16, v43
	v_and_b32_e32 v187, 0xffff0000, v43
	v_lshlrev_b32_e32 v188, 16, v44
	v_and_b32_e32 v189, 0xffff0000, v44
	v_lshlrev_b32_e32 v190, 16, v45
	v_and_b32_e32 v191, 0xffff0000, v45
	v_lshlrev_b32_e32 v192, 16, v46
	v_and_b32_e32 v193, 0xffff0000, v46
	v_lshlrev_b32_e32 v194, 16, v47
	v_and_b32_e32 v195, 0xffff0000, v47
	v_pk_mul_f32 v[196:197], v[164:165], v[164:165]
	v_pk_mul_f32 v[198:199], v[180:181], v[180:181]
	v_pk_fma_f32 v[196:197], v[166:167], v[166:167], v[196:197]
	v_pk_fma_f32 v[198:199], v[182:183], v[182:183], v[198:199]
	v_pk_fma_f32 v[196:197], v[168:169], v[168:169], v[196:197]
	v_pk_fma_f32 v[198:199], v[184:185], v[184:185], v[198:199]
	v_pk_fma_f32 v[196:197], v[170:171], v[170:171], v[196:197]
	v_pk_fma_f32 v[198:199], v[186:187], v[186:187], v[198:199]
	v_pk_fma_f32 v[196:197], v[172:173], v[172:173], v[196:197]
	v_pk_fma_f32 v[198:199], v[188:189], v[188:189], v[198:199]
	v_pk_fma_f32 v[196:197], v[174:175], v[174:175], v[196:197]
	v_pk_fma_f32 v[198:199], v[190:191], v[190:191], v[198:199]
	v_pk_fma_f32 v[196:197], v[176:177], v[176:177], v[196:197]
	v_pk_fma_f32 v[198:199], v[192:193], v[192:193], v[198:199]
	v_pk_fma_f32 v[196:197], v[178:179], v[178:179], v[196:197]
	v_pk_fma_f32 v[198:199], v[194:195], v[194:195], v[198:199]
	v_add_f32_e32 v196, v196, v197
	v_add_f32_e32 v198, v198, v199
	ds_bpermute_b32 v200, v144, v196
	ds_bpermute_b32 v201, v144, v198
	s_waitcnt lgkmcnt(1)
	v_add_f32_e32 v196, v196, v200
	s_waitcnt lgkmcnt(0)
	v_add_f32_e32 v198, v198, v201
	ds_bpermute_b32 v200, v145, v196
	ds_bpermute_b32 v201, v145, v198
	s_waitcnt lgkmcnt(1)
	v_add_f32_e32 v196, v196, v200
	s_waitcnt lgkmcnt(0)
	v_add_f32_e32 v198, v198, v201
	ds_bpermute_b32 v200, v146, v196
	ds_bpermute_b32 v201, v146, v198
	s_waitcnt lgkmcnt(1)
	v_add_f32_e32 v196, v196, v200
	s_waitcnt lgkmcnt(0)
	v_add_f32_e32 v198, v198, v201
	ds_bpermute_b32 v200, v147, v196
	ds_bpermute_b32 v201, v147, v198
	s_waitcnt lgkmcnt(1)
	v_add_f32_e32 v196, v196, v200
	s_waitcnt lgkmcnt(0)
	v_add_f32_e32 v198, v198, v201
	ds_bpermute_b32 v200, v148, v196
	ds_bpermute_b32 v201, v148, v198
	s_waitcnt lgkmcnt(1)
	v_add_f32_e32 v196, v196, v200
	s_waitcnt lgkmcnt(0)
	v_add_f32_e32 v198, v198, v201
	ds_bpermute_b32 v200, v149, v196
	ds_bpermute_b32 v201, v149, v198
	s_waitcnt lgkmcnt(1)
	v_add_f32_e32 v196, v196, v200
	s_waitcnt lgkmcnt(0)
	v_add_f32_e32 v198, v198, v201
	v_mov_b32_e32 v200, 0x358637bd
	v_fmamk_f32 v196, v196, 0x3a800000, v200
	v_fmamk_f32 v198, v198, 0x3a800000, v200
	v_rsq_f32_e32 v202, v196
	v_rsq_f32_e32 v204, v198
	s_add_u32 s16, s16, 0x2000
	s_addc_u32 s17, s17, 0
	v_pk_mul_f32 v[164:165], v[164:165], v[202:203] op_sel_hi:[1,0]
	v_pk_mul_f32 v[166:167], v[166:167], v[202:203] op_sel_hi:[1,0]
	v_pk_mul_f32 v[168:169], v[168:169], v[202:203] op_sel_hi:[1,0]
	v_pk_mul_f32 v[170:171], v[170:171], v[202:203] op_sel_hi:[1,0]
	v_pk_mul_f32 v[172:173], v[172:173], v[202:203] op_sel_hi:[1,0]
	v_pk_mul_f32 v[174:175], v[174:175], v[202:203] op_sel_hi:[1,0]
	v_pk_mul_f32 v[176:177], v[176:177], v[202:203] op_sel_hi:[1,0]
	v_pk_mul_f32 v[178:179], v[178:179], v[202:203] op_sel_hi:[1,0]
	v_pk_mul_f32 v[164:165], v[128:129], v[164:165]
	v_pk_mul_f32 v[166:167], v[130:131], v[166:167]
	v_pk_mul_f32 v[168:169], v[132:133], v[168:169]
	v_pk_mul_f32 v[170:171], v[134:135], v[170:171]
	v_pk_mul_f32 v[172:173], v[136:137], v[172:173]
	v_pk_mul_f32 v[174:175], v[138:139], v[174:175]
	v_pk_mul_f32 v[176:177], v[140:141], v[176:177]
	v_pk_mul_f32 v[178:179], v[142:143], v[178:179]
	global_store_dwordx4 v151, v[164:167], s[16:17] offset:-4096
	global_store_dwordx4 v151, v[168:171], s[16:17] offset:-4080
	global_store_dwordx4 v151, v[172:175], s[16:17] offset:-2048
	global_store_dwordx4 v151, v[176:179], s[16:17] offset:-2032
	v_pk_mul_f32 v[180:181], v[180:181], v[204:205] op_sel_hi:[1,0]
	v_pk_mul_f32 v[182:183], v[182:183], v[204:205] op_sel_hi:[1,0]
	v_pk_mul_f32 v[184:185], v[184:185], v[204:205] op_sel_hi:[1,0]
	v_pk_mul_f32 v[186:187], v[186:187], v[204:205] op_sel_hi:[1,0]
	v_pk_mul_f32 v[188:189], v[188:189], v[204:205] op_sel_hi:[1,0]
	v_pk_mul_f32 v[190:191], v[190:191], v[204:205] op_sel_hi:[1,0]
	v_pk_mul_f32 v[192:193], v[192:193], v[204:205] op_sel_hi:[1,0]
	v_pk_mul_f32 v[194:195], v[194:195], v[204:205] op_sel_hi:[1,0]
	v_pk_mul_f32 v[180:181], v[128:129], v[180:181]
	v_pk_mul_f32 v[182:183], v[130:131], v[182:183]
	v_pk_mul_f32 v[184:185], v[132:133], v[184:185]
	v_pk_mul_f32 v[186:187], v[134:135], v[186:187]
	v_pk_mul_f32 v[188:189], v[136:137], v[188:189]
	v_pk_mul_f32 v[190:191], v[138:139], v[190:191]
	v_pk_mul_f32 v[192:193], v[140:141], v[192:193]
	v_pk_mul_f32 v[194:195], v[142:143], v[194:195]
	global_store_dwordx4 v151, v[180:183], s[16:17] offset:0
	global_store_dwordx4 v151, v[184:187], s[16:17] offset:16
	global_store_dwordx4 v151, v[188:191], s[16:17] offset:2048
	global_store_dwordx4 v151, v[192:195], s[16:17] offset:2064
	s_waitcnt vmcnt(42)
	v_lshlrev_b32_e32 v164, 16, v48
	v_and_b32_e32 v165, 0xffff0000, v48
	v_lshlrev_b32_e32 v166, 16, v49
	v_and_b32_e32 v167, 0xffff0000, v49
	v_lshlrev_b32_e32 v168, 16, v50
	v_and_b32_e32 v169, 0xffff0000, v50
	v_lshlrev_b32_e32 v170, 16, v51
	v_and_b32_e32 v171, 0xffff0000, v51
	v_lshlrev_b32_e32 v172, 16, v52
	v_and_b32_e32 v173, 0xffff0000, v52
	v_lshlrev_b32_e32 v174, 16, v53
	v_and_b32_e32 v175, 0xffff0000, v53
	v_lshlrev_b32_e32 v176, 16, v54
	v_and_b32_e32 v177, 0xffff0000, v54
	v_lshlrev_b32_e32 v178, 16, v55
	v_and_b32_e32 v179, 0xffff0000, v55
	s_waitcnt vmcnt(40)
	v_lshlrev_b32_e32 v180, 16, v56
	v_and_b32_e32 v181, 0xffff0000, v56
	v_lshlrev_b32_e32 v182, 16, v57
	v_and_b32_e32 v183, 0xffff0000, v57
	v_lshlrev_b32_e32 v184, 16, v58
	v_and_b32_e32 v185, 0xffff0000, v58
	v_lshlrev_b32_e32 v186, 16, v59
	v_and_b32_e32 v187, 0xffff0000, v59
	v_lshlrev_b32_e32 v188, 16, v60
	v_and_b32_e32 v189, 0xffff0000, v60
	v_lshlrev_b32_e32 v190, 16, v61
	v_and_b32_e32 v191, 0xffff0000, v61
	v_lshlrev_b32_e32 v192, 16, v62
	v_and_b32_e32 v193, 0xffff0000, v62
	v_lshlrev_b32_e32 v194, 16, v63
	v_and_b32_e32 v195, 0xffff0000, v63
	v_pk_mul_f32 v[196:197], v[164:165], v[164:165]
	v_pk_mul_f32 v[198:199], v[180:181], v[180:181]
	v_pk_fma_f32 v[196:197], v[166:167], v[166:167], v[196:197]
	v_pk_fma_f32 v[198:199], v[182:183], v[182:183], v[198:199]
	v_pk_fma_f32 v[196:197], v[168:169], v[168:169], v[196:197]
	v_pk_fma_f32 v[198:199], v[184:185], v[184:185], v[198:199]
	v_pk_fma_f32 v[196:197], v[170:171], v[170:171], v[196:197]
	v_pk_fma_f32 v[198:199], v[186:187], v[186:187], v[198:199]
	v_pk_fma_f32 v[196:197], v[172:173], v[172:173], v[196:197]
	v_pk_fma_f32 v[198:199], v[188:189], v[188:189], v[198:199]
	v_pk_fma_f32 v[196:197], v[174:175], v[174:175], v[196:197]
	v_pk_fma_f32 v[198:199], v[190:191], v[190:191], v[198:199]
	v_pk_fma_f32 v[196:197], v[176:177], v[176:177], v[196:197]
	v_pk_fma_f32 v[198:199], v[192:193], v[192:193], v[198:199]
	v_pk_fma_f32 v[196:197], v[178:179], v[178:179], v[196:197]
	v_pk_fma_f32 v[198:199], v[194:195], v[194:195], v[198:199]
	v_add_f32_e32 v196, v196, v197
	v_add_f32_e32 v198, v198, v199
	ds_bpermute_b32 v200, v144, v196
	ds_bpermute_b32 v201, v144, v198
	s_waitcnt lgkmcnt(1)
	v_add_f32_e32 v196, v196, v200
	s_waitcnt lgkmcnt(0)
	v_add_f32_e32 v198, v198, v201
	ds_bpermute_b32 v200, v145, v196
	ds_bpermute_b32 v201, v145, v198
	s_waitcnt lgkmcnt(1)
	v_add_f32_e32 v196, v196, v200
	s_waitcnt lgkmcnt(0)
	v_add_f32_e32 v198, v198, v201
	ds_bpermute_b32 v200, v146, v196
	ds_bpermute_b32 v201, v146, v198
	s_waitcnt lgkmcnt(1)
	v_add_f32_e32 v196, v196, v200
	s_waitcnt lgkmcnt(0)
	v_add_f32_e32 v198, v198, v201
	ds_bpermute_b32 v200, v147, v196
	ds_bpermute_b32 v201, v147, v198
	s_waitcnt lgkmcnt(1)
	v_add_f32_e32 v196, v196, v200
	s_waitcnt lgkmcnt(0)
	v_add_f32_e32 v198, v198, v201
	ds_bpermute_b32 v200, v148, v196
	ds_bpermute_b32 v201, v148, v198
	s_waitcnt lgkmcnt(1)
	v_add_f32_e32 v196, v196, v200
	s_waitcnt lgkmcnt(0)
	v_add_f32_e32 v198, v198, v201
	ds_bpermute_b32 v200, v149, v196
	ds_bpermute_b32 v201, v149, v198
	s_waitcnt lgkmcnt(1)
	v_add_f32_e32 v196, v196, v200
	s_waitcnt lgkmcnt(0)
	v_add_f32_e32 v198, v198, v201
	v_mov_b32_e32 v200, 0x358637bd
	v_fmamk_f32 v196, v196, 0x3a800000, v200
	v_fmamk_f32 v198, v198, 0x3a800000, v200
	v_rsq_f32_e32 v202, v196
	v_rsq_f32_e32 v204, v198
	s_add_u32 s16, s16, 0x2000
	s_addc_u32 s17, s17, 0
	v_pk_mul_f32 v[164:165], v[164:165], v[202:203] op_sel_hi:[1,0]
	v_pk_mul_f32 v[166:167], v[166:167], v[202:203] op_sel_hi:[1,0]
	v_pk_mul_f32 v[168:169], v[168:169], v[202:203] op_sel_hi:[1,0]
	v_pk_mul_f32 v[170:171], v[170:171], v[202:203] op_sel_hi:[1,0]
	v_pk_mul_f32 v[172:173], v[172:173], v[202:203] op_sel_hi:[1,0]
	v_pk_mul_f32 v[174:175], v[174:175], v[202:203] op_sel_hi:[1,0]
	v_pk_mul_f32 v[176:177], v[176:177], v[202:203] op_sel_hi:[1,0]
	v_pk_mul_f32 v[178:179], v[178:179], v[202:203] op_sel_hi:[1,0]
	v_pk_mul_f32 v[164:165], v[128:129], v[164:165]
	v_pk_mul_f32 v[166:167], v[130:131], v[166:167]
	v_pk_mul_f32 v[168:169], v[132:133], v[168:169]
	v_pk_mul_f32 v[170:171], v[134:135], v[170:171]
	v_pk_mul_f32 v[172:173], v[136:137], v[172:173]
	v_pk_mul_f32 v[174:175], v[138:139], v[174:175]
	v_pk_mul_f32 v[176:177], v[140:141], v[176:177]
	v_pk_mul_f32 v[178:179], v[142:143], v[178:179]
	global_store_dwordx4 v151, v[164:167], s[16:17] offset:-4096
	global_store_dwordx4 v151, v[168:171], s[16:17] offset:-4080
	global_store_dwordx4 v151, v[172:175], s[16:17] offset:-2048
	global_store_dwordx4 v151, v[176:179], s[16:17] offset:-2032
	v_pk_mul_f32 v[180:181], v[180:181], v[204:205] op_sel_hi:[1,0]
	v_pk_mul_f32 v[182:183], v[182:183], v[204:205] op_sel_hi:[1,0]
	v_pk_mul_f32 v[184:185], v[184:185], v[204:205] op_sel_hi:[1,0]
	v_pk_mul_f32 v[186:187], v[186:187], v[204:205] op_sel_hi:[1,0]
	v_pk_mul_f32 v[188:189], v[188:189], v[204:205] op_sel_hi:[1,0]
	v_pk_mul_f32 v[190:191], v[190:191], v[204:205] op_sel_hi:[1,0]
	v_pk_mul_f32 v[192:193], v[192:193], v[204:205] op_sel_hi:[1,0]
	v_pk_mul_f32 v[194:195], v[194:195], v[204:205] op_sel_hi:[1,0]
	v_pk_mul_f32 v[180:181], v[128:129], v[180:181]
	v_pk_mul_f32 v[182:183], v[130:131], v[182:183]
	v_pk_mul_f32 v[184:185], v[132:133], v[184:185]
	v_pk_mul_f32 v[186:187], v[134:135], v[186:187]
	v_pk_mul_f32 v[188:189], v[136:137], v[188:189]
	v_pk_mul_f32 v[190:191], v[138:139], v[190:191]
	v_pk_mul_f32 v[192:193], v[140:141], v[192:193]
	v_pk_mul_f32 v[194:195], v[142:143], v[194:195]
	global_store_dwordx4 v151, v[180:183], s[16:17] offset:0
	global_store_dwordx4 v151, v[184:187], s[16:17] offset:16
	global_store_dwordx4 v151, v[188:191], s[16:17] offset:2048
	global_store_dwordx4 v151, v[192:195], s[16:17] offset:2064
	s_waitcnt vmcnt(46)
	v_lshlrev_b32_e32 v164, 16, v64
	v_and_b32_e32 v165, 0xffff0000, v64
	v_lshlrev_b32_e32 v166, 16, v65
	v_and_b32_e32 v167, 0xffff0000, v65
	v_lshlrev_b32_e32 v168, 16, v66
	v_and_b32_e32 v169, 0xffff0000, v66
	v_lshlrev_b32_e32 v170, 16, v67
	v_and_b32_e32 v171, 0xffff0000, v67
	v_lshlrev_b32_e32 v172, 16, v68
	v_and_b32_e32 v173, 0xffff0000, v68
	v_lshlrev_b32_e32 v174, 16, v69
	v_and_b32_e32 v175, 0xffff0000, v69
	v_lshlrev_b32_e32 v176, 16, v70
	v_and_b32_e32 v177, 0xffff0000, v70
	v_lshlrev_b32_e32 v178, 16, v71
	v_and_b32_e32 v179, 0xffff0000, v71
	s_waitcnt vmcnt(44)
	v_lshlrev_b32_e32 v180, 16, v72
	v_and_b32_e32 v181, 0xffff0000, v72
	v_lshlrev_b32_e32 v182, 16, v73
	v_and_b32_e32 v183, 0xffff0000, v73
	v_lshlrev_b32_e32 v184, 16, v74
	v_and_b32_e32 v185, 0xffff0000, v74
	v_lshlrev_b32_e32 v186, 16, v75
	v_and_b32_e32 v187, 0xffff0000, v75
	v_lshlrev_b32_e32 v188, 16, v76
	v_and_b32_e32 v189, 0xffff0000, v76
	v_lshlrev_b32_e32 v190, 16, v77
	v_and_b32_e32 v191, 0xffff0000, v77
	v_lshlrev_b32_e32 v192, 16, v78
	v_and_b32_e32 v193, 0xffff0000, v78
	v_lshlrev_b32_e32 v194, 16, v79
	v_and_b32_e32 v195, 0xffff0000, v79
	v_pk_mul_f32 v[196:197], v[164:165], v[164:165]
	v_pk_mul_f32 v[198:199], v[180:181], v[180:181]
	v_pk_fma_f32 v[196:197], v[166:167], v[166:167], v[196:197]
	v_pk_fma_f32 v[198:199], v[182:183], v[182:183], v[198:199]
	v_pk_fma_f32 v[196:197], v[168:169], v[168:169], v[196:197]
	v_pk_fma_f32 v[198:199], v[184:185], v[184:185], v[198:199]
	v_pk_fma_f32 v[196:197], v[170:171], v[170:171], v[196:197]
	v_pk_fma_f32 v[198:199], v[186:187], v[186:187], v[198:199]
	v_pk_fma_f32 v[196:197], v[172:173], v[172:173], v[196:197]
	v_pk_fma_f32 v[198:199], v[188:189], v[188:189], v[198:199]
	v_pk_fma_f32 v[196:197], v[174:175], v[174:175], v[196:197]
	v_pk_fma_f32 v[198:199], v[190:191], v[190:191], v[198:199]
	v_pk_fma_f32 v[196:197], v[176:177], v[176:177], v[196:197]
	v_pk_fma_f32 v[198:199], v[192:193], v[192:193], v[198:199]
	v_pk_fma_f32 v[196:197], v[178:179], v[178:179], v[196:197]
	v_pk_fma_f32 v[198:199], v[194:195], v[194:195], v[198:199]
	v_add_f32_e32 v196, v196, v197
	v_add_f32_e32 v198, v198, v199
	ds_bpermute_b32 v200, v144, v196
	ds_bpermute_b32 v201, v144, v198
	s_waitcnt lgkmcnt(1)
	v_add_f32_e32 v196, v196, v200
	s_waitcnt lgkmcnt(0)
	v_add_f32_e32 v198, v198, v201
	ds_bpermute_b32 v200, v145, v196
	ds_bpermute_b32 v201, v145, v198
	s_waitcnt lgkmcnt(1)
	v_add_f32_e32 v196, v196, v200
	s_waitcnt lgkmcnt(0)
	v_add_f32_e32 v198, v198, v201
	ds_bpermute_b32 v200, v146, v196
	ds_bpermute_b32 v201, v146, v198
	s_waitcnt lgkmcnt(1)
	v_add_f32_e32 v196, v196, v200
	s_waitcnt lgkmcnt(0)
	v_add_f32_e32 v198, v198, v201
	ds_bpermute_b32 v200, v147, v196
	ds_bpermute_b32 v201, v147, v198
	s_waitcnt lgkmcnt(1)
	v_add_f32_e32 v196, v196, v200
	s_waitcnt lgkmcnt(0)
	v_add_f32_e32 v198, v198, v201
	ds_bpermute_b32 v200, v148, v196
	ds_bpermute_b32 v201, v148, v198
	s_waitcnt lgkmcnt(1)
	v_add_f32_e32 v196, v196, v200
	s_waitcnt lgkmcnt(0)
	v_add_f32_e32 v198, v198, v201
	ds_bpermute_b32 v200, v149, v196
	ds_bpermute_b32 v201, v149, v198
	s_waitcnt lgkmcnt(1)
	v_add_f32_e32 v196, v196, v200
	s_waitcnt lgkmcnt(0)
	v_add_f32_e32 v198, v198, v201
	v_mov_b32_e32 v200, 0x358637bd
	v_fmamk_f32 v196, v196, 0x3a800000, v200
	v_fmamk_f32 v198, v198, 0x3a800000, v200
	v_rsq_f32_e32 v202, v196
	v_rsq_f32_e32 v204, v198
	s_add_u32 s16, s16, 0x2000
	s_addc_u32 s17, s17, 0
	v_pk_mul_f32 v[164:165], v[164:165], v[202:203] op_sel_hi:[1,0]
	v_pk_mul_f32 v[166:167], v[166:167], v[202:203] op_sel_hi:[1,0]
	v_pk_mul_f32 v[168:169], v[168:169], v[202:203] op_sel_hi:[1,0]
	v_pk_mul_f32 v[170:171], v[170:171], v[202:203] op_sel_hi:[1,0]
	v_pk_mul_f32 v[172:173], v[172:173], v[202:203] op_sel_hi:[1,0]
	v_pk_mul_f32 v[174:175], v[174:175], v[202:203] op_sel_hi:[1,0]
	v_pk_mul_f32 v[176:177], v[176:177], v[202:203] op_sel_hi:[1,0]
	v_pk_mul_f32 v[178:179], v[178:179], v[202:203] op_sel_hi:[1,0]
	v_pk_mul_f32 v[164:165], v[128:129], v[164:165]
	v_pk_mul_f32 v[166:167], v[130:131], v[166:167]
	v_pk_mul_f32 v[168:169], v[132:133], v[168:169]
	v_pk_mul_f32 v[170:171], v[134:135], v[170:171]
	v_pk_mul_f32 v[172:173], v[136:137], v[172:173]
	v_pk_mul_f32 v[174:175], v[138:139], v[174:175]
	v_pk_mul_f32 v[176:177], v[140:141], v[176:177]
	v_pk_mul_f32 v[178:179], v[142:143], v[178:179]
	global_store_dwordx4 v151, v[164:167], s[16:17] offset:-4096
	global_store_dwordx4 v151, v[168:171], s[16:17] offset:-4080
	global_store_dwordx4 v151, v[172:175], s[16:17] offset:-2048
	global_store_dwordx4 v151, v[176:179], s[16:17] offset:-2032
	v_pk_mul_f32 v[180:181], v[180:181], v[204:205] op_sel_hi:[1,0]
	v_pk_mul_f32 v[182:183], v[182:183], v[204:205] op_sel_hi:[1,0]
	v_pk_mul_f32 v[184:185], v[184:185], v[204:205] op_sel_hi:[1,0]
	v_pk_mul_f32 v[186:187], v[186:187], v[204:205] op_sel_hi:[1,0]
	v_pk_mul_f32 v[188:189], v[188:189], v[204:205] op_sel_hi:[1,0]
	v_pk_mul_f32 v[190:191], v[190:191], v[204:205] op_sel_hi:[1,0]
	v_pk_mul_f32 v[192:193], v[192:193], v[204:205] op_sel_hi:[1,0]
	v_pk_mul_f32 v[194:195], v[194:195], v[204:205] op_sel_hi:[1,0]
	v_pk_mul_f32 v[180:181], v[128:129], v[180:181]
	v_pk_mul_f32 v[182:183], v[130:131], v[182:183]
	v_pk_mul_f32 v[184:185], v[132:133], v[184:185]
	v_pk_mul_f32 v[186:187], v[134:135], v[186:187]
	v_pk_mul_f32 v[188:189], v[136:137], v[188:189]
	v_pk_mul_f32 v[190:191], v[138:139], v[190:191]
	v_pk_mul_f32 v[192:193], v[140:141], v[192:193]
	v_pk_mul_f32 v[194:195], v[142:143], v[194:195]
	global_store_dwordx4 v151, v[180:183], s[16:17] offset:0
	global_store_dwordx4 v151, v[184:187], s[16:17] offset:16
	global_store_dwordx4 v151, v[188:191], s[16:17] offset:2048
	global_store_dwordx4 v151, v[192:195], s[16:17] offset:2064
	s_waitcnt vmcnt(50)
	v_lshlrev_b32_e32 v164, 16, v80
	v_and_b32_e32 v165, 0xffff0000, v80
	v_lshlrev_b32_e32 v166, 16, v81
	v_and_b32_e32 v167, 0xffff0000, v81
	v_lshlrev_b32_e32 v168, 16, v82
	v_and_b32_e32 v169, 0xffff0000, v82
	v_lshlrev_b32_e32 v170, 16, v83
	v_and_b32_e32 v171, 0xffff0000, v83
	v_lshlrev_b32_e32 v172, 16, v84
	v_and_b32_e32 v173, 0xffff0000, v84
	v_lshlrev_b32_e32 v174, 16, v85
	v_and_b32_e32 v175, 0xffff0000, v85
	v_lshlrev_b32_e32 v176, 16, v86
	v_and_b32_e32 v177, 0xffff0000, v86
	v_lshlrev_b32_e32 v178, 16, v87
	v_and_b32_e32 v179, 0xffff0000, v87
	s_waitcnt vmcnt(48)
	v_lshlrev_b32_e32 v180, 16, v88
	v_and_b32_e32 v181, 0xffff0000, v88
	v_lshlrev_b32_e32 v182, 16, v89
	v_and_b32_e32 v183, 0xffff0000, v89
	v_lshlrev_b32_e32 v184, 16, v90
	v_and_b32_e32 v185, 0xffff0000, v90
	v_lshlrev_b32_e32 v186, 16, v91
	v_and_b32_e32 v187, 0xffff0000, v91
	v_lshlrev_b32_e32 v188, 16, v92
	v_and_b32_e32 v189, 0xffff0000, v92
	v_lshlrev_b32_e32 v190, 16, v93
	v_and_b32_e32 v191, 0xffff0000, v93
	v_lshlrev_b32_e32 v192, 16, v94
	v_and_b32_e32 v193, 0xffff0000, v94
	v_lshlrev_b32_e32 v194, 16, v95
	v_and_b32_e32 v195, 0xffff0000, v95
	v_pk_mul_f32 v[196:197], v[164:165], v[164:165]
	v_pk_mul_f32 v[198:199], v[180:181], v[180:181]
	v_pk_fma_f32 v[196:197], v[166:167], v[166:167], v[196:197]
	v_pk_fma_f32 v[198:199], v[182:183], v[182:183], v[198:199]
	v_pk_fma_f32 v[196:197], v[168:169], v[168:169], v[196:197]
	v_pk_fma_f32 v[198:199], v[184:185], v[184:185], v[198:199]
	v_pk_fma_f32 v[196:197], v[170:171], v[170:171], v[196:197]
	v_pk_fma_f32 v[198:199], v[186:187], v[186:187], v[198:199]
	v_pk_fma_f32 v[196:197], v[172:173], v[172:173], v[196:197]
	v_pk_fma_f32 v[198:199], v[188:189], v[188:189], v[198:199]
	v_pk_fma_f32 v[196:197], v[174:175], v[174:175], v[196:197]
	v_pk_fma_f32 v[198:199], v[190:191], v[190:191], v[198:199]
	v_pk_fma_f32 v[196:197], v[176:177], v[176:177], v[196:197]
	v_pk_fma_f32 v[198:199], v[192:193], v[192:193], v[198:199]
	v_pk_fma_f32 v[196:197], v[178:179], v[178:179], v[196:197]
	v_pk_fma_f32 v[198:199], v[194:195], v[194:195], v[198:199]
	v_add_f32_e32 v196, v196, v197
	v_add_f32_e32 v198, v198, v199
	ds_bpermute_b32 v200, v144, v196
	ds_bpermute_b32 v201, v144, v198
	s_waitcnt lgkmcnt(1)
	v_add_f32_e32 v196, v196, v200
	s_waitcnt lgkmcnt(0)
	v_add_f32_e32 v198, v198, v201
	ds_bpermute_b32 v200, v145, v196
	ds_bpermute_b32 v201, v145, v198
	s_waitcnt lgkmcnt(1)
	v_add_f32_e32 v196, v196, v200
	s_waitcnt lgkmcnt(0)
	v_add_f32_e32 v198, v198, v201
	ds_bpermute_b32 v200, v146, v196
	ds_bpermute_b32 v201, v146, v198
	s_waitcnt lgkmcnt(1)
	v_add_f32_e32 v196, v196, v200
	s_waitcnt lgkmcnt(0)
	v_add_f32_e32 v198, v198, v201
	ds_bpermute_b32 v200, v147, v196
	ds_bpermute_b32 v201, v147, v198
	s_waitcnt lgkmcnt(1)
	v_add_f32_e32 v196, v196, v200
	s_waitcnt lgkmcnt(0)
	v_add_f32_e32 v198, v198, v201
	ds_bpermute_b32 v200, v148, v196
	ds_bpermute_b32 v201, v148, v198
	s_waitcnt lgkmcnt(1)
	v_add_f32_e32 v196, v196, v200
	s_waitcnt lgkmcnt(0)
	v_add_f32_e32 v198, v198, v201
	ds_bpermute_b32 v200, v149, v196
	ds_bpermute_b32 v201, v149, v198
	s_waitcnt lgkmcnt(1)
	v_add_f32_e32 v196, v196, v200
	s_waitcnt lgkmcnt(0)
	v_add_f32_e32 v198, v198, v201
	v_mov_b32_e32 v200, 0x358637bd
	v_fmamk_f32 v196, v196, 0x3a800000, v200
	v_fmamk_f32 v198, v198, 0x3a800000, v200
	v_rsq_f32_e32 v202, v196
	v_rsq_f32_e32 v204, v198
	s_add_u32 s16, s16, 0x2000
	s_addc_u32 s17, s17, 0
	v_pk_mul_f32 v[164:165], v[164:165], v[202:203] op_sel_hi:[1,0]
	v_pk_mul_f32 v[166:167], v[166:167], v[202:203] op_sel_hi:[1,0]
	v_pk_mul_f32 v[168:169], v[168:169], v[202:203] op_sel_hi:[1,0]
	v_pk_mul_f32 v[170:171], v[170:171], v[202:203] op_sel_hi:[1,0]
	v_pk_mul_f32 v[172:173], v[172:173], v[202:203] op_sel_hi:[1,0]
	v_pk_mul_f32 v[174:175], v[174:175], v[202:203] op_sel_hi:[1,0]
	v_pk_mul_f32 v[176:177], v[176:177], v[202:203] op_sel_hi:[1,0]
	v_pk_mul_f32 v[178:179], v[178:179], v[202:203] op_sel_hi:[1,0]
	v_pk_mul_f32 v[164:165], v[128:129], v[164:165]
	v_pk_mul_f32 v[166:167], v[130:131], v[166:167]
	v_pk_mul_f32 v[168:169], v[132:133], v[168:169]
	v_pk_mul_f32 v[170:171], v[134:135], v[170:171]
	v_pk_mul_f32 v[172:173], v[136:137], v[172:173]
	v_pk_mul_f32 v[174:175], v[138:139], v[174:175]
	v_pk_mul_f32 v[176:177], v[140:141], v[176:177]
	v_pk_mul_f32 v[178:179], v[142:143], v[178:179]
	global_store_dwordx4 v151, v[164:167], s[16:17] offset:-4096
	global_store_dwordx4 v151, v[168:171], s[16:17] offset:-4080
	global_store_dwordx4 v151, v[172:175], s[16:17] offset:-2048
	global_store_dwordx4 v151, v[176:179], s[16:17] offset:-2032
	v_pk_mul_f32 v[180:181], v[180:181], v[204:205] op_sel_hi:[1,0]
	v_pk_mul_f32 v[182:183], v[182:183], v[204:205] op_sel_hi:[1,0]
	v_pk_mul_f32 v[184:185], v[184:185], v[204:205] op_sel_hi:[1,0]
	v_pk_mul_f32 v[186:187], v[186:187], v[204:205] op_sel_hi:[1,0]
	v_pk_mul_f32 v[188:189], v[188:189], v[204:205] op_sel_hi:[1,0]
	v_pk_mul_f32 v[190:191], v[190:191], v[204:205] op_sel_hi:[1,0]
	v_pk_mul_f32 v[192:193], v[192:193], v[204:205] op_sel_hi:[1,0]
	v_pk_mul_f32 v[194:195], v[194:195], v[204:205] op_sel_hi:[1,0]
	v_pk_mul_f32 v[180:181], v[128:129], v[180:181]
	v_pk_mul_f32 v[182:183], v[130:131], v[182:183]
	v_pk_mul_f32 v[184:185], v[132:133], v[184:185]
	v_pk_mul_f32 v[186:187], v[134:135], v[186:187]
	v_pk_mul_f32 v[188:189], v[136:137], v[188:189]
	v_pk_mul_f32 v[190:191], v[138:139], v[190:191]
	v_pk_mul_f32 v[192:193], v[140:141], v[192:193]
	v_pk_mul_f32 v[194:195], v[142:143], v[194:195]
	global_store_dwordx4 v151, v[180:183], s[16:17] offset:0
	global_store_dwordx4 v151, v[184:187], s[16:17] offset:16
	global_store_dwordx4 v151, v[188:191], s[16:17] offset:2048
	global_store_dwordx4 v151, v[192:195], s[16:17] offset:2064
	s_waitcnt vmcnt(54)
	v_lshlrev_b32_e32 v164, 16, v96
	v_and_b32_e32 v165, 0xffff0000, v96
	v_lshlrev_b32_e32 v166, 16, v97
	v_and_b32_e32 v167, 0xffff0000, v97
	v_lshlrev_b32_e32 v168, 16, v98
	v_and_b32_e32 v169, 0xffff0000, v98
	v_lshlrev_b32_e32 v170, 16, v99
	v_and_b32_e32 v171, 0xffff0000, v99
	v_lshlrev_b32_e32 v172, 16, v100
	v_and_b32_e32 v173, 0xffff0000, v100
	v_lshlrev_b32_e32 v174, 16, v101
	v_and_b32_e32 v175, 0xffff0000, v101
	v_lshlrev_b32_e32 v176, 16, v102
	v_and_b32_e32 v177, 0xffff0000, v102
	v_lshlrev_b32_e32 v178, 16, v103
	v_and_b32_e32 v179, 0xffff0000, v103
	s_waitcnt vmcnt(52)
	v_lshlrev_b32_e32 v180, 16, v104
	v_and_b32_e32 v181, 0xffff0000, v104
	v_lshlrev_b32_e32 v182, 16, v105
	v_and_b32_e32 v183, 0xffff0000, v105
	v_lshlrev_b32_e32 v184, 16, v106
	v_and_b32_e32 v185, 0xffff0000, v106
	v_lshlrev_b32_e32 v186, 16, v107
	v_and_b32_e32 v187, 0xffff0000, v107
	v_lshlrev_b32_e32 v188, 16, v108
	v_and_b32_e32 v189, 0xffff0000, v108
	v_lshlrev_b32_e32 v190, 16, v109
	v_and_b32_e32 v191, 0xffff0000, v109
	v_lshlrev_b32_e32 v192, 16, v110
	v_and_b32_e32 v193, 0xffff0000, v110
	v_lshlrev_b32_e32 v194, 16, v111
	v_and_b32_e32 v195, 0xffff0000, v111
	v_pk_mul_f32 v[196:197], v[164:165], v[164:165]
	v_pk_mul_f32 v[198:199], v[180:181], v[180:181]
	v_pk_fma_f32 v[196:197], v[166:167], v[166:167], v[196:197]
	v_pk_fma_f32 v[198:199], v[182:183], v[182:183], v[198:199]
	v_pk_fma_f32 v[196:197], v[168:169], v[168:169], v[196:197]
	v_pk_fma_f32 v[198:199], v[184:185], v[184:185], v[198:199]
	v_pk_fma_f32 v[196:197], v[170:171], v[170:171], v[196:197]
	v_pk_fma_f32 v[198:199], v[186:187], v[186:187], v[198:199]
	v_pk_fma_f32 v[196:197], v[172:173], v[172:173], v[196:197]
	v_pk_fma_f32 v[198:199], v[188:189], v[188:189], v[198:199]
	v_pk_fma_f32 v[196:197], v[174:175], v[174:175], v[196:197]
	v_pk_fma_f32 v[198:199], v[190:191], v[190:191], v[198:199]
	v_pk_fma_f32 v[196:197], v[176:177], v[176:177], v[196:197]
	v_pk_fma_f32 v[198:199], v[192:193], v[192:193], v[198:199]
	v_pk_fma_f32 v[196:197], v[178:179], v[178:179], v[196:197]
	v_pk_fma_f32 v[198:199], v[194:195], v[194:195], v[198:199]
	v_add_f32_e32 v196, v196, v197
	v_add_f32_e32 v198, v198, v199
	ds_bpermute_b32 v200, v144, v196
	ds_bpermute_b32 v201, v144, v198
	s_waitcnt lgkmcnt(1)
	v_add_f32_e32 v196, v196, v200
	s_waitcnt lgkmcnt(0)
	v_add_f32_e32 v198, v198, v201
	ds_bpermute_b32 v200, v145, v196
	ds_bpermute_b32 v201, v145, v198
	s_waitcnt lgkmcnt(1)
	v_add_f32_e32 v196, v196, v200
	s_waitcnt lgkmcnt(0)
	v_add_f32_e32 v198, v198, v201
	ds_bpermute_b32 v200, v146, v196
	ds_bpermute_b32 v201, v146, v198
	s_waitcnt lgkmcnt(1)
	v_add_f32_e32 v196, v196, v200
	s_waitcnt lgkmcnt(0)
	v_add_f32_e32 v198, v198, v201
	ds_bpermute_b32 v200, v147, v196
	ds_bpermute_b32 v201, v147, v198
	s_waitcnt lgkmcnt(1)
	v_add_f32_e32 v196, v196, v200
	s_waitcnt lgkmcnt(0)
	v_add_f32_e32 v198, v198, v201
	ds_bpermute_b32 v200, v148, v196
	ds_bpermute_b32 v201, v148, v198
	s_waitcnt lgkmcnt(1)
	v_add_f32_e32 v196, v196, v200
	s_waitcnt lgkmcnt(0)
	v_add_f32_e32 v198, v198, v201
	ds_bpermute_b32 v200, v149, v196
	ds_bpermute_b32 v201, v149, v198
	s_waitcnt lgkmcnt(1)
	v_add_f32_e32 v196, v196, v200
	s_waitcnt lgkmcnt(0)
	v_add_f32_e32 v198, v198, v201
	v_mov_b32_e32 v200, 0x358637bd
	v_fmamk_f32 v196, v196, 0x3a800000, v200
	v_fmamk_f32 v198, v198, 0x3a800000, v200
	v_rsq_f32_e32 v202, v196
	v_rsq_f32_e32 v204, v198
	s_add_u32 s16, s16, 0x2000
	s_addc_u32 s17, s17, 0
	v_pk_mul_f32 v[164:165], v[164:165], v[202:203] op_sel_hi:[1,0]
	v_pk_mul_f32 v[166:167], v[166:167], v[202:203] op_sel_hi:[1,0]
	v_pk_mul_f32 v[168:169], v[168:169], v[202:203] op_sel_hi:[1,0]
	v_pk_mul_f32 v[170:171], v[170:171], v[202:203] op_sel_hi:[1,0]
	v_pk_mul_f32 v[172:173], v[172:173], v[202:203] op_sel_hi:[1,0]
	v_pk_mul_f32 v[174:175], v[174:175], v[202:203] op_sel_hi:[1,0]
	v_pk_mul_f32 v[176:177], v[176:177], v[202:203] op_sel_hi:[1,0]
	v_pk_mul_f32 v[178:179], v[178:179], v[202:203] op_sel_hi:[1,0]
	v_pk_mul_f32 v[164:165], v[128:129], v[164:165]
	v_pk_mul_f32 v[166:167], v[130:131], v[166:167]
	v_pk_mul_f32 v[168:169], v[132:133], v[168:169]
	v_pk_mul_f32 v[170:171], v[134:135], v[170:171]
	v_pk_mul_f32 v[172:173], v[136:137], v[172:173]
	v_pk_mul_f32 v[174:175], v[138:139], v[174:175]
	v_pk_mul_f32 v[176:177], v[140:141], v[176:177]
	v_pk_mul_f32 v[178:179], v[142:143], v[178:179]
	global_store_dwordx4 v151, v[164:167], s[16:17] offset:-4096
	global_store_dwordx4 v151, v[168:171], s[16:17] offset:-4080
	global_store_dwordx4 v151, v[172:175], s[16:17] offset:-2048
	global_store_dwordx4 v151, v[176:179], s[16:17] offset:-2032
	v_pk_mul_f32 v[180:181], v[180:181], v[204:205] op_sel_hi:[1,0]
	v_pk_mul_f32 v[182:183], v[182:183], v[204:205] op_sel_hi:[1,0]
	v_pk_mul_f32 v[184:185], v[184:185], v[204:205] op_sel_hi:[1,0]
	v_pk_mul_f32 v[186:187], v[186:187], v[204:205] op_sel_hi:[1,0]
	v_pk_mul_f32 v[188:189], v[188:189], v[204:205] op_sel_hi:[1,0]
	v_pk_mul_f32 v[190:191], v[190:191], v[204:205] op_sel_hi:[1,0]
	v_pk_mul_f32 v[192:193], v[192:193], v[204:205] op_sel_hi:[1,0]
	v_pk_mul_f32 v[194:195], v[194:195], v[204:205] op_sel_hi:[1,0]
	v_pk_mul_f32 v[180:181], v[128:129], v[180:181]
	v_pk_mul_f32 v[182:183], v[130:131], v[182:183]
	v_pk_mul_f32 v[184:185], v[132:133], v[184:185]
	v_pk_mul_f32 v[186:187], v[134:135], v[186:187]
	v_pk_mul_f32 v[188:189], v[136:137], v[188:189]
	v_pk_mul_f32 v[190:191], v[138:139], v[190:191]
	v_pk_mul_f32 v[192:193], v[140:141], v[192:193]
	v_pk_mul_f32 v[194:195], v[142:143], v[194:195]
	global_store_dwordx4 v151, v[180:183], s[16:17] offset:0
	global_store_dwordx4 v151, v[184:187], s[16:17] offset:16
	global_store_dwordx4 v151, v[188:191], s[16:17] offset:2048
	global_store_dwordx4 v151, v[192:195], s[16:17] offset:2064
	s_waitcnt vmcnt(58)
	v_lshlrev_b32_e32 v164, 16, v112
	v_and_b32_e32 v165, 0xffff0000, v112
	v_lshlrev_b32_e32 v166, 16, v113
	v_and_b32_e32 v167, 0xffff0000, v113
	v_lshlrev_b32_e32 v168, 16, v114
	v_and_b32_e32 v169, 0xffff0000, v114
	v_lshlrev_b32_e32 v170, 16, v115
	v_and_b32_e32 v171, 0xffff0000, v115
	v_lshlrev_b32_e32 v172, 16, v116
	v_and_b32_e32 v173, 0xffff0000, v116
	v_lshlrev_b32_e32 v174, 16, v117
	v_and_b32_e32 v175, 0xffff0000, v117
	v_lshlrev_b32_e32 v176, 16, v118
	v_and_b32_e32 v177, 0xffff0000, v118
	v_lshlrev_b32_e32 v178, 16, v119
	v_and_b32_e32 v179, 0xffff0000, v119
	s_waitcnt vmcnt(56)
	v_lshlrev_b32_e32 v180, 16, v120
	v_and_b32_e32 v181, 0xffff0000, v120
	v_lshlrev_b32_e32 v182, 16, v121
	v_and_b32_e32 v183, 0xffff0000, v121
	v_lshlrev_b32_e32 v184, 16, v122
	v_and_b32_e32 v185, 0xffff0000, v122
	v_lshlrev_b32_e32 v186, 16, v123
	v_and_b32_e32 v187, 0xffff0000, v123
	v_lshlrev_b32_e32 v188, 16, v124
	v_and_b32_e32 v189, 0xffff0000, v124
	v_lshlrev_b32_e32 v190, 16, v125
	v_and_b32_e32 v191, 0xffff0000, v125
	v_lshlrev_b32_e32 v192, 16, v126
	v_and_b32_e32 v193, 0xffff0000, v126
	v_lshlrev_b32_e32 v194, 16, v127
	v_and_b32_e32 v195, 0xffff0000, v127
	v_pk_mul_f32 v[196:197], v[164:165], v[164:165]
	v_pk_mul_f32 v[198:199], v[180:181], v[180:181]
	v_pk_fma_f32 v[196:197], v[166:167], v[166:167], v[196:197]
	v_pk_fma_f32 v[198:199], v[182:183], v[182:183], v[198:199]
	v_pk_fma_f32 v[196:197], v[168:169], v[168:169], v[196:197]
	v_pk_fma_f32 v[198:199], v[184:185], v[184:185], v[198:199]
	v_pk_fma_f32 v[196:197], v[170:171], v[170:171], v[196:197]
	v_pk_fma_f32 v[198:199], v[186:187], v[186:187], v[198:199]
	v_pk_fma_f32 v[196:197], v[172:173], v[172:173], v[196:197]
	v_pk_fma_f32 v[198:199], v[188:189], v[188:189], v[198:199]
	v_pk_fma_f32 v[196:197], v[174:175], v[174:175], v[196:197]
	v_pk_fma_f32 v[198:199], v[190:191], v[190:191], v[198:199]
	v_pk_fma_f32 v[196:197], v[176:177], v[176:177], v[196:197]
	v_pk_fma_f32 v[198:199], v[192:193], v[192:193], v[198:199]
	v_pk_fma_f32 v[196:197], v[178:179], v[178:179], v[196:197]
	v_pk_fma_f32 v[198:199], v[194:195], v[194:195], v[198:199]
	v_add_f32_e32 v196, v196, v197
	v_add_f32_e32 v198, v198, v199
	ds_bpermute_b32 v200, v144, v196
	ds_bpermute_b32 v201, v144, v198
	s_waitcnt lgkmcnt(1)
	v_add_f32_e32 v196, v196, v200
	s_waitcnt lgkmcnt(0)
	v_add_f32_e32 v198, v198, v201
	ds_bpermute_b32 v200, v145, v196
	ds_bpermute_b32 v201, v145, v198
	s_waitcnt lgkmcnt(1)
	v_add_f32_e32 v196, v196, v200
	s_waitcnt lgkmcnt(0)
	v_add_f32_e32 v198, v198, v201
	ds_bpermute_b32 v200, v146, v196
	ds_bpermute_b32 v201, v146, v198
	s_waitcnt lgkmcnt(1)
	v_add_f32_e32 v196, v196, v200
	s_waitcnt lgkmcnt(0)
	v_add_f32_e32 v198, v198, v201
	ds_bpermute_b32 v200, v147, v196
	ds_bpermute_b32 v201, v147, v198
	s_waitcnt lgkmcnt(1)
	v_add_f32_e32 v196, v196, v200
	s_waitcnt lgkmcnt(0)
	v_add_f32_e32 v198, v198, v201
	ds_bpermute_b32 v200, v148, v196
	ds_bpermute_b32 v201, v148, v198
	s_waitcnt lgkmcnt(1)
	v_add_f32_e32 v196, v196, v200
	s_waitcnt lgkmcnt(0)
	v_add_f32_e32 v198, v198, v201
	ds_bpermute_b32 v200, v149, v196
	ds_bpermute_b32 v201, v149, v198
	s_waitcnt lgkmcnt(1)
	v_add_f32_e32 v196, v196, v200
	s_waitcnt lgkmcnt(0)
	v_add_f32_e32 v198, v198, v201
	v_mov_b32_e32 v200, 0x358637bd
	v_fmamk_f32 v196, v196, 0x3a800000, v200
	v_fmamk_f32 v198, v198, 0x3a800000, v200
	v_rsq_f32_e32 v202, v196
	v_rsq_f32_e32 v204, v198
	s_add_u32 s16, s16, 0x2000
	s_addc_u32 s17, s17, 0
	v_pk_mul_f32 v[164:165], v[164:165], v[202:203] op_sel_hi:[1,0]
	v_pk_mul_f32 v[166:167], v[166:167], v[202:203] op_sel_hi:[1,0]
	v_pk_mul_f32 v[168:169], v[168:169], v[202:203] op_sel_hi:[1,0]
	v_pk_mul_f32 v[170:171], v[170:171], v[202:203] op_sel_hi:[1,0]
	v_pk_mul_f32 v[172:173], v[172:173], v[202:203] op_sel_hi:[1,0]
	v_pk_mul_f32 v[174:175], v[174:175], v[202:203] op_sel_hi:[1,0]
	v_pk_mul_f32 v[176:177], v[176:177], v[202:203] op_sel_hi:[1,0]
	v_pk_mul_f32 v[178:179], v[178:179], v[202:203] op_sel_hi:[1,0]
	v_pk_mul_f32 v[164:165], v[128:129], v[164:165]
	v_pk_mul_f32 v[166:167], v[130:131], v[166:167]
	v_pk_mul_f32 v[168:169], v[132:133], v[168:169]
	v_pk_mul_f32 v[170:171], v[134:135], v[170:171]
	v_pk_mul_f32 v[172:173], v[136:137], v[172:173]
	v_pk_mul_f32 v[174:175], v[138:139], v[174:175]
	v_pk_mul_f32 v[176:177], v[140:141], v[176:177]
	v_pk_mul_f32 v[178:179], v[142:143], v[178:179]
	global_store_dwordx4 v151, v[164:167], s[16:17] offset:-4096
	global_store_dwordx4 v151, v[168:171], s[16:17] offset:-4080
	global_store_dwordx4 v151, v[172:175], s[16:17] offset:-2048
	global_store_dwordx4 v151, v[176:179], s[16:17] offset:-2032
	v_pk_mul_f32 v[180:181], v[180:181], v[204:205] op_sel_hi:[1,0]
	v_pk_mul_f32 v[182:183], v[182:183], v[204:205] op_sel_hi:[1,0]
	v_pk_mul_f32 v[184:185], v[184:185], v[204:205] op_sel_hi:[1,0]
	v_pk_mul_f32 v[186:187], v[186:187], v[204:205] op_sel_hi:[1,0]
	v_pk_mul_f32 v[188:189], v[188:189], v[204:205] op_sel_hi:[1,0]
	v_pk_mul_f32 v[190:191], v[190:191], v[204:205] op_sel_hi:[1,0]
	v_pk_mul_f32 v[192:193], v[192:193], v[204:205] op_sel_hi:[1,0]
	v_pk_mul_f32 v[194:195], v[194:195], v[204:205] op_sel_hi:[1,0]
	v_pk_mul_f32 v[180:181], v[128:129], v[180:181]
	v_pk_mul_f32 v[182:183], v[130:131], v[182:183]
	v_pk_mul_f32 v[184:185], v[132:133], v[184:185]
	v_pk_mul_f32 v[186:187], v[134:135], v[186:187]
	v_pk_mul_f32 v[188:189], v[136:137], v[188:189]
	v_pk_mul_f32 v[190:191], v[138:139], v[190:191]
	v_pk_mul_f32 v[192:193], v[140:141], v[192:193]
	v_pk_mul_f32 v[194:195], v[142:143], v[194:195]
	global_store_dwordx4 v151, v[180:183], s[16:17] offset:0
	global_store_dwordx4 v151, v[184:187], s[16:17] offset:16
	global_store_dwordx4 v151, v[188:191], s[16:17] offset:2048
	global_store_dwordx4 v151, v[192:195], s[16:17] offset:2064
	s_add_u32 s10, s10, s12
	s_cmp_lt_u32 s10, 0x800
	s_cbranch_scc1 .Lp20_group
.Lp20_done:
.LBB0_96:
	s_or_b64 exec, exec, s[0:1]

.LBB0_453:
	s_add_u32 s12, s64, s92
	s_addc_u32 s13, s65, s93
	s_add_u32 s14, s12, 0x100
	s_addc_u32 s15, s13, 0
	s_and_b64 s[8:9], s[62:63], exec
	s_cselect_b32 s21, s61, s15
	s_cselect_b32 s20, s60, s14
	s_add_u32 s8, s58, s92
	s_addc_u32 s9, s59, s93
	s_add_u32 s14, s8, 0x100
	s_addc_u32 s15, s9, 0
	s_add_i32 s18, 0, 0x10000
	s_and_b64 s[8:9], s[62:63], exec
	s_cselect_b32 s9, s5, s15
	s_cselect_b32 s8, s7, s14
	s_add_u32 s36, s12, 0x40080
	s_addc_u32 s37, s13, 0
	s_add_i32 s24, s18, s39
	s_add_i32 m0, s40, 0xc000
	s_add_i32 s25, s40, 0xe000
	s_add_i32 s23, 0, 0x14000
	s_add_i32 s22, s24, 0x2000
	s_add_u32 vcc_lo, s8, 0x10000
	v_add_u32_e32 v140, s18, v238
	s_addc_u32 vcc_hi, s9, 0
	s_add_i32 s17, s23, s39
	ds_read_b128 v[76:79], v140
	ds_read_b128 v[84:87], v140 offset:1024
	ds_read_b128 v[88:91], v140 offset:2048
	ds_read_b128 v[140:143], v140 offset:3072
	s_add_i32 s16, s17, 0x2000
	s_add_i32 s15, 0, 0x18000
	s_add_u32 s92, s20, 0x40000
	s_addc_u32 s93, s21, 0
	s_add_i32 s14, s15, s39
	s_add_i32 s13, 0, 0x1c000
	s_add_i32 s12, s14, 0x2000
	s_add_u32 s62, s8, 0x10080
	s_addc_u32 s63, s9, 0
	s_add_i32 s19, s13, s39
	s_add_i32 s18, s19, 0x2000
	v_lshl_add_u64 v[158:159], s[36:37], 0, v[160:161]
	ds_read_b128 v[144:147], v240
	ds_read_b128 v[148:151], v240 offset:1024
	ds_read_b128 v[170:173], v240 offset:2048
	ds_read_b128 v[174:177], v240 offset:3072
	ds_read_b128 v[178:181], v240 offset:4096
	ds_read_b128 v[182:185], v240 offset:5120
	ds_read_b128 v[186:189], v240 offset:6144
	ds_read_b128 v[190:193], v240 offset:7168
	global_load_lds_dwordx4 v[158:159], off
	v_lshl_add_u64 v[158:159], s[36:37], 0, v[154:155]
	s_mov_b32 m0, s25
	s_nop 0
	global_load_lds_dwordx4 v[158:159], off
	s_waitcnt lgkmcnt(8)
	s_barrier
	s_waitcnt lgkmcnt(0)
	s_setprio 1
	s_waitcnt lgkmcnt(0)
	v_mfma_f32_16x16x32_bf16 v[136:139], v[76:79], v[144:147], v[136:139]
	v_mfma_f32_16x16x32_bf16 v[132:135], v[88:91], v[144:147], v[132:135]
	v_mfma_f32_16x16x32_bf16 v[128:131], v[76:79], v[170:173], v[128:131]
	v_mfma_f32_16x16x32_bf16 v[124:127], v[88:91], v[170:173], v[124:127]
	v_mfma_f32_16x16x32_bf16 v[120:123], v[76:79], v[178:181], v[120:123]
	v_mfma_f32_16x16x32_bf16 v[116:119], v[88:91], v[178:181], v[116:119]
	v_mfma_f32_16x16x32_bf16 v[112:115], v[76:79], v[186:189], v[112:115]
	v_mfma_f32_16x16x32_bf16 v[108:111], v[88:91], v[186:189], v[108:111]
	v_mfma_f32_16x16x32_bf16 v[136:139], v[84:87], v[148:151], v[136:139]
	v_mfma_f32_16x16x32_bf16 v[132:135], v[140:143], v[148:151], v[132:135]
	v_mfma_f32_16x16x32_bf16 v[128:131], v[84:87], v[174:177], v[128:131]
	v_mfma_f32_16x16x32_bf16 v[124:127], v[140:143], v[174:177], v[124:127]
	v_mfma_f32_16x16x32_bf16 v[120:123], v[84:87], v[182:185], v[120:123]
	v_mfma_f32_16x16x32_bf16 v[116:119], v[140:143], v[182:185], v[116:119]
	v_mfma_f32_16x16x32_bf16 v[112:115], v[84:87], v[190:193], v[112:115]
	v_mfma_f32_16x16x32_bf16 v[108:111], v[140:143], v[190:193], v[108:111]
	s_setprio 0
	s_barrier
	v_add_u32_e32 v158, s23, v238
	s_mov_b32 m0, s24
	ds_read_b128 v[194:197], v158
	ds_read_b128 v[198:201], v158 offset:1024
	ds_read_b128 v[202:205], v158 offset:2048
	ds_read_b128 v[206:209], v158 offset:3072
	v_lshl_add_u64 v[158:159], s[8:9], 0, v[152:153]
	global_load_lds_dwordx4 v[158:159], off
	v_lshl_add_u64 v[210:211], s[8:9], 0, v[156:157]
	s_mov_b32 m0, s22
	s_nop 0
	global_load_lds_dwordx4 v[210:211], off
	s_barrier
	s_waitcnt lgkmcnt(0)
	s_setprio 1
	s_waitcnt lgkmcnt(0)
	v_mfma_f32_16x16x32_bf16 v[60:63], v[194:197], v[144:147], v[60:63]
	v_mfma_f32_16x16x32_bf16 v[56:59], v[202:205], v[144:147], v[56:59]
	v_mfma_f32_16x16x32_bf16 v[52:55], v[194:197], v[170:173], v[52:55]
	v_mfma_f32_16x16x32_bf16 v[48:51], v[202:205], v[170:173], v[48:51]
	v_mfma_f32_16x16x32_bf16 v[44:47], v[194:197], v[178:181], v[44:47]
	v_mfma_f32_16x16x32_bf16 v[40:43], v[202:205], v[178:181], v[40:43]
	v_mfma_f32_16x16x32_bf16 v[36:39], v[194:197], v[186:189], v[36:39]
	v_mfma_f32_16x16x32_bf16 v[32:35], v[202:205], v[186:189], v[32:35]
	v_mfma_f32_16x16x32_bf16 v[60:63], v[198:201], v[148:151], v[60:63]
	v_mfma_f32_16x16x32_bf16 v[56:59], v[206:209], v[148:151], v[56:59]
	v_mfma_f32_16x16x32_bf16 v[52:55], v[198:201], v[174:177], v[52:55]
	v_mfma_f32_16x16x32_bf16 v[48:51], v[206:209], v[174:177], v[48:51]
	v_mfma_f32_16x16x32_bf16 v[44:47], v[198:201], v[182:185], v[44:47]
	v_mfma_f32_16x16x32_bf16 v[40:43], v[206:209], v[182:185], v[40:43]
	v_mfma_f32_16x16x32_bf16 v[36:39], v[198:201], v[190:193], v[36:39]
	v_mfma_f32_16x16x32_bf16 v[32:35], v[206:209], v[190:193], v[32:35]
	s_setprio 0
	s_mov_b32 m0, s40
	v_lshl_add_u64 v[212:213], s[20:21], 0, v[160:161]
	s_barrier
	ds_read_b128 v[144:147], v240 offset:16384
	ds_read_b128 v[148:151], v240 offset:17408
	ds_read_b128 v[170:173], v240 offset:18432
	ds_read_b128 v[174:177], v240 offset:19456
	ds_read_b128 v[178:181], v240 offset:20480
	ds_read_b128 v[182:185], v240 offset:21504
	ds_read_b128 v[186:189], v240 offset:22528
	ds_read_b128 v[190:193], v240 offset:23552
	global_load_lds_dwordx4 v[212:213], off
	v_lshl_add_u64 v[214:215], s[20:21], 0, v[154:155]
	s_mov_b32 m0, s41
	s_nop 0
	global_load_lds_dwordx4 v[214:215], off
	s_barrier
	s_waitcnt lgkmcnt(0)
	s_setprio 1
	s_waitcnt lgkmcnt(0)
	v_mfma_f32_16x16x32_bf16 v[104:107], v[76:79], v[144:147], v[104:107]
	v_mfma_f32_16x16x32_bf16 v[100:103], v[88:91], v[144:147], v[100:103]
	v_mfma_f32_16x16x32_bf16 v[96:99], v[76:79], v[170:173], v[96:99]
	v_mfma_f32_16x16x32_bf16 v[92:95], v[88:91], v[170:173], v[92:95]
	v_mfma_f32_16x16x32_bf16 v[80:83], v[76:79], v[178:181], v[80:83]
	v_mfma_f32_16x16x32_bf16 v[72:75], v[88:91], v[178:181], v[72:75]
	v_mfma_f32_16x16x32_bf16 v[68:71], v[76:79], v[186:189], v[68:71]
	v_mfma_f32_16x16x32_bf16 v[64:67], v[88:91], v[186:189], v[64:67]
	v_mfma_f32_16x16x32_bf16 v[104:107], v[84:87], v[148:151], v[104:107]
	v_mfma_f32_16x16x32_bf16 v[100:103], v[140:143], v[148:151], v[100:103]
	v_mfma_f32_16x16x32_bf16 v[96:99], v[84:87], v[174:177], v[96:99]
	v_mfma_f32_16x16x32_bf16 v[92:95], v[140:143], v[174:177], v[92:95]
	v_mfma_f32_16x16x32_bf16 v[80:83], v[84:87], v[182:185], v[80:83]
	v_mfma_f32_16x16x32_bf16 v[72:75], v[140:143], v[182:185], v[72:75]
	v_mfma_f32_16x16x32_bf16 v[68:71], v[84:87], v[190:193], v[68:71]
	v_mfma_f32_16x16x32_bf16 v[64:67], v[140:143], v[190:193], v[64:67]
	s_setprio 0
	s_barrier
	s_mov_b32 m0, s17
	v_lshl_add_u64 v[76:77], vcc, 0, v[152:153]
	global_load_lds_dwordx4 v[76:77], off
	v_lshl_add_u64 v[76:77], vcc, 0, v[156:157]
	s_mov_b32 m0, s16
	s_nop 0
	global_load_lds_dwordx4 v[76:77], off
	s_waitcnt vmcnt(6)
	s_barrier
	s_setprio 1
	v_mfma_f32_16x16x32_bf16 v[28:31], v[194:197], v[144:147], v[28:31]
	v_mfma_f32_16x16x32_bf16 v[24:27], v[202:205], v[144:147], v[24:27]
	v_mfma_f32_16x16x32_bf16 v[20:23], v[194:197], v[170:173], v[20:23]
	v_mfma_f32_16x16x32_bf16 v[16:19], v[202:205], v[170:173], v[16:19]
	v_mfma_f32_16x16x32_bf16 v[12:15], v[194:197], v[178:181], v[12:15]
	v_mfma_f32_16x16x32_bf16 v[8:11], v[202:205], v[178:181], v[8:11]
	v_mfma_f32_16x16x32_bf16 v[4:7], v[194:197], v[186:189], v[4:7]
	v_mfma_f32_16x16x32_bf16 v[0:3], v[202:205], v[186:189], v[0:3]
	v_mfma_f32_16x16x32_bf16 v[28:31], v[198:201], v[148:151], v[28:31]
	v_mfma_f32_16x16x32_bf16 v[24:27], v[206:209], v[148:151], v[24:27]
	v_mfma_f32_16x16x32_bf16 v[20:23], v[198:201], v[174:177], v[20:23]
	v_mfma_f32_16x16x32_bf16 v[16:19], v[206:209], v[174:177], v[16:19]
	v_mfma_f32_16x16x32_bf16 v[12:15], v[198:201], v[182:185], v[12:15]
	v_mfma_f32_16x16x32_bf16 v[8:11], v[206:209], v[182:185], v[8:11]
	v_mfma_f32_16x16x32_bf16 v[4:7], v[198:201], v[190:193], v[4:7]
	v_mfma_f32_16x16x32_bf16 v[0:3], v[206:209], v[190:193], v[0:3]
	s_setprio 0
	v_add_u32_e32 v140, s15, v238
	s_barrier
	ds_read_b128 v[76:79], v140
	ds_read_b128 v[84:87], v140 offset:1024
	ds_read_b128 v[88:91], v140 offset:2048
	ds_read_b128 v[140:143], v140 offset:3072
	s_mov_b32 m0, s42
	v_lshl_add_u64 v[194:195], s[92:93], 0, v[160:161]
	ds_read_b128 v[144:147], v240 offset:32768
	ds_read_b128 v[148:151], v240 offset:33792
	ds_read_b128 v[170:173], v240 offset:34816
	ds_read_b128 v[174:177], v240 offset:35840
	ds_read_b128 v[178:181], v240 offset:36864
	ds_read_b128 v[182:185], v240 offset:37888
	ds_read_b128 v[186:189], v240 offset:38912
	ds_read_b128 v[190:193], v240 offset:39936
	global_load_lds_dwordx4 v[194:195], off
	v_lshl_add_u64 v[194:195], s[92:93], 0, v[154:155]
	s_mov_b32 m0, s43
	s_nop 0
	global_load_lds_dwordx4 v[194:195], off
	s_waitcnt lgkmcnt(8)
	s_barrier
	s_waitcnt lgkmcnt(0)
	s_setprio 1
	s_waitcnt lgkmcnt(0)
	v_mfma_f32_16x16x32_bf16 v[136:139], v[76:79], v[144:147], v[136:139]
	v_mfma_f32_16x16x32_bf16 v[132:135], v[88:91], v[144:147], v[132:135]
	v_mfma_f32_16x16x32_bf16 v[128:131], v[76:79], v[170:173], v[128:131]
	v_mfma_f32_16x16x32_bf16 v[124:127], v[88:91], v[170:173], v[124:127]
	v_mfma_f32_16x16x32_bf16 v[120:123], v[76:79], v[178:181], v[120:123]
	v_mfma_f32_16x16x32_bf16 v[116:119], v[88:91], v[178:181], v[116:119]
	v_mfma_f32_16x16x32_bf16 v[112:115], v[76:79], v[186:189], v[112:115]
	v_mfma_f32_16x16x32_bf16 v[108:111], v[88:91], v[186:189], v[108:111]
	v_mfma_f32_16x16x32_bf16 v[136:139], v[84:87], v[148:151], v[136:139]
	v_mfma_f32_16x16x32_bf16 v[132:135], v[140:143], v[148:151], v[132:135]
	v_mfma_f32_16x16x32_bf16 v[128:131], v[84:87], v[174:177], v[128:131]
	v_mfma_f32_16x16x32_bf16 v[124:127], v[140:143], v[174:177], v[124:127]
	v_mfma_f32_16x16x32_bf16 v[120:123], v[84:87], v[182:185], v[120:123]
	v_mfma_f32_16x16x32_bf16 v[116:119], v[140:143], v[182:185], v[116:119]
	v_mfma_f32_16x16x32_bf16 v[112:115], v[84:87], v[190:193], v[112:115]
	v_mfma_f32_16x16x32_bf16 v[108:111], v[140:143], v[190:193], v[108:111]
	s_setprio 0
	s_barrier
	s_mov_b32 m0, s14
	v_add_u32_e32 v164, s13, v238
	v_lshl_add_u64 v[158:159], v[158:159], 0, s[74:75]
	ds_read_b128 v[194:197], v164
	ds_read_b128 v[198:201], v164 offset:1024
	ds_read_b128 v[202:205], v164 offset:2048
	ds_read_b128 v[206:209], v164 offset:3072
	global_load_lds_dwordx4 v[158:159], off
	v_lshl_add_u64 v[158:159], v[210:211], 0, s[74:75]
	s_mov_b32 m0, s12
	s_nop 0
	global_load_lds_dwordx4 v[158:159], off
	s_barrier
	s_waitcnt lgkmcnt(0)
	s_setprio 1
	s_waitcnt lgkmcnt(0)
	v_mfma_f32_16x16x32_bf16 v[60:63], v[194:197], v[144:147], v[60:63]
	v_mfma_f32_16x16x32_bf16 v[56:59], v[202:205], v[144:147], v[56:59]
	v_mfma_f32_16x16x32_bf16 v[52:55], v[194:197], v[170:173], v[52:55]
	v_mfma_f32_16x16x32_bf16 v[48:51], v[202:205], v[170:173], v[48:51]
	v_mfma_f32_16x16x32_bf16 v[44:47], v[194:197], v[178:181], v[44:47]
	v_mfma_f32_16x16x32_bf16 v[40:43], v[202:205], v[178:181], v[40:43]
	v_mfma_f32_16x16x32_bf16 v[36:39], v[194:197], v[186:189], v[36:39]
	v_mfma_f32_16x16x32_bf16 v[32:35], v[202:205], v[186:189], v[32:35]
	v_mfma_f32_16x16x32_bf16 v[60:63], v[198:201], v[148:151], v[60:63]
	v_mfma_f32_16x16x32_bf16 v[56:59], v[206:209], v[148:151], v[56:59]
	v_mfma_f32_16x16x32_bf16 v[52:55], v[198:201], v[174:177], v[52:55]
	v_mfma_f32_16x16x32_bf16 v[48:51], v[206:209], v[174:177], v[48:51]
	v_mfma_f32_16x16x32_bf16 v[44:47], v[198:201], v[182:185], v[44:47]
	v_mfma_f32_16x16x32_bf16 v[40:43], v[206:209], v[182:185], v[40:43]
	v_mfma_f32_16x16x32_bf16 v[36:39], v[198:201], v[190:193], v[36:39]
	v_mfma_f32_16x16x32_bf16 v[32:35], v[206:209], v[190:193], v[32:35]
	s_setprio 0
	s_mov_b32 m0, s38
	v_lshl_add_u64 v[158:159], v[212:213], 0, s[74:75]
	s_barrier
	ds_read_b128 v[144:147], v240 offset:49152
	ds_read_b128 v[148:151], v240 offset:50176
	ds_read_b128 v[170:173], v240 offset:51200
	ds_read_b128 v[174:177], v240 offset:52224
	ds_read_b128 v[178:181], v240 offset:53248
	ds_read_b128 v[182:185], v240 offset:54272
	ds_read_b128 v[186:189], v240 offset:55296
	ds_read_b128 v[190:193], v240 offset:56320
	global_load_lds_dwordx4 v[158:159], off
	v_lshl_add_u64 v[158:159], v[214:215], 0, s[74:75]
	s_mov_b32 m0, s81
	s_nop 0
	global_load_lds_dwordx4 v[158:159], off
	s_barrier
	s_waitcnt lgkmcnt(0)
	s_setprio 1
	s_waitcnt lgkmcnt(0)
	v_mfma_f32_16x16x32_bf16 v[104:107], v[76:79], v[144:147], v[104:107]
	v_mfma_f32_16x16x32_bf16 v[100:103], v[88:91], v[144:147], v[100:103]
	v_mfma_f32_16x16x32_bf16 v[96:99], v[76:79], v[170:173], v[96:99]
	v_mfma_f32_16x16x32_bf16 v[92:95], v[88:91], v[170:173], v[92:95]
	v_mfma_f32_16x16x32_bf16 v[80:83], v[76:79], v[178:181], v[80:83]
	v_mfma_f32_16x16x32_bf16 v[72:75], v[88:91], v[178:181], v[72:75]
	v_mfma_f32_16x16x32_bf16 v[68:71], v[76:79], v[186:189], v[68:71]
	v_mfma_f32_16x16x32_bf16 v[64:67], v[88:91], v[186:189], v[64:67]
	v_mfma_f32_16x16x32_bf16 v[104:107], v[84:87], v[148:151], v[104:107]
	v_mfma_f32_16x16x32_bf16 v[100:103], v[140:143], v[148:151], v[100:103]
	v_mfma_f32_16x16x32_bf16 v[96:99], v[84:87], v[174:177], v[96:99]
	v_mfma_f32_16x16x32_bf16 v[92:95], v[140:143], v[174:177], v[92:95]
	v_mfma_f32_16x16x32_bf16 v[80:83], v[84:87], v[182:185], v[80:83]
	v_mfma_f32_16x16x32_bf16 v[72:75], v[140:143], v[182:185], v[72:75]
	v_mfma_f32_16x16x32_bf16 v[68:71], v[84:87], v[190:193], v[68:71]
	v_mfma_f32_16x16x32_bf16 v[64:67], v[140:143], v[190:193], v[64:67]
	s_setprio 0
	s_barrier
	s_mov_b32 m0, s19
	v_lshl_add_u64 v[76:77], s[62:63], 0, v[152:153]
	global_load_lds_dwordx4 v[76:77], off
	v_lshl_add_u64 v[76:77], s[62:63], 0, v[156:157]
	s_mov_b32 m0, s18
	s_nop 0
	global_load_lds_dwordx4 v[76:77], off
	s_waitcnt vmcnt(6)
	s_barrier
	s_setprio 1
	v_mfma_f32_16x16x32_bf16 v[28:31], v[194:197], v[144:147], v[28:31]
	v_mfma_f32_16x16x32_bf16 v[24:27], v[202:205], v[144:147], v[24:27]
	v_mfma_f32_16x16x32_bf16 v[20:23], v[194:197], v[170:173], v[20:23]
	v_mfma_f32_16x16x32_bf16 v[16:19], v[202:205], v[170:173], v[16:19]
	v_mfma_f32_16x16x32_bf16 v[12:15], v[194:197], v[178:181], v[12:15]
	v_mfma_f32_16x16x32_bf16 v[8:11], v[202:205], v[178:181], v[8:11]
	v_mfma_f32_16x16x32_bf16 v[4:7], v[194:197], v[186:189], v[4:7]
	v_mfma_f32_16x16x32_bf16 v[0:3], v[202:205], v[186:189], v[0:3]
	v_mfma_f32_16x16x32_bf16 v[28:31], v[198:201], v[148:151], v[28:31]
	v_mfma_f32_16x16x32_bf16 v[24:27], v[206:209], v[148:151], v[24:27]
	v_mfma_f32_16x16x32_bf16 v[20:23], v[198:201], v[174:177], v[20:23]
	v_mfma_f32_16x16x32_bf16 v[16:19], v[206:209], v[174:177], v[16:19]
	v_mfma_f32_16x16x32_bf16 v[12:15], v[198:201], v[182:185], v[12:15]
	v_mfma_f32_16x16x32_bf16 v[8:11], v[206:209], v[182:185], v[8:11]
	v_mfma_f32_16x16x32_bf16 v[4:7], v[198:201], v[190:193], v[4:7]
	v_mfma_f32_16x16x32_bf16 v[0:3], v[206:209], v[190:193], v[0:3]
	s_setprio 0
	s_andn2_b64 vcc, exec, s[0:1]
	s_mov_b64 s[62:63], -1
	s_mov_b64 s[0:1], 0
	s_mov_b64 s[92:93], 0x100
	s_barrier
	s_cbranch_vccz .LBB0_453
	s_lshl_b32 s0, s97, 8
	s_bfe_u32 s7, s4, 0x10001
	s_add_i32 s1, s0, 0xffff8000
	s_cmpk_gt_i32 s97, 0x7f
	s_cselect_b32 s8, s1, s0
	s_lshl_b32 s0, s4, 6
	s_lshl_b32 s1, s4, 7
	s_and_b32 s0, s0, 0xffffff00
	s_and_b32 s1, s1, 0x80
	v_readlane_b32 s12, v251, 50
	s_or_b32 s5, s1, s0
	s_lshl_b32 s9, s7, 12
	v_readlane_b32 s24, v251, 62
	v_readlane_b32 s13, v251, 51
	v_readlane_b32 s14, v251, 52
	v_readlane_b32 s15, v251, 53
	v_readlane_b32 s16, v251, 54
	v_readlane_b32 s17, v251, 55
	v_readlane_b32 s18, v251, 56
	v_readlane_b32 s19, v251, 57
	v_readlane_b32 s20, v251, 58
	v_readlane_b32 s21, v251, 59
	v_readlane_b32 s22, v251, 60
	v_readlane_b32 s23, v251, 61
	v_readlane_b32 s25, v251, 63
	v_readlane_b32 s26, v252, 0
	v_readlane_b32 s27, v252, 1
	s_add_u32 s0, s24, s9
	v_or_b32_e32 v180, s5, v239
	s_addc_u32 s1, s25, 0
	v_readlane_b32 s12, v250, 62
	v_ashrrev_i32_e32 v181, 31, v180
	v_readlane_b32 s13, v250, 63
	s_add_u32 s4, s12, s9
	v_lshlrev_b64 v[84:85], 2, v[180:181]
	v_lshl_add_u64 v[172:173], s[0:1], 0, v[84:85]
	s_addc_u32 s5, s13, 0
	global_load_dwordx4 v[88:91], v[172:173], off
	v_lshl_add_u64 v[158:159], s[4:5], 0, v[84:85]
	global_load_dwordx4 v[76:79], v[158:159], off
	v_readlane_b32 s0, v251, 28
	v_readlane_b32 s1, v251, 29
	s_add_u32 s0, s0, s9
	s_addc_u32 s1, s1, 0
	v_lshl_add_u64 v[174:175], s[0:1], 0, v[84:85]
	global_load_dwordx4 v[84:87], v[174:175], off
	v_add_u32_e32 v182, s8, v162
	v_ashrrev_i32_e32 v183, 31, v182
	v_or_b32_e32 v184, 16, v182
	v_readlane_b32 s14, v251, 0
	v_lshlrev_b64 v[178:179], 11, v[182:183]
	v_ashrrev_i32_e32 v185, 31, v184
	v_lshlrev_b64 v[186:187], 10, v[182:183]
	v_readlane_b32 s62, v255, 4
	v_lshlrev_b64 v[176:177], 11, v[184:185]
	s_cmpk_lt_i32 s97, 0x80
	v_readlane_b32 s36, v249, 22
	s_mov_b32 s90, s62
	v_readlane_b32 s93, v250, 12
	v_readlane_b32 s92, v255, 6
	s_mov_b32 s14, 0x3e2aaaab
	v_readlane_b32 s15, v251, 1
	v_readlane_b32 s16, v251, 2
	v_readlane_b32 s17, v251, 3
	v_readlane_b32 s18, v251, 4
	v_readlane_b32 s19, v251, 5
	v_readlane_b32 s20, v251, 6
	v_readlane_b32 s21, v251, 7
	v_readlane_b32 s22, v251, 8
	v_readlane_b32 s23, v251, 9
	v_readlane_b32 s24, v251, 10
	v_readlane_b32 s25, v251, 11
	v_readlane_b32 s26, v251, 12
	v_readlane_b32 s27, v251, 13
	v_readlane_b32 s37, v249, 23
	v_readlane_b32 s63, v255, 5
	s_waitcnt vmcnt(0)
	v_add_f32_e32 v136, v136, v88
	v_mul_f32_e32 v136, 0xbfb8aa3b, v136
	v_add_f32_e32 v132, v132, v76
	v_exp_f32_e32 v136, v136
	v_mul_f32_e32 v132, 0xbfb8aa3b, v132
	v_exp_f32_e32 v132, v132
	v_add_f32_e32 v136, 1.0, v136
	v_add_f32_e32 v132, 1.0, v132
	s_mov_b64 vcc, s[0:1]
	v_rcp_f32_e32 v140, v136
	v_rcp_f32_e32 v136, v132
	v_mul_f32_e32 v132, 0xc1000000, v140
	v_mul_f32_e32 v132, v84, v132
	v_add_f32_e32 v183, v132, v132
	v_cmp_nlt_f32_e64 s[4:5], s51, v183
	s_mov_b64 s[0:1], -1
	s_cbranch_scc0 .LBB0_712
	v_lshl_add_u64 v[140:141], v[180:181], 1, s[28:29]
	v_lshl_add_u64 v[142:143], v[140:141], 0, v[178:179]
	v_lshl_add_u64 v[146:147], v[140:141], 0, v[176:177]
	global_load_dwordx2 v[144:145], v[142:143], off
	s_nop 0
	global_load_dwordx2 v[142:143], v[146:147], off
	s_and_saveexec_b64 s[0:1], s[4:5]
	s_xor_b64 s[0:1], exec, s[0:1]
	v_mul_f32_e32 v146, 0x3fb8aa3b, v183
	v_exp_f32_e32 v146, v146
	s_nop 0
	v_sub_f32_e32 v147, 1.0, v146
	s_andn2_saveexec_b64 s[0:1], s[0:1]
	v_fma_f32 v146, v183, s14, 0.5
	v_fma_f32 v146, v183, v146, 1.0
	v_mul_f32_e64 v147, v146, -v183
	s_or_b64 exec, exec, s[0:1]
	v_add_f32_e32 v146, v137, v89
	v_mul_f32_e32 v146, 0xbfb8aa3b, v146
	v_exp_f32_e32 v146, v146
	s_nop 0
	v_add_f32_e32 v146, 1.0, v146
	v_rcp_f32_e32 v146, v146
	s_nop 0
	v_mul_f32_e32 v146, 0xc1000000, v146
	v_mul_f32_e32 v146, v85, v146
	v_add_f32_e32 v148, v146, v146
	v_cmp_nlt_f32_e32 vcc, s51, v148
	s_and_saveexec_b64 s[0:1], vcc
	s_xor_b64 s[0:1], exec, s[0:1]
	v_mul_f32_e32 v148, 0x3fb8aa3b, v148
	v_exp_f32_e32 v148, v148
	s_nop 0
	v_sub_f32_e32 v149, 1.0, v148
	s_andn2_saveexec_b64 s[0:1], s[0:1]
	v_fma_f32 v149, v148, s14, 0.5
	v_fma_f32 v149, v148, v149, 1.0
	v_mul_f32_e64 v149, v149, -v148
	s_or_b64 exec, exec, s[0:1]
	v_add_f32_e32 v148, v138, v90
	v_mul_f32_e32 v148, 0xbfb8aa3b, v148
	v_exp_f32_e32 v148, v148
	s_nop 0
	v_add_f32_e32 v148, 1.0, v148
	v_rcp_f32_e32 v148, v148
	s_nop 0
	v_mul_f32_e32 v148, 0xc1000000, v148
	v_mul_f32_e32 v148, v86, v148
	v_add_f32_e32 v150, v148, v148
	v_cmp_nlt_f32_e32 vcc, s51, v150
	s_and_saveexec_b64 s[0:1], vcc
	s_xor_b64 s[0:1], exec, s[0:1]
	v_mul_f32_e32 v150, 0x3fb8aa3b, v150
	v_exp_f32_e32 v150, v150
	s_nop 0
	v_sub_f32_e32 v168, 1.0, v150
	s_andn2_saveexec_b64 s[0:1], s[0:1]
	v_fma_f32 v151, v150, s14, 0.5
	v_fma_f32 v151, v150, v151, 1.0
	v_mul_f32_e64 v168, v151, -v150
	s_or_b64 exec, exec, s[0:1]
	v_add_f32_e32 v150, v139, v91
	v_mul_f32_e32 v150, 0xbfb8aa3b, v150
	v_exp_f32_e32 v150, v150
	s_nop 0
	v_add_f32_e32 v150, 1.0, v150
	v_rcp_f32_e32 v150, v150
	s_nop 0
	v_mul_f32_e32 v150, 0xc1000000, v150
	v_mul_f32_e32 v150, v87, v150
	v_add_f32_e32 v170, v150, v150
	v_cmp_nlt_f32_e32 vcc, s51, v170
	s_and_saveexec_b64 s[0:1], vcc
	s_xor_b64 s[0:1], exec, s[0:1]
	v_mul_f32_e32 v151, 0x3fb8aa3b, v170
	v_exp_f32_e32 v151, v151
	s_nop 0
	v_sub_f32_e32 v151, 1.0, v151
	s_andn2_saveexec_b64 s[0:1], s[0:1]
	v_fma_f32 v151, v170, s14, 0.5
	v_fma_f32 v151, v170, v151, 1.0
	v_mul_f32_e64 v151, v151, -v170
	s_or_b64 exec, exec, s[0:1]
	v_add_f32_e32 v164, v134, v78
	v_mul_f32_e32 v164, 0xbfb8aa3b, v164
	v_exp_f32_e32 v164, v164
	v_max_f32_e32 v149, 0, v149
	v_add_f32_e32 v164, 1.0, v164
	v_max_f32_e32 v147, 0, v147
	v_readlane_b32 s8, v253, 8
	v_readlane_b32 s9, v253, 9
	v_max_f32_e32 v166, 0, v168
	v_rcp_f32_e32 v164, v164
	s_waitcnt vmcnt(0)
	v_lshlrev_b32_e32 v165, 16, v145
	v_sqrt_f32_e32 v166, v166
	v_cvt_pk_bf16_f32 v146, v132, v146
	v_mul_f32_e32 v164, v164, v166
	v_mul_f32_e32 v164, v164, v165
	v_add_f32_e32 v165, v135, v79
	v_mul_f32_e32 v165, 0xbfb8aa3b, v165
	v_exp_f32_e32 v165, v165
	s_nop 0
	v_add_f32_e32 v165, 1.0, v165
	s_nop 0
	v_rcp_f32_e32 v165, v165
	v_add_f32_e32 v166, v133, v77
	v_mul_f32_e32 v166, 0xbfb8aa3b, v166
	v_exp_f32_e32 v166, v166
	s_nop 0
	v_add_f32_e32 v166, 1.0, v166
	s_lshl_b32 s0, s7, 26
	s_add_u32 s58, s8, s0
	s_addc_u32 s59, s9, 0
	v_rcp_f32_e32 v166, v166
	v_and_b32_e32 v167, 0xffff0000, v144
	v_sqrt_f32_e32 v149, v149
	v_lshlrev_b32_e32 v144, 16, v144
	v_mul_f32_e32 v149, v166, v149
	v_sqrt_f32_e32 v147, v147
	s_add_u32 s0, s68, s0
	s_addc_u32 s1, s69, 0
	v_mul_f32_e32 v147, v136, v147
	v_mul_f32_e32 v166, v147, v144
	v_and_b32_e32 v144, 0xffff0000, v145
	v_max_f32_e32 v145, 0, v151
	v_mul_f32_e32 v149, v149, v167
	s_nop 0
	v_sqrt_f32_e32 v145, v145
	s_nop 0
	v_mul_f32_e32 v145, v165, v145
	v_mul_f32_e32 v151, v145, v144
	v_lshl_add_u64 v[144:145], v[186:187], 0, v[180:181]
	v_lshlrev_b64 v[144:145], 1, v[144:145]
	v_lshl_add_u64 v[190:191], s[58:59], 0, v[144:145]
	v_lshl_add_u64 v[194:195], s[0:1], 0, v[144:145]
	v_add_f32_e32 v144, v128, v88
	v_mul_f32_e32 v144, 0xbfb8aa3b, v144
	v_exp_f32_e32 v144, v144
	v_cvt_pk_bf16_f32 v147, v148, v150
	global_store_dwordx2 v[190:191], v[146:147], off
	v_cvt_pk_bf16_f32 v146, v166, v149
	v_add_f32_e32 v144, 1.0, v144
	v_cvt_pk_bf16_f32 v147, v164, v151
	global_store_dwordx2 v[194:195], v[146:147], off
	s_nop 0
	v_rcp_f32_e32 v144, v144
	s_nop 0
	v_mul_f32_e32 v144, 0xc1000000, v144
	v_mul_f32_e32 v144, v84, v144
	v_add_f32_e32 v145, v144, v144
	v_cmp_nlt_f32_e32 vcc, s51, v145
	s_and_saveexec_b64 s[8:9], vcc
	s_xor_b64 s[8:9], exec, s[8:9]
	v_mul_f32_e32 v145, 0x3fb8aa3b, v145
	v_exp_f32_e32 v145, v145
	s_nop 0
	v_sub_f32_e32 v146, 1.0, v145
	s_andn2_saveexec_b64 s[8:9], s[8:9]
	v_fma_f32 v146, v145, s14, 0.5
	v_fma_f32 v146, v145, v146, 1.0
	v_mul_f32_e64 v146, v146, -v145
	s_or_b64 exec, exec, s[8:9]
	v_add_f32_e32 v145, v129, v89
	v_mul_f32_e32 v145, 0xbfb8aa3b, v145
	v_exp_f32_e32 v145, v145
	s_nop 0
	v_add_f32_e32 v145, 1.0, v145
	v_rcp_f32_e32 v145, v145
	s_nop 0
	v_mul_f32_e32 v145, 0xc1000000, v145
	v_mul_f32_e32 v145, v85, v145
	v_add_f32_e32 v147, v145, v145
	v_cmp_nlt_f32_e32 vcc, s51, v147
	s_and_saveexec_b64 s[8:9], vcc
	s_xor_b64 s[8:9], exec, s[8:9]
	v_mul_f32_e32 v147, 0x3fb8aa3b, v147
	v_exp_f32_e32 v147, v147
	s_nop 0
	v_sub_f32_e32 v150, 1.0, v147
	s_andn2_saveexec_b64 s[8:9], s[8:9]
	v_fma_f32 v148, v147, s14, 0.5
	v_fma_f32 v148, v147, v148, 1.0
	v_mul_f32_e64 v150, v148, -v147
	s_or_b64 exec, exec, s[8:9]
	v_add_f32_e32 v147, v130, v90
	v_mul_f32_e32 v147, 0xbfb8aa3b, v147
	v_exp_f32_e32 v147, v147
	s_nop 0
	v_add_f32_e32 v147, 1.0, v147
	v_rcp_f32_e32 v147, v147
	s_nop 0
	v_mul_f32_e32 v147, 0xc1000000, v147
	v_mul_f32_e32 v147, v86, v147
	v_add_f32_e32 v148, v147, v147
	v_cmp_nlt_f32_e32 vcc, s51, v148
	s_and_saveexec_b64 s[8:9], vcc
	s_xor_b64 s[8:9], exec, s[8:9]
	v_mul_f32_e32 v148, 0x3fb8aa3b, v148
	v_exp_f32_e32 v148, v148
	s_nop 0
	v_sub_f32_e32 v151, 1.0, v148
	s_andn2_saveexec_b64 s[8:9], s[8:9]
	v_fma_f32 v149, v148, s14, 0.5
	v_fma_f32 v149, v148, v149, 1.0
	v_mul_f32_e64 v151, v149, -v148
	s_or_b64 exec, exec, s[8:9]
	v_add_f32_e32 v148, v131, v91
	v_mul_f32_e32 v148, 0xbfb8aa3b, v148
	v_exp_f32_e32 v148, v148
	s_nop 0
	v_add_f32_e32 v148, 1.0, v148
	v_rcp_f32_e32 v148, v148
	s_nop 0
	v_mul_f32_e32 v148, 0xc1000000, v148
	v_mul_f32_e32 v148, v87, v148
	v_add_f32_e32 v168, v148, v148
	v_cmp_nlt_f32_e32 vcc, s51, v168
	s_and_saveexec_b64 s[8:9], vcc
	s_xor_b64 s[8:9], exec, s[8:9]
	v_mul_f32_e32 v149, 0x3fb8aa3b, v168
	v_exp_f32_e32 v149, v149
	s_nop 0
	v_sub_f32_e32 v149, 1.0, v149
	s_andn2_saveexec_b64 s[8:9], s[8:9]
	v_fma_f32 v149, v168, s14, 0.5
	v_fma_f32 v149, v168, v149, 1.0
	v_mul_f32_e64 v149, v149, -v168
	s_or_b64 exec, exec, s[8:9]
	v_add_f32_e32 v164, v126, v78
	v_mul_f32_e32 v164, 0xbfb8aa3b, v164
	v_exp_f32_e32 v164, v164
	v_max_f32_e32 v151, 0, v151
	v_add_f32_e32 v164, 1.0, v164
	v_max_f32_e32 v150, 0, v150
	v_max_f32_e32 v146, 0, v146
	v_rcp_f32_e32 v164, v164
	v_lshlrev_b32_e32 v165, 16, v143
	v_sqrt_f32_e32 v151, v151
	v_cvt_pk_bf16_f32 v144, v144, v145
	v_cvt_pk_bf16_f32 v145, v147, v148
	v_mul_f32_e32 v151, v164, v151
	v_mul_f32_e32 v164, v151, v165
	v_add_f32_e32 v151, v127, v79
	v_mul_f32_e32 v151, 0xbfb8aa3b, v151
	v_exp_f32_e32 v151, v151
	s_nop 0
	v_add_f32_e32 v151, 1.0, v151
	s_nop 0
	v_rcp_f32_e32 v165, v151
	v_add_f32_e32 v151, v125, v77
	v_mul_f32_e32 v151, 0xbfb8aa3b, v151
	v_exp_f32_e32 v151, v151
	s_nop 0
	v_add_f32_e32 v151, 1.0, v151
	s_nop 0
	v_rcp_f32_e32 v151, v151
	v_and_b32_e32 v166, 0xffff0000, v142
	v_sqrt_f32_e32 v150, v150
	v_lshlrev_b32_e32 v142, 16, v142
	v_mul_f32_e32 v150, v151, v150
	v_mul_f32_e32 v166, v150, v166
	v_add_f32_e32 v150, v124, v76
	v_mul_f32_e32 v150, 0xbfb8aa3b, v150
	v_exp_f32_e32 v150, v150
	s_nop 0
	v_add_f32_e32 v150, 1.0, v150
	s_nop 0
	v_rcp_f32_e32 v150, v150
	s_nop 0
	v_sqrt_f32_e32 v146, v146
	s_nop 0
	v_mul_f32_e32 v146, v150, v146
	v_mul_f32_e32 v146, v146, v142
	v_and_b32_e32 v142, 0xffff0000, v143
	v_max_f32_e32 v143, 0, v149
	v_lshlrev_b64 v[150:151], 10, v[184:185]
	s_nop 0
	v_sqrt_f32_e32 v143, v143
	s_nop 0
	v_mul_f32_e32 v143, v165, v143
	v_mul_f32_e32 v149, v143, v142
	v_lshl_add_u64 v[142:143], v[150:151], 0, v[180:181]
	v_lshlrev_b64 v[142:143], 1, v[142:143]
	v_lshl_add_u64 v[188:189], s[58:59], 0, v[142:143]
	global_store_dwordx2 v[188:189], v[144:145], off
	v_cvt_pk_bf16_f32 v144, v146, v166
	v_or_b32_e32 v146, 32, v182
	v_ashrrev_i32_e32 v147, 31, v146
	v_lshl_add_u64 v[192:193], s[0:1], 0, v[142:143]
	v_lshlrev_b64 v[196:197], 11, v[146:147]
	v_cvt_pk_bf16_f32 v145, v164, v149
	global_store_dwordx2 v[192:193], v[144:145], off
	v_lshl_add_u64 v[142:143], v[140:141], 0, v[196:197]
	global_load_dwordx2 v[148:149], v[142:143], off
	v_or_b32_e32 v142, 48, v182
	v_ashrrev_i32_e32 v143, 31, v142
	v_lshlrev_b64 v[198:199], 11, v[142:143]
	v_lshl_add_u64 v[144:145], v[140:141], 0, v[198:199]
	global_load_dwordx2 v[144:145], v[144:145], off
	v_add_f32_e32 v150, v120, v88
	v_mul_f32_e32 v150, 0xbfb8aa3b, v150
	v_exp_f32_e32 v150, v150
	s_nop 0
	v_add_f32_e32 v150, 1.0, v150
	s_nop 0
	v_rcp_f32_e32 v150, v150
	s_nop 0
	v_mul_f32_e32 v150, 0xc1000000, v150
	v_mul_f32_e32 v150, v84, v150
	v_add_f32_e32 v151, v150, v150
	v_cmp_nlt_f32_e32 vcc, s51, v151
	s_and_saveexec_b64 s[8:9], vcc
	s_xor_b64 s[8:9], exec, s[8:9]
	v_mul_f32_e32 v151, 0x3fb8aa3b, v151
	v_exp_f32_e32 v151, v151
	s_nop 0
	v_sub_f32_e32 v168, 1.0, v151
	s_andn2_saveexec_b64 s[8:9], s[8:9]
	v_fma_f32 v164, v151, s14, 0.5
	v_fma_f32 v164, v151, v164, 1.0
	v_mul_f32_e64 v168, v164, -v151
	s_or_b64 exec, exec, s[8:9]
	v_add_f32_e32 v151, v121, v89
	v_mul_f32_e32 v151, 0xbfb8aa3b, v151
	v_exp_f32_e32 v151, v151
	s_nop 0
	v_add_f32_e32 v151, 1.0, v151
	v_rcp_f32_e32 v151, v151
	s_nop 0
	v_mul_f32_e32 v151, 0xc1000000, v151
	v_mul_f32_e32 v151, v85, v151
	v_add_f32_e32 v170, v151, v151
	v_cmp_nlt_f32_e32 vcc, s51, v170
	s_and_saveexec_b64 s[8:9], vcc
	s_xor_b64 s[8:9], exec, s[8:9]
	v_mul_f32_e32 v164, 0x3fb8aa3b, v170
	v_exp_f32_e32 v164, v164
	s_nop 0
	v_sub_f32_e32 v201, 1.0, v164
	s_andn2_saveexec_b64 s[8:9], s[8:9]
	v_fma_f32 v164, v170, s14, 0.5
	v_fma_f32 v164, v170, v164, 1.0
	v_mul_f32_e64 v201, v164, -v170
	s_or_b64 exec, exec, s[8:9]
	v_add_f32_e32 v164, v122, v90
	v_mul_f32_e32 v164, 0xbfb8aa3b, v164
	v_exp_f32_e32 v164, v164
	s_nop 0
	v_add_f32_e32 v164, 1.0, v164
	v_rcp_f32_e32 v164, v164
	s_nop 0
	v_mul_f32_e32 v164, 0xc1000000, v164
	v_mul_f32_e32 v170, v86, v164
	v_add_f32_e32 v171, v170, v170
	v_cmp_nlt_f32_e32 vcc, s51, v171
	s_and_saveexec_b64 s[8:9], vcc
	s_xor_b64 s[8:9], exec, s[8:9]
	v_mul_f32_e32 v164, 0x3fb8aa3b, v171
	v_exp_f32_e32 v164, v164
	s_nop 0
	v_sub_f32_e32 v202, 1.0, v164
	s_andn2_saveexec_b64 s[8:9], s[8:9]
	v_fma_f32 v164, v171, s14, 0.5
	v_fma_f32 v164, v171, v164, 1.0
	v_mul_f32_e64 v202, v164, -v171
	s_or_b64 exec, exec, s[8:9]
	v_add_f32_e32 v164, v123, v91
	v_mul_f32_e32 v164, 0xbfb8aa3b, v164
	v_exp_f32_e32 v164, v164
	s_nop 0
	v_add_f32_e32 v164, 1.0, v164
	v_rcp_f32_e32 v164, v164
	s_nop 0
	v_mul_f32_e32 v164, 0xc1000000, v164
	v_mul_f32_e32 v171, v87, v164
	v_add_f32_e32 v203, v171, v171
	v_cmp_nlt_f32_e32 vcc, s51, v203
	s_and_saveexec_b64 s[8:9], vcc
	s_xor_b64 s[8:9], exec, s[8:9]
	v_mul_f32_e32 v164, 0x3fb8aa3b, v203
	v_exp_f32_e32 v164, v164
	s_nop 0
	v_sub_f32_e32 v200, 1.0, v164
	s_andn2_saveexec_b64 s[8:9], s[8:9]
	v_fma_f32 v164, v203, s14, 0.5
	v_fma_f32 v164, v203, v164, 1.0
	v_mul_f32_e64 v200, v164, -v203
	s_or_b64 exec, exec, s[8:9]
	v_add_f32_e32 v164, v118, v78
	v_mul_f32_e32 v164, 0xbfb8aa3b, v164
	v_exp_f32_e32 v164, v164
	v_max_f32_e32 v201, 0, v201
	v_add_f32_e32 v164, 1.0, v164
	v_max_f32_e32 v168, 0, v168
	v_lshlrev_b64 v[146:147], 10, v[146:147]
	v_lshl_add_u64 v[146:147], v[146:147], 0, v[180:181]
	v_max_f32_e32 v166, 0, v202
	v_rcp_f32_e32 v164, v164
	s_waitcnt vmcnt(0)
	v_lshlrev_b32_e32 v165, 16, v149
	v_sqrt_f32_e32 v166, v166
	v_lshlrev_b64 v[146:147], 1, v[146:147]
	v_lshl_add_u64 v[206:207], s[0:1], 0, v[146:147]
	v_mul_f32_e32 v164, v164, v166
	v_mul_f32_e32 v164, v164, v165
	v_add_f32_e32 v165, v119, v79
	v_mul_f32_e32 v165, 0xbfb8aa3b, v165
	v_exp_f32_e32 v165, v165
	s_nop 0
	v_add_f32_e32 v165, 1.0, v165
	s_nop 0
	v_rcp_f32_e32 v165, v165
	v_add_f32_e32 v166, v117, v77
	v_mul_f32_e32 v166, 0xbfb8aa3b, v166
	v_exp_f32_e32 v166, v166
	s_nop 0
	v_add_f32_e32 v166, 1.0, v166
	s_nop 0
	v_rcp_f32_e32 v166, v166
	v_and_b32_e32 v167, 0xffff0000, v148
	v_sqrt_f32_e32 v201, v201
	v_lshlrev_b32_e32 v148, 16, v148
	v_mul_f32_e32 v166, v166, v201
	v_mul_f32_e32 v166, v166, v167
	v_add_f32_e32 v167, v116, v76
	v_mul_f32_e32 v167, 0xbfb8aa3b, v167
	v_exp_f32_e32 v167, v167
	s_nop 0
	v_add_f32_e32 v167, 1.0, v167
	s_nop 0
	v_rcp_f32_e32 v167, v167
	v_lshl_add_u64 v[202:203], s[58:59], 0, v[146:147]
	v_sqrt_f32_e32 v168, v168
	v_add_f32_e32 v146, v112, v88
	v_mul_f32_e32 v146, 0xbfb8aa3b, v146
	v_mul_f32_e32 v167, v167, v168
	v_mul_f32_e32 v167, v167, v148
	v_and_b32_e32 v148, 0xffff0000, v149
	v_max_f32_e32 v149, 0, v200
	v_exp_f32_e32 v146, v146
	s_nop 0
	v_sqrt_f32_e32 v149, v149
	v_add_f32_e32 v146, 1.0, v146
	v_mul_f32_e32 v149, v165, v149
	v_mul_f32_e32 v165, v149, v148
	v_cvt_pk_bf16_f32 v148, v150, v151
	v_cvt_pk_bf16_f32 v149, v170, v171
	global_store_dwordx2 v[202:203], v[148:149], off
	v_cvt_pk_bf16_f32 v148, v167, v166
	v_cvt_pk_bf16_f32 v149, v164, v165
	global_store_dwordx2 v[206:207], v[148:149], off
	s_nop 0
	v_rcp_f32_e32 v146, v146
	s_nop 0
	v_mul_f32_e32 v146, 0xc1000000, v146
	v_mul_f32_e32 v146, v84, v146
	v_add_f32_e32 v147, v146, v146
	v_cmp_nlt_f32_e32 vcc, s51, v147
	s_and_saveexec_b64 s[8:9], vcc
	s_xor_b64 s[8:9], exec, s[8:9]
	v_mul_f32_e32 v147, 0x3fb8aa3b, v147
	v_exp_f32_e32 v147, v147
	s_nop 0
	v_sub_f32_e32 v148, 1.0, v147
	s_andn2_saveexec_b64 s[8:9], s[8:9]
	v_fma_f32 v148, v147, s14, 0.5
	v_fma_f32 v148, v147, v148, 1.0
	v_mul_f32_e64 v148, v148, -v147
	s_or_b64 exec, exec, s[8:9]
	v_add_f32_e32 v147, v113, v89
	v_mul_f32_e32 v147, 0xbfb8aa3b, v147
	v_exp_f32_e32 v147, v147
	s_nop 0
	v_add_f32_e32 v147, 1.0, v147
	v_rcp_f32_e32 v147, v147
	s_nop 0
	v_mul_f32_e32 v147, 0xc1000000, v147
	v_mul_f32_e32 v147, v85, v147
	v_add_f32_e32 v149, v147, v147
	v_cmp_nlt_f32_e32 vcc, s51, v149
	s_and_saveexec_b64 s[8:9], vcc
	s_xor_b64 s[8:9], exec, s[8:9]
	v_mul_f32_e32 v149, 0x3fb8aa3b, v149
	v_exp_f32_e32 v149, v149
	s_nop 0
	v_sub_f32_e32 v168, 1.0, v149
	s_andn2_saveexec_b64 s[8:9], s[8:9]
	v_fma_f32 v150, v149, s14, 0.5
	v_fma_f32 v150, v149, v150, 1.0
	v_mul_f32_e64 v168, v150, -v149
	s_or_b64 exec, exec, s[8:9]
	v_add_f32_e32 v149, v114, v90
	v_mul_f32_e32 v149, 0xbfb8aa3b, v149
	v_exp_f32_e32 v149, v149
	s_nop 0
	v_add_f32_e32 v149, 1.0, v149
	v_rcp_f32_e32 v149, v149
	s_nop 0
	v_mul_f32_e32 v149, 0xc1000000, v149
	v_mul_f32_e32 v149, v86, v149
	v_add_f32_e32 v150, v149, v149
	v_cmp_nlt_f32_e32 vcc, s51, v150
	s_and_saveexec_b64 s[8:9], vcc
	s_xor_b64 s[8:9], exec, s[8:9]
	v_mul_f32_e32 v150, 0x3fb8aa3b, v150
	v_exp_f32_e32 v150, v150
	s_nop 0
	v_sub_f32_e32 v170, 1.0, v150
	s_andn2_saveexec_b64 s[8:9], s[8:9]
	v_fma_f32 v151, v150, s14, 0.5
	v_fma_f32 v151, v150, v151, 1.0
	v_mul_f32_e64 v170, v151, -v150
	s_or_b64 exec, exec, s[8:9]
	v_add_f32_e32 v150, v115, v91
	v_mul_f32_e32 v150, 0xbfb8aa3b, v150
	v_exp_f32_e32 v150, v150
	s_nop 0
	v_add_f32_e32 v150, 1.0, v150
	v_rcp_f32_e32 v150, v150
	s_nop 0
	v_mul_f32_e32 v150, 0xc1000000, v150
	v_mul_f32_e32 v150, v87, v150
	v_add_f32_e32 v171, v150, v150
	v_cmp_nlt_f32_e32 vcc, s51, v171
	s_and_saveexec_b64 s[8:9], vcc
	s_xor_b64 s[8:9], exec, s[8:9]
	v_mul_f32_e32 v151, 0x3fb8aa3b, v171
	v_exp_f32_e32 v151, v151
	s_nop 0
	v_sub_f32_e32 v151, 1.0, v151
	s_andn2_saveexec_b64 s[8:9], s[8:9]
	v_fma_f32 v151, v171, s14, 0.5
	v_fma_f32 v151, v171, v151, 1.0
	v_mul_f32_e64 v151, v151, -v171
	s_or_b64 exec, exec, s[8:9]
	v_add_f32_e32 v164, v110, v78
	v_mul_f32_e32 v164, 0xbfb8aa3b, v164
	v_exp_f32_e32 v164, v164
	v_max_f32_e32 v168, 0, v168
	v_add_f32_e32 v164, 1.0, v164
	v_max_f32_e32 v148, 0, v148
	v_lshlrev_b64 v[142:143], 10, v[142:143]
	v_lshl_add_u64 v[142:143], v[142:143], 0, v[180:181]
	v_max_f32_e32 v166, 0, v170
	v_rcp_f32_e32 v164, v164
	v_lshlrev_b32_e32 v165, 16, v145
	v_sqrt_f32_e32 v166, v166
	v_lshlrev_b64 v[142:143], 1, v[142:143]
	v_lshl_add_u64 v[204:205], s[0:1], 0, v[142:143]
	v_mul_f32_e32 v164, v164, v166
	v_mul_f32_e32 v164, v164, v165
	v_add_f32_e32 v165, v111, v79
	v_mul_f32_e32 v165, 0xbfb8aa3b, v165
	v_exp_f32_e32 v165, v165
	s_nop 0
	v_add_f32_e32 v165, 1.0, v165
	s_nop 0
	v_rcp_f32_e32 v165, v165
	v_add_f32_e32 v166, v109, v77
	v_mul_f32_e32 v166, 0xbfb8aa3b, v166
	v_exp_f32_e32 v166, v166
	s_nop 0
	v_add_f32_e32 v166, 1.0, v166
	s_nop 0
	v_rcp_f32_e32 v166, v166
	v_and_b32_e32 v167, 0xffff0000, v144
	v_sqrt_f32_e32 v168, v168
	v_lshlrev_b32_e32 v144, 16, v144
	v_mul_f32_e32 v166, v166, v168
	v_mul_f32_e32 v166, v166, v167
	v_add_f32_e32 v167, v108, v76
	v_mul_f32_e32 v167, 0xbfb8aa3b, v167
	v_exp_f32_e32 v167, v167
	s_nop 0
	v_add_f32_e32 v167, 1.0, v167
	s_nop 0
	v_rcp_f32_e32 v167, v167
	v_lshl_add_u64 v[200:201], s[58:59], 0, v[142:143]
	v_sqrt_f32_e32 v148, v148
	s_nop 0
	v_mul_f32_e32 v148, v167, v148
	v_mul_f32_e32 v148, v148, v144
	v_and_b32_e32 v144, 0xffff0000, v145
	v_max_f32_e32 v145, 0, v151
	s_nop 1
	v_sqrt_f32_e32 v145, v145
	s_nop 0
	v_mul_f32_e32 v145, v165, v145
	v_mul_f32_e32 v151, v145, v144
	v_cvt_pk_bf16_f32 v144, v146, v147
	v_add_u32_e32 v146, 0x80, v182
	v_ashrrev_i32_e32 v147, 31, v146
	v_cvt_pk_bf16_f32 v145, v149, v150
	v_lshlrev_b64 v[208:209], 11, v[146:147]
	global_store_dwordx2 v[200:201], v[144:145], off
	v_cvt_pk_bf16_f32 v144, v148, v166
	v_cvt_pk_bf16_f32 v145, v164, v151
	global_store_dwordx2 v[204:205], v[144:145], off
	v_lshl_add_u64 v[142:143], v[140:141], 0, v[208:209]
	global_load_dwordx2 v[148:149], v[142:143], off
	v_add_u32_e32 v142, 0x90, v182
	v_ashrrev_i32_e32 v143, 31, v142
	v_lshlrev_b64 v[210:211], 11, v[142:143]
	v_lshl_add_u64 v[144:145], v[140:141], 0, v[210:211]
	global_load_dwordx2 v[144:145], v[144:145], off
	v_add_f32_e32 v150, v104, v88
	v_mul_f32_e32 v150, 0xbfb8aa3b, v150
	v_exp_f32_e32 v150, v150
	s_nop 0
	v_add_f32_e32 v150, 1.0, v150
	s_nop 0
	v_rcp_f32_e32 v150, v150
	s_nop 0
	v_mul_f32_e32 v150, 0xc1000000, v150
	v_mul_f32_e32 v150, v84, v150
	v_add_f32_e32 v151, v150, v150
	v_cmp_nlt_f32_e32 vcc, s51, v151
	s_and_saveexec_b64 s[8:9], vcc
	s_xor_b64 s[8:9], exec, s[8:9]
	v_mul_f32_e32 v151, 0x3fb8aa3b, v151
	v_exp_f32_e32 v151, v151
	s_nop 0
	v_sub_f32_e32 v168, 1.0, v151
	s_andn2_saveexec_b64 s[8:9], s[8:9]
	v_fma_f32 v164, v151, s14, 0.5
	v_fma_f32 v164, v151, v164, 1.0
	v_mul_f32_e64 v168, v164, -v151
	s_or_b64 exec, exec, s[8:9]
	v_add_f32_e32 v151, v105, v89
	v_mul_f32_e32 v151, 0xbfb8aa3b, v151
	v_exp_f32_e32 v151, v151
	s_nop 0
	v_add_f32_e32 v151, 1.0, v151
	v_rcp_f32_e32 v151, v151
	s_nop 0
	v_mul_f32_e32 v151, 0xc1000000, v151
	v_mul_f32_e32 v151, v85, v151
	v_add_f32_e32 v170, v151, v151
	v_cmp_nlt_f32_e32 vcc, s51, v170
	s_and_saveexec_b64 s[8:9], vcc
	s_xor_b64 s[8:9], exec, s[8:9]
	v_mul_f32_e32 v164, 0x3fb8aa3b, v170
	v_exp_f32_e32 v164, v164
	s_nop 0
	v_sub_f32_e32 v213, 1.0, v164
	s_andn2_saveexec_b64 s[8:9], s[8:9]
	v_fma_f32 v164, v170, s14, 0.5
	v_fma_f32 v164, v170, v164, 1.0
	v_mul_f32_e64 v213, v164, -v170
	s_or_b64 exec, exec, s[8:9]
	v_add_f32_e32 v164, v106, v90
	v_mul_f32_e32 v164, 0xbfb8aa3b, v164
	v_exp_f32_e32 v164, v164
	s_nop 0
	v_add_f32_e32 v164, 1.0, v164
	v_rcp_f32_e32 v164, v164
	s_nop 0
	v_mul_f32_e32 v164, 0xc1000000, v164
	v_mul_f32_e32 v170, v86, v164
	v_add_f32_e32 v171, v170, v170
	v_cmp_nlt_f32_e32 vcc, s51, v171
	s_and_saveexec_b64 s[8:9], vcc
	s_xor_b64 s[8:9], exec, s[8:9]
	v_mul_f32_e32 v164, 0x3fb8aa3b, v171
	v_exp_f32_e32 v164, v164
	s_nop 0
	v_sub_f32_e32 v214, 1.0, v164
	s_andn2_saveexec_b64 s[8:9], s[8:9]
	v_fma_f32 v164, v171, s14, 0.5
	v_fma_f32 v164, v171, v164, 1.0
	v_mul_f32_e64 v214, v164, -v171
	s_or_b64 exec, exec, s[8:9]
	v_add_f32_e32 v164, v107, v91
	v_mul_f32_e32 v164, 0xbfb8aa3b, v164
	v_exp_f32_e32 v164, v164
	s_nop 0
	v_add_f32_e32 v164, 1.0, v164
	v_rcp_f32_e32 v164, v164
	s_nop 0
	v_mul_f32_e32 v164, 0xc1000000, v164
	v_mul_f32_e32 v171, v87, v164
	v_add_f32_e32 v215, v171, v171
	v_cmp_nlt_f32_e32 vcc, s51, v215
	s_and_saveexec_b64 s[8:9], vcc
	s_xor_b64 s[8:9], exec, s[8:9]
	v_mul_f32_e32 v164, 0x3fb8aa3b, v215
	v_exp_f32_e32 v164, v164
	s_nop 0
	v_sub_f32_e32 v212, 1.0, v164
	s_andn2_saveexec_b64 s[8:9], s[8:9]
	v_fma_f32 v164, v215, s14, 0.5
	v_fma_f32 v164, v215, v164, 1.0
	v_mul_f32_e64 v212, v164, -v215
	s_or_b64 exec, exec, s[8:9]
	v_add_f32_e32 v164, v102, v78
	v_mul_f32_e32 v164, 0xbfb8aa3b, v164
	v_exp_f32_e32 v164, v164
	v_max_f32_e32 v213, 0, v213
	v_add_f32_e32 v164, 1.0, v164
	v_max_f32_e32 v168, 0, v168
	v_lshlrev_b64 v[146:147], 10, v[146:147]
	v_lshl_add_u64 v[146:147], v[146:147], 0, v[180:181]
	v_max_f32_e32 v166, 0, v214
	v_rcp_f32_e32 v164, v164
	s_waitcnt vmcnt(0)
	v_lshlrev_b32_e32 v165, 16, v149
	v_sqrt_f32_e32 v166, v166
	v_lshlrev_b64 v[146:147], 1, v[146:147]
	v_lshl_add_u64 v[218:219], s[0:1], 0, v[146:147]
	v_mul_f32_e32 v164, v164, v166
	v_mul_f32_e32 v164, v164, v165
	v_add_f32_e32 v165, v103, v79
	v_mul_f32_e32 v165, 0xbfb8aa3b, v165
	v_exp_f32_e32 v165, v165
	s_nop 0
	v_add_f32_e32 v165, 1.0, v165
	s_nop 0
	v_rcp_f32_e32 v165, v165
	v_add_f32_e32 v166, v101, v77
	v_mul_f32_e32 v166, 0xbfb8aa3b, v166
	v_exp_f32_e32 v166, v166
	s_nop 0
	v_add_f32_e32 v166, 1.0, v166
	s_nop 0
	v_rcp_f32_e32 v166, v166
	v_and_b32_e32 v167, 0xffff0000, v148
	v_sqrt_f32_e32 v213, v213
	v_lshlrev_b32_e32 v148, 16, v148
	v_mul_f32_e32 v166, v166, v213
	v_mul_f32_e32 v166, v166, v167
	v_add_f32_e32 v167, v100, v76
	v_mul_f32_e32 v167, 0xbfb8aa3b, v167
	v_exp_f32_e32 v167, v167
	s_nop 0
	v_add_f32_e32 v167, 1.0, v167
	s_nop 0
	v_rcp_f32_e32 v167, v167
	v_lshl_add_u64 v[214:215], s[58:59], 0, v[146:147]
	v_sqrt_f32_e32 v168, v168
	v_add_f32_e32 v146, v96, v88
	v_mul_f32_e32 v146, 0xbfb8aa3b, v146
	v_mul_f32_e32 v167, v167, v168
	v_mul_f32_e32 v167, v167, v148
	v_and_b32_e32 v148, 0xffff0000, v149
	v_max_f32_e32 v149, 0, v212
	v_exp_f32_e32 v146, v146
	s_nop 0
	v_sqrt_f32_e32 v149, v149
	v_add_f32_e32 v146, 1.0, v146
	v_mul_f32_e32 v149, v165, v149
	v_mul_f32_e32 v165, v149, v148
	v_cvt_pk_bf16_f32 v148, v150, v151
	v_cvt_pk_bf16_f32 v149, v170, v171
	global_store_dwordx2 v[214:215], v[148:149], off
	v_cvt_pk_bf16_f32 v148, v167, v166
	v_cvt_pk_bf16_f32 v149, v164, v165
	global_store_dwordx2 v[218:219], v[148:149], off
	s_nop 0
	v_rcp_f32_e32 v146, v146
	s_nop 0
	v_mul_f32_e32 v146, 0xc1000000, v146
	v_mul_f32_e32 v146, v84, v146
	v_add_f32_e32 v147, v146, v146
	v_cmp_nlt_f32_e32 vcc, s51, v147
	s_and_saveexec_b64 s[8:9], vcc
	s_xor_b64 s[8:9], exec, s[8:9]
	v_mul_f32_e32 v147, 0x3fb8aa3b, v147
	v_exp_f32_e32 v147, v147
	s_nop 0
	v_sub_f32_e32 v148, 1.0, v147
	s_andn2_saveexec_b64 s[8:9], s[8:9]
	v_fma_f32 v148, v147, s14, 0.5
	v_fma_f32 v148, v147, v148, 1.0
	v_mul_f32_e64 v148, v148, -v147
	s_or_b64 exec, exec, s[8:9]
	v_add_f32_e32 v147, v97, v89
	v_mul_f32_e32 v147, 0xbfb8aa3b, v147
	v_exp_f32_e32 v147, v147
	s_nop 0
	v_add_f32_e32 v147, 1.0, v147
	v_rcp_f32_e32 v147, v147
	s_nop 0
	v_mul_f32_e32 v147, 0xc1000000, v147
	v_mul_f32_e32 v147, v85, v147
	v_add_f32_e32 v149, v147, v147
	v_cmp_nlt_f32_e32 vcc, s51, v149
	s_and_saveexec_b64 s[8:9], vcc
	s_xor_b64 s[8:9], exec, s[8:9]
	v_mul_f32_e32 v149, 0x3fb8aa3b, v149
	v_exp_f32_e32 v149, v149
	s_nop 0
	v_sub_f32_e32 v168, 1.0, v149
	s_andn2_saveexec_b64 s[8:9], s[8:9]
	v_fma_f32 v150, v149, s14, 0.5
	v_fma_f32 v150, v149, v150, 1.0
	v_mul_f32_e64 v168, v150, -v149
	s_or_b64 exec, exec, s[8:9]
	v_add_f32_e32 v149, v98, v90
	v_mul_f32_e32 v149, 0xbfb8aa3b, v149
	v_exp_f32_e32 v149, v149
	s_nop 0
	v_add_f32_e32 v149, 1.0, v149
	v_rcp_f32_e32 v149, v149
	s_nop 0
	v_mul_f32_e32 v149, 0xc1000000, v149
	v_mul_f32_e32 v149, v86, v149
	v_add_f32_e32 v150, v149, v149
	v_cmp_nlt_f32_e32 vcc, s51, v150
	s_and_saveexec_b64 s[8:9], vcc
	s_xor_b64 s[8:9], exec, s[8:9]
	v_mul_f32_e32 v150, 0x3fb8aa3b, v150
	v_exp_f32_e32 v150, v150
	s_nop 0
	v_sub_f32_e32 v170, 1.0, v150
	s_andn2_saveexec_b64 s[8:9], s[8:9]
	v_fma_f32 v151, v150, s14, 0.5
	v_fma_f32 v151, v150, v151, 1.0
	v_mul_f32_e64 v170, v151, -v150
	s_or_b64 exec, exec, s[8:9]
	v_add_f32_e32 v150, v99, v91
	v_mul_f32_e32 v150, 0xbfb8aa3b, v150
	v_exp_f32_e32 v150, v150
	s_nop 0
	v_add_f32_e32 v150, 1.0, v150
	v_rcp_f32_e32 v150, v150
	s_nop 0
	v_mul_f32_e32 v150, 0xc1000000, v150
	v_mul_f32_e32 v150, v87, v150
	v_add_f32_e32 v171, v150, v150
	v_cmp_nlt_f32_e32 vcc, s51, v171
	s_and_saveexec_b64 s[8:9], vcc
	s_xor_b64 s[8:9], exec, s[8:9]
	v_mul_f32_e32 v151, 0x3fb8aa3b, v171
	v_exp_f32_e32 v151, v151
	s_nop 0
	v_sub_f32_e32 v151, 1.0, v151
	s_andn2_saveexec_b64 s[8:9], s[8:9]
	v_fma_f32 v151, v171, s14, 0.5
	v_fma_f32 v151, v171, v151, 1.0
	v_mul_f32_e64 v151, v151, -v171
	s_or_b64 exec, exec, s[8:9]
	v_add_f32_e32 v164, v94, v78
	v_mul_f32_e32 v164, 0xbfb8aa3b, v164
	v_exp_f32_e32 v164, v164
	v_max_f32_e32 v168, 0, v168
	v_add_f32_e32 v164, 1.0, v164
	v_max_f32_e32 v148, 0, v148
	v_lshlrev_b64 v[142:143], 10, v[142:143]
	v_lshl_add_u64 v[142:143], v[142:143], 0, v[180:181]
	v_max_f32_e32 v166, 0, v170
	v_rcp_f32_e32 v164, v164
	v_lshlrev_b32_e32 v165, 16, v145
	v_sqrt_f32_e32 v166, v166
	v_lshlrev_b64 v[142:143], 1, v[142:143]
	v_lshl_add_u64 v[216:217], s[0:1], 0, v[142:143]
	v_mul_f32_e32 v164, v164, v166
	v_mul_f32_e32 v164, v164, v165
	v_add_f32_e32 v165, v95, v79
	v_mul_f32_e32 v165, 0xbfb8aa3b, v165
	v_exp_f32_e32 v165, v165
	s_nop 0
	v_add_f32_e32 v165, 1.0, v165
	s_nop 0
	v_rcp_f32_e32 v165, v165
	v_add_f32_e32 v166, v93, v77
	v_mul_f32_e32 v166, 0xbfb8aa3b, v166
	v_exp_f32_e32 v166, v166
	s_nop 0
	v_add_f32_e32 v166, 1.0, v166
	s_nop 0
	v_rcp_f32_e32 v166, v166
	v_and_b32_e32 v167, 0xffff0000, v144
	v_sqrt_f32_e32 v168, v168
	v_lshlrev_b32_e32 v144, 16, v144
	v_mul_f32_e32 v166, v166, v168
	v_mul_f32_e32 v166, v166, v167
	v_add_f32_e32 v167, v92, v76
	v_mul_f32_e32 v167, 0xbfb8aa3b, v167
	v_exp_f32_e32 v167, v167
	s_nop 0
	v_add_f32_e32 v167, 1.0, v167
	s_nop 0
	v_rcp_f32_e32 v167, v167
	v_lshl_add_u64 v[212:213], s[58:59], 0, v[142:143]
	v_sqrt_f32_e32 v148, v148
	s_nop 0
	v_mul_f32_e32 v148, v167, v148
	v_mul_f32_e32 v148, v148, v144
	v_and_b32_e32 v144, 0xffff0000, v145
	v_max_f32_e32 v145, 0, v151
	s_nop 1
	v_sqrt_f32_e32 v145, v145
	s_nop 0
	v_mul_f32_e32 v145, v165, v145
	v_mul_f32_e32 v151, v145, v144
	v_cvt_pk_bf16_f32 v144, v146, v147
	v_cvt_pk_bf16_f32 v145, v149, v150
	global_store_dwordx2 v[212:213], v[144:145], off
	v_cvt_pk_bf16_f32 v144, v148, v166
	v_cvt_pk_bf16_f32 v145, v164, v151
	global_store_dwordx2 v[216:217], v[144:145], off
	v_add_u32_e32 v144, 0xa0, v182
	v_ashrrev_i32_e32 v145, 31, v144
	v_lshlrev_b64 v[220:221], 11, v[144:145]
	v_lshl_add_u64 v[142:143], v[140:141], 0, v[220:221]
	global_load_dwordx2 v[146:147], v[142:143], off
	v_add_u32_e32 v142, 0xb0, v182
	v_ashrrev_i32_e32 v143, 31, v142
	v_lshlrev_b64 v[222:223], 11, v[142:143]
	v_lshl_add_u64 v[140:141], v[140:141], 0, v[222:223]
	global_load_dwordx2 v[140:141], v[140:141], off
	v_add_f32_e32 v148, v80, v88
	v_mul_f32_e32 v148, 0xbfb8aa3b, v148
	v_exp_f32_e32 v148, v148
	s_nop 0
	v_add_f32_e32 v148, 1.0, v148
	s_nop 0
	v_rcp_f32_e32 v148, v148
	s_nop 0
	v_mul_f32_e32 v148, 0xc1000000, v148
	v_mul_f32_e32 v148, v84, v148
	v_add_f32_e32 v149, v148, v148
	v_cmp_nlt_f32_e32 vcc, s51, v149
	s_and_saveexec_b64 s[8:9], vcc
	s_xor_b64 s[8:9], exec, s[8:9]
	v_mul_f32_e32 v149, 0x3fb8aa3b, v149
	v_exp_f32_e32 v149, v149
	s_nop 0
	v_sub_f32_e32 v150, 1.0, v149
	s_andn2_saveexec_b64 s[8:9], s[8:9]
	v_fma_f32 v150, v149, s14, 0.5
	v_fma_f32 v150, v149, v150, 1.0
	v_mul_f32_e64 v150, v150, -v149
	s_or_b64 exec, exec, s[8:9]
	v_add_f32_e32 v149, v81, v89
	v_mul_f32_e32 v149, 0xbfb8aa3b, v149
	v_exp_f32_e32 v149, v149
	s_nop 0
	v_add_f32_e32 v149, 1.0, v149
	v_rcp_f32_e32 v149, v149
	s_nop 0
	v_mul_f32_e32 v149, 0xc1000000, v149
	v_mul_f32_e32 v149, v85, v149
	v_add_f32_e32 v151, v149, v149
	v_cmp_nlt_f32_e32 vcc, s51, v151
	s_and_saveexec_b64 s[8:9], vcc
	s_xor_b64 s[8:9], exec, s[8:9]
	v_mul_f32_e32 v151, 0x3fb8aa3b, v151
	v_exp_f32_e32 v151, v151
	s_nop 0
	v_sub_f32_e32 v171, 1.0, v151
	s_andn2_saveexec_b64 s[8:9], s[8:9]
	v_fma_f32 v164, v151, s14, 0.5
	v_fma_f32 v164, v151, v164, 1.0
	v_mul_f32_e64 v171, v164, -v151
	s_or_b64 exec, exec, s[8:9]
	v_add_f32_e32 v151, v82, v90
	v_mul_f32_e32 v151, 0xbfb8aa3b, v151
	v_exp_f32_e32 v151, v151
	s_nop 0
	v_add_f32_e32 v151, 1.0, v151
	v_rcp_f32_e32 v151, v151
	s_nop 0
	v_mul_f32_e32 v151, 0xc1000000, v151
	v_mul_f32_e32 v151, v86, v151
	v_add_f32_e32 v168, v151, v151
	v_cmp_nlt_f32_e32 vcc, s51, v168
	s_and_saveexec_b64 s[8:9], vcc
	s_xor_b64 s[8:9], exec, s[8:9]
	v_mul_f32_e32 v164, 0x3fb8aa3b, v168
	v_exp_f32_e32 v164, v164
	s_nop 0
	v_sub_f32_e32 v224, 1.0, v164
	s_andn2_saveexec_b64 s[8:9], s[8:9]
	v_fma_f32 v164, v168, s14, 0.5
	v_fma_f32 v164, v168, v164, 1.0
	v_mul_f32_e64 v224, v164, -v168
	s_or_b64 exec, exec, s[8:9]
	v_add_f32_e32 v164, v83, v91
	v_mul_f32_e32 v164, 0xbfb8aa3b, v164
	v_exp_f32_e32 v164, v164
	s_nop 0
	v_add_f32_e32 v164, 1.0, v164
	v_rcp_f32_e32 v164, v164
	s_nop 0
	v_mul_f32_e32 v164, 0xc1000000, v164
	v_mul_f32_e32 v168, v87, v164
	v_add_f32_e32 v225, v168, v168
	v_cmp_nlt_f32_e32 vcc, s51, v225
	s_and_saveexec_b64 s[8:9], vcc
	s_xor_b64 s[8:9], exec, s[8:9]
	v_mul_f32_e32 v164, 0x3fb8aa3b, v225
	v_exp_f32_e32 v164, v164
	s_nop 0
	v_sub_f32_e32 v170, 1.0, v164
	s_andn2_saveexec_b64 s[8:9], s[8:9]
	v_fma_f32 v164, v225, s14, 0.5
	v_fma_f32 v164, v225, v164, 1.0
	v_mul_f32_e64 v170, v164, -v225
	s_or_b64 exec, exec, s[8:9]
	v_add_f32_e32 v164, v74, v78
	v_mul_f32_e32 v164, 0xbfb8aa3b, v164
	v_exp_f32_e32 v164, v164
	v_max_f32_e32 v171, 0, v171
	v_add_f32_e32 v164, 1.0, v164
	v_max_f32_e32 v150, 0, v150
	v_lshlrev_b64 v[144:145], 10, v[144:145]
	v_lshl_add_u64 v[144:145], v[144:145], 0, v[180:181]
	v_max_f32_e32 v166, 0, v224
	v_rcp_f32_e32 v164, v164
	s_waitcnt vmcnt(0)
	v_lshlrev_b32_e32 v165, 16, v147
	v_sqrt_f32_e32 v166, v166
	v_lshlrev_b64 v[144:145], 1, v[144:145]
	v_mul_f32_e32 v164, v164, v166
	v_mul_f32_e32 v164, v164, v165
	v_add_f32_e32 v165, v75, v79
	v_mul_f32_e32 v165, 0xbfb8aa3b, v165
	v_exp_f32_e32 v165, v165
	s_nop 0
	v_add_f32_e32 v165, 1.0, v165
	s_nop 0
	v_rcp_f32_e32 v165, v165
	v_add_f32_e32 v166, v73, v77
	v_mul_f32_e32 v166, 0xbfb8aa3b, v166
	v_exp_f32_e32 v166, v166
	s_nop 0
	v_add_f32_e32 v166, 1.0, v166
	s_nop 0
	v_rcp_f32_e32 v166, v166
	v_and_b32_e32 v167, 0xffff0000, v146
	v_sqrt_f32_e32 v171, v171
	v_lshlrev_b32_e32 v146, 16, v146
	v_mul_f32_e32 v166, v166, v171
	v_mul_f32_e32 v166, v166, v167
	v_add_f32_e32 v167, v72, v76
	v_mul_f32_e32 v167, 0xbfb8aa3b, v167
	v_exp_f32_e32 v167, v167
	s_nop 0
	v_add_f32_e32 v167, 1.0, v167
	s_nop 0
	v_rcp_f32_e32 v167, v167
	v_lshl_add_u64 v[224:225], s[58:59], 0, v[144:145]
	v_sqrt_f32_e32 v150, v150
	v_lshl_add_u64 v[226:227], s[0:1], 0, v[144:145]
	v_add_f32_e32 v144, v68, v88
	v_mul_f32_e32 v150, v167, v150
	v_mul_f32_e32 v150, v150, v146
	v_and_b32_e32 v146, 0xffff0000, v147
	v_max_f32_e32 v147, 0, v170
	v_mul_f32_e32 v144, 0xbfb8aa3b, v144
	v_exp_f32_e32 v144, v144
	v_sqrt_f32_e32 v147, v147
	v_add_f32_e32 v144, 1.0, v144
	v_mul_f32_e32 v147, v165, v147
	v_mul_f32_e32 v165, v147, v146
	v_cvt_pk_bf16_f32 v146, v148, v149
	v_cvt_pk_bf16_f32 v147, v151, v168
	global_store_dwordx2 v[224:225], v[146:147], off
	v_cvt_pk_bf16_f32 v146, v150, v166
	v_cvt_pk_bf16_f32 v147, v164, v165
	global_store_dwordx2 v[226:227], v[146:147], off
	s_nop 0
	v_rcp_f32_e32 v144, v144
	s_nop 0
	v_mul_f32_e32 v144, 0xc1000000, v144
	v_mul_f32_e32 v144, v84, v144
	v_add_f32_e32 v145, v144, v144
	v_cmp_nlt_f32_e32 vcc, s51, v145
	s_and_saveexec_b64 s[8:9], vcc
	s_xor_b64 s[8:9], exec, s[8:9]
	v_mul_f32_e32 v145, 0x3fb8aa3b, v145
	v_exp_f32_e32 v145, v145
	s_nop 0
	v_sub_f32_e32 v146, 1.0, v145
	s_andn2_saveexec_b64 s[8:9], s[8:9]
	v_fma_f32 v146, v145, s14, 0.5
	v_fma_f32 v146, v145, v146, 1.0
	v_mul_f32_e64 v146, v146, -v145
	s_or_b64 exec, exec, s[8:9]
	v_add_f32_e32 v145, v69, v89
	v_mul_f32_e32 v145, 0xbfb8aa3b, v145
	v_exp_f32_e32 v145, v145
	s_nop 0
	v_add_f32_e32 v145, 1.0, v145
	v_rcp_f32_e32 v145, v145
	s_nop 0
	v_mul_f32_e32 v145, 0xc1000000, v145
	v_mul_f32_e32 v145, v85, v145
	v_add_f32_e32 v147, v145, v145
	v_cmp_nlt_f32_e32 vcc, s51, v147
	s_and_saveexec_b64 s[8:9], vcc
	s_xor_b64 s[8:9], exec, s[8:9]
	v_mul_f32_e32 v147, 0x3fb8aa3b, v147
	v_exp_f32_e32 v147, v147
	s_nop 0
	v_sub_f32_e32 v150, 1.0, v147
	s_andn2_saveexec_b64 s[8:9], s[8:9]
	v_fma_f32 v148, v147, s14, 0.5
	v_fma_f32 v148, v147, v148, 1.0
	v_mul_f32_e64 v150, v148, -v147
	s_or_b64 exec, exec, s[8:9]
	v_add_f32_e32 v147, v70, v90
	v_mul_f32_e32 v147, 0xbfb8aa3b, v147
	v_exp_f32_e32 v147, v147
	s_nop 0
	v_add_f32_e32 v147, 1.0, v147
	v_rcp_f32_e32 v147, v147
	s_nop 0
	v_mul_f32_e32 v147, 0xc1000000, v147
	v_mul_f32_e32 v147, v86, v147
	v_add_f32_e32 v148, v147, v147
	v_cmp_nlt_f32_e32 vcc, s51, v148
	s_and_saveexec_b64 s[8:9], vcc
	s_xor_b64 s[8:9], exec, s[8:9]
	v_mul_f32_e32 v148, 0x3fb8aa3b, v148
	v_exp_f32_e32 v148, v148
	s_nop 0
	v_sub_f32_e32 v151, 1.0, v148
	s_andn2_saveexec_b64 s[8:9], s[8:9]
	v_fma_f32 v149, v148, s14, 0.5
	v_fma_f32 v149, v148, v149, 1.0
	v_mul_f32_e64 v151, v149, -v148
	s_or_b64 exec, exec, s[8:9]
	v_add_f32_e32 v148, v71, v91
	v_mul_f32_e32 v148, 0xbfb8aa3b, v148
	v_exp_f32_e32 v148, v148
	s_nop 0
	v_add_f32_e32 v148, 1.0, v148
	v_rcp_f32_e32 v148, v148
	s_nop 0
	v_mul_f32_e32 v148, 0xc1000000, v148
	v_mul_f32_e32 v148, v87, v148
	v_add_f32_e32 v168, v148, v148
	v_cmp_nlt_f32_e32 vcc, s51, v168
	s_and_saveexec_b64 s[8:9], vcc
	s_xor_b64 s[8:9], exec, s[8:9]
	v_mul_f32_e32 v149, 0x3fb8aa3b, v168
	v_exp_f32_e32 v149, v149
	s_nop 0
	v_sub_f32_e32 v149, 1.0, v149
	s_andn2_saveexec_b64 s[8:9], s[8:9]
	v_fma_f32 v149, v168, s14, 0.5
	v_fma_f32 v149, v168, v149, 1.0
	v_mul_f32_e64 v149, v149, -v168
	s_or_b64 exec, exec, s[8:9]
	v_add_f32_e32 v164, v66, v78
	v_mul_f32_e32 v164, 0xbfb8aa3b, v164
	v_exp_f32_e32 v164, v164
	v_max_f32_e32 v151, 0, v151
	v_add_f32_e32 v164, 1.0, v164
	v_max_f32_e32 v150, 0, v150
	v_max_f32_e32 v146, 0, v146
	v_rcp_f32_e32 v164, v164
	v_lshlrev_b32_e32 v165, 16, v141
	v_sqrt_f32_e32 v151, v151
	v_lshlrev_b64 v[142:143], 10, v[142:143]
	v_lshl_add_u64 v[234:235], s[28:29], 0, v[178:179]
	v_mul_f32_e32 v151, v164, v151
	v_add_f32_e32 v164, v67, v79
	v_mul_f32_e32 v164, 0xbfb8aa3b, v164
	v_exp_f32_e32 v164, v164
	v_mul_f32_e32 v151, v151, v165
	v_add_f32_e32 v164, 1.0, v164
	s_nop 0
	v_rcp_f32_e32 v164, v164
	v_add_f32_e32 v165, v65, v77
	v_mul_f32_e32 v165, 0xbfb8aa3b, v165
	v_exp_f32_e32 v165, v165
	s_nop 0
	v_add_f32_e32 v165, 1.0, v165
	s_nop 0
	v_rcp_f32_e32 v165, v165
	v_and_b32_e32 v166, 0xffff0000, v140
	v_sqrt_f32_e32 v150, v150
	v_lshlrev_b32_e32 v140, 16, v140
	v_mul_f32_e32 v150, v165, v150
	v_add_f32_e32 v165, v64, v76
	v_mul_f32_e32 v165, 0xbfb8aa3b, v165
	v_exp_f32_e32 v165, v165
	v_mul_f32_e32 v150, v150, v166
	v_add_f32_e32 v165, 1.0, v165
	s_nop 0
	v_rcp_f32_e32 v165, v165
	v_or_b32_e32 v170, 64, v180
	v_sqrt_f32_e32 v146, v146
	v_ashrrev_i32_e32 v171, 31, v170
	v_lshlrev_b64 v[232:233], 1, v[170:171]
	v_mul_f32_e32 v146, v165, v146
	v_mul_f32_e32 v146, v146, v140
	v_and_b32_e32 v140, 0xffff0000, v141
	v_max_f32_e32 v141, 0, v149
	v_lshl_add_u64 v[170:171], v[234:235], 0, v[232:233]
	s_nop 0
	v_sqrt_f32_e32 v141, v141
	s_nop 0
	v_mul_f32_e32 v141, v164, v141
	v_mul_f32_e32 v149, v141, v140
	v_lshl_add_u64 v[140:141], v[142:143], 0, v[180:181]
	v_lshlrev_b64 v[140:141], 1, v[140:141]
	v_cvt_pk_bf16_f32 v142, v144, v145
	v_cvt_pk_bf16_f32 v143, v147, v148
	v_lshl_add_u64 v[228:229], s[58:59], 0, v[140:141]
	v_lshl_add_u64 v[230:231], s[0:1], 0, v[140:141]
	global_store_dwordx2 v[228:229], v[142:143], off
	v_cvt_pk_bf16_f32 v142, v146, v150
	v_cvt_pk_bf16_f32 v143, v151, v149
	global_store_dwordx2 v[230:231], v[142:143], off
	global_load_dwordx4 v[148:151], v[172:173], off offset:256
	s_nop 0
	global_load_dwordx4 v[140:143], v[158:159], off offset:256
	global_load_dwordx4 v[144:147], v[174:175], off offset:256
	global_load_dwordx2 v[236:237], v[170:171], off
	v_lshl_add_u64 v[170:171], s[28:29], 0, v[176:177]
	v_lshl_add_u64 v[170:171], v[170:171], 0, v[232:233]
	global_load_dwordx2 v[234:235], v[170:171], off
	s_waitcnt vmcnt(0)
	v_add_f32_e32 v164, v60, v148
	v_mul_f32_e32 v164, 0xbfb8aa3b, v164
	v_exp_f32_e32 v164, v164
	s_nop 0
	v_add_f32_e32 v164, 1.0, v164
	s_nop 0
	v_rcp_f32_e32 v164, v164
	s_nop 0
	v_mul_f32_e32 v164, 0xc1000000, v164
	v_mul_f32_e32 v168, v144, v164
	v_add_f32_e32 v170, v168, v168
	v_cmp_nlt_f32_e32 vcc, s51, v170
	s_and_saveexec_b64 s[0:1], vcc
	s_xor_b64 s[0:1], exec, s[0:1]
	v_mul_f32_e32 v164, 0x3fb8aa3b, v170
	v_exp_f32_e32 v164, v164
	s_nop 0
	v_sub_f32_e32 v171, 1.0, v164
	s_andn2_saveexec_b64 s[0:1], s[0:1]
	v_fma_f32 v164, v170, s14, 0.5
	v_fma_f32 v164, v170, v164, 1.0
	v_mul_f32_e64 v171, v164, -v170
	s_or_b64 exec, exec, s[0:1]
	v_add_f32_e32 v164, v61, v149
	v_mul_f32_e32 v164, 0xbfb8aa3b, v164
	v_exp_f32_e32 v164, v164
	s_nop 0
	v_add_f32_e32 v164, 1.0, v164
	v_rcp_f32_e32 v164, v164
	s_nop 0
	v_mul_f32_e32 v164, 0xc1000000, v164
	v_mul_f32_e32 v170, v145, v164
	v_add_f32_e32 v241, v170, v170
	v_cmp_nlt_f32_e32 vcc, s51, v241
	s_and_saveexec_b64 s[0:1], vcc
	s_xor_b64 s[0:1], exec, s[0:1]
	v_mul_f32_e32 v164, 0x3fb8aa3b, v241
	v_exp_f32_e32 v164, v164
	s_nop 0
	v_sub_f32_e32 v244, 1.0, v164
	s_andn2_saveexec_b64 s[0:1], s[0:1]
	v_fma_f32 v164, v241, s14, 0.5
	v_fma_f32 v164, v241, v164, 1.0
	v_mul_f32_e64 v244, v164, -v241
	s_or_b64 exec, exec, s[0:1]
	v_add_f32_e32 v164, v62, v150
	v_mul_f32_e32 v164, 0xbfb8aa3b, v164
	v_exp_f32_e32 v164, v164
	s_nop 0
	v_add_f32_e32 v164, 1.0, v164
	v_rcp_f32_e32 v164, v164
	s_nop 0
	v_mul_f32_e32 v164, 0xc1000000, v164
	v_mul_f32_e32 v241, v146, v164
	v_add_f32_e32 v242, v241, v241
	v_cmp_nlt_f32_e32 vcc, s51, v242
	s_and_saveexec_b64 s[0:1], vcc
	s_xor_b64 s[0:1], exec, s[0:1]
	v_mul_f32_e32 v164, 0x3fb8aa3b, v242
	v_exp_f32_e32 v164, v164
	s_nop 0
	v_sub_f32_e32 v245, 1.0, v164
	s_andn2_saveexec_b64 s[0:1], s[0:1]
	v_fma_f32 v164, v242, s14, 0.5
	v_fma_f32 v164, v242, v164, 1.0
	v_mul_f32_e64 v245, v164, -v242
	s_or_b64 exec, exec, s[0:1]
	v_add_f32_e32 v164, v63, v151
	v_mul_f32_e32 v164, 0xbfb8aa3b, v164
	v_exp_f32_e32 v164, v164
	s_nop 0
	v_add_f32_e32 v164, 1.0, v164
	v_rcp_f32_e32 v164, v164
	s_nop 0
	v_mul_f32_e32 v164, 0xc1000000, v164
	v_mul_f32_e32 v242, v147, v164
	v_add_f32_e32 v246, v242, v242
	v_cmp_nlt_f32_e32 vcc, s51, v246
	s_and_saveexec_b64 s[0:1], vcc
	s_xor_b64 s[0:1], exec, s[0:1]
	v_mul_f32_e32 v164, 0x3fb8aa3b, v246
	v_exp_f32_e32 v164, v164
	s_nop 0
	v_sub_f32_e32 v243, 1.0, v164
	s_andn2_saveexec_b64 s[0:1], s[0:1]
	v_fma_f32 v164, v246, s14, 0.5
	v_fma_f32 v164, v246, v164, 1.0
	v_mul_f32_e64 v243, v164, -v246
	s_or_b64 exec, exec, s[0:1]
	v_add_f32_e32 v164, v58, v142
	v_mul_f32_e32 v164, 0xbfb8aa3b, v164
	v_exp_f32_e32 v164, v164
	v_max_f32_e32 v171, 0, v171
	v_cvt_pk_bf16_f32 v170, v168, v170
	v_add_f32_e32 v164, 1.0, v164
	s_nop 0
	v_max_f32_e32 v166, 0, v245
	v_rcp_f32_e32 v164, v164
	v_lshlrev_b32_e32 v165, 16, v237
	v_sqrt_f32_e32 v166, v166
	s_nop 0
	v_mul_f32_e32 v164, v164, v166
	v_mul_f32_e32 v164, v164, v165
	v_add_f32_e32 v165, v59, v143
	v_mul_f32_e32 v165, 0xbfb8aa3b, v165
	v_exp_f32_e32 v165, v165
	s_nop 0
	v_add_f32_e32 v165, 1.0, v165
	s_nop 0
	v_rcp_f32_e32 v165, v165
	v_add_f32_e32 v166, v57, v141
	v_mul_f32_e32 v166, 0xbfb8aa3b, v166
	v_exp_f32_e32 v166, v166
	s_nop 0
	v_add_f32_e32 v166, 1.0, v166
	s_nop 0
	v_max_f32_e32 v169, 0, v244
	v_rcp_f32_e32 v166, v166
	v_and_b32_e32 v167, 0xffff0000, v236
	v_sqrt_f32_e32 v169, v169
	s_nop 0
	v_mul_f32_e32 v166, v166, v169
	v_add_f32_e32 v169, v56, v140
	v_mul_f32_e32 v169, 0xbfb8aa3b, v169
	v_exp_f32_e32 v169, v169
	v_mul_f32_e32 v166, v166, v167
	v_lshlrev_b32_e32 v167, 16, v236
	v_add_f32_e32 v169, 1.0, v169
	s_nop 0
	v_rcp_f32_e32 v169, v169
	s_nop 0
	v_sqrt_f32_e32 v171, v171
	s_nop 0
	v_mul_f32_e32 v169, v169, v171
	v_max_f32_e32 v171, 0, v243
	v_mul_f32_e32 v167, v169, v167
	v_and_b32_e32 v169, 0xffff0000, v237
	v_sqrt_f32_e32 v171, v171
	s_nop 0
	v_mul_f32_e32 v165, v165, v171
	v_cvt_pk_bf16_f32 v171, v241, v242
	v_mul_f32_e32 v165, v165, v169
	global_store_dwordx2 v[190:191], v[170:171], off offset:128
	v_cvt_pk_bf16_f32 v170, v167, v166
	v_cvt_pk_bf16_f32 v171, v164, v165
	v_add_f32_e32 v164, v52, v148
	v_mul_f32_e32 v164, 0xbfb8aa3b, v164
	v_exp_f32_e32 v164, v164
	global_store_dwordx2 v[194:195], v[170:171], off offset:128
	v_add_f32_e32 v164, 1.0, v164
	s_nop 0
	v_rcp_f32_e32 v164, v164
	s_nop 0
	v_mul_f32_e32 v164, 0xc1000000, v164
	v_mul_f32_e32 v168, v144, v164
	v_add_f32_e32 v170, v168, v168
	v_cmp_nlt_f32_e32 vcc, s51, v170
	s_and_saveexec_b64 s[0:1], vcc
	s_xor_b64 s[0:1], exec, s[0:1]
	v_mul_f32_e32 v164, 0x3fb8aa3b, v170
	v_exp_f32_e32 v164, v164
	s_nop 0
	v_sub_f32_e32 v171, 1.0, v164
	s_andn2_saveexec_b64 s[0:1], s[0:1]
	v_fma_f32 v164, v170, s14, 0.5
	v_fma_f32 v164, v170, v164, 1.0
	v_mul_f32_e64 v171, v164, -v170
	s_or_b64 exec, exec, s[0:1]
	v_add_f32_e32 v164, v53, v149
	v_mul_f32_e32 v164, 0xbfb8aa3b, v164
	v_exp_f32_e32 v164, v164
	s_nop 0
	v_add_f32_e32 v164, 1.0, v164
	v_rcp_f32_e32 v164, v164
	s_nop 0
	v_mul_f32_e32 v164, 0xc1000000, v164
	v_mul_f32_e32 v170, v145, v164
	v_add_f32_e32 v190, v170, v170
	v_cmp_nlt_f32_e32 vcc, s51, v190
	s_and_saveexec_b64 s[0:1], vcc
	s_xor_b64 s[0:1], exec, s[0:1]
	v_mul_f32_e32 v164, 0x3fb8aa3b, v190
	v_exp_f32_e32 v164, v164
	s_nop 0
	v_sub_f32_e32 v195, 1.0, v164
	s_andn2_saveexec_b64 s[0:1], s[0:1]
	v_fma_f32 v164, v190, s14, 0.5
	v_fma_f32 v164, v190, v164, 1.0
	v_mul_f32_e64 v195, v164, -v190
	s_or_b64 exec, exec, s[0:1]
	v_add_f32_e32 v164, v54, v150
	v_mul_f32_e32 v164, 0xbfb8aa3b, v164
	v_exp_f32_e32 v164, v164
	s_nop 0
	v_add_f32_e32 v164, 1.0, v164
	v_rcp_f32_e32 v164, v164
	s_nop 0
	v_mul_f32_e32 v164, 0xc1000000, v164
	v_mul_f32_e32 v190, v146, v164
	v_add_f32_e32 v191, v190, v190
	v_cmp_nlt_f32_e32 vcc, s51, v191
	s_and_saveexec_b64 s[0:1], vcc
	s_xor_b64 s[0:1], exec, s[0:1]
	v_mul_f32_e32 v164, 0x3fb8aa3b, v191
	v_exp_f32_e32 v164, v164
	s_nop 0
	v_sub_f32_e32 v236, 1.0, v164
	s_andn2_saveexec_b64 s[0:1], s[0:1]
	v_fma_f32 v164, v191, s14, 0.5
	v_fma_f32 v164, v191, v164, 1.0
	v_mul_f32_e64 v236, v164, -v191
	s_or_b64 exec, exec, s[0:1]
	v_add_f32_e32 v164, v55, v151
	v_mul_f32_e32 v164, 0xbfb8aa3b, v164
	v_exp_f32_e32 v164, v164
	s_nop 0
	v_add_f32_e32 v164, 1.0, v164
	v_rcp_f32_e32 v164, v164
	s_nop 0
	v_mul_f32_e32 v164, 0xc1000000, v164
	v_mul_f32_e32 v191, v147, v164
	v_add_f32_e32 v237, v191, v191
	v_cmp_nlt_f32_e32 vcc, s51, v237
	s_and_saveexec_b64 s[0:1], vcc
	s_xor_b64 s[0:1], exec, s[0:1]
	v_mul_f32_e32 v164, 0x3fb8aa3b, v237
	v_exp_f32_e32 v164, v164
	s_nop 0
	v_sub_f32_e32 v194, 1.0, v164
	s_andn2_saveexec_b64 s[0:1], s[0:1]
	v_fma_f32 v164, v237, s14, 0.5
	v_fma_f32 v164, v237, v164, 1.0
	v_mul_f32_e64 v194, v164, -v237
	s_or_b64 exec, exec, s[0:1]
	v_add_f32_e32 v164, v50, v142
	v_mul_f32_e32 v164, 0xbfb8aa3b, v164
	v_exp_f32_e32 v164, v164
	v_max_f32_e32 v171, 0, v171
	v_cvt_pk_bf16_f32 v170, v168, v170
	v_add_f32_e32 v164, 1.0, v164
	s_nop 0
	v_max_f32_e32 v166, 0, v236
	v_rcp_f32_e32 v164, v164
	v_lshlrev_b32_e32 v165, 16, v235
	v_sqrt_f32_e32 v166, v166
	s_nop 0
	v_mul_f32_e32 v164, v164, v166
	v_mul_f32_e32 v164, v164, v165
	v_add_f32_e32 v165, v51, v143
	v_mul_f32_e32 v165, 0xbfb8aa3b, v165
	v_exp_f32_e32 v165, v165
	s_nop 0
	v_add_f32_e32 v165, 1.0, v165
	s_nop 0
	v_rcp_f32_e32 v165, v165
	v_add_f32_e32 v166, v49, v141
	v_mul_f32_e32 v166, 0xbfb8aa3b, v166
	v_exp_f32_e32 v166, v166
	s_nop 0
	v_add_f32_e32 v166, 1.0, v166
	s_nop 0
	v_max_f32_e32 v169, 0, v195
	v_rcp_f32_e32 v166, v166
	v_and_b32_e32 v167, 0xffff0000, v234
	v_sqrt_f32_e32 v169, v169
	s_nop 0
	v_mul_f32_e32 v166, v166, v169
	v_add_f32_e32 v169, v48, v140
	v_mul_f32_e32 v169, 0xbfb8aa3b, v169
	v_exp_f32_e32 v169, v169
	v_mul_f32_e32 v166, v166, v167
	v_lshlrev_b32_e32 v167, 16, v234
	v_add_f32_e32 v169, 1.0, v169
	s_nop 0
	v_rcp_f32_e32 v169, v169
	s_nop 0
	v_sqrt_f32_e32 v171, v171
	s_nop 0
	v_mul_f32_e32 v169, v169, v171
	v_max_f32_e32 v171, 0, v194
	v_mul_f32_e32 v167, v169, v167
	v_and_b32_e32 v169, 0xffff0000, v235
	v_sqrt_f32_e32 v171, v171
	s_nop 0
	v_mul_f32_e32 v165, v165, v171
	v_cvt_pk_bf16_f32 v171, v190, v191
	v_mul_f32_e32 v165, v165, v169
	global_store_dwordx2 v[188:189], v[170:171], off offset:128
	v_cvt_pk_bf16_f32 v170, v167, v166
	v_cvt_pk_bf16_f32 v171, v164, v165
	global_store_dwordx2 v[192:193], v[170:171], off offset:128
	v_lshl_add_u64 v[170:171], s[28:29], 0, v[196:197]
	v_lshl_add_u64 v[170:171], v[170:171], 0, v[232:233]
	global_load_dwordx2 v[190:191], v[170:171], off
	v_lshl_add_u64 v[170:171], s[28:29], 0, v[198:199]
	v_lshl_add_u64 v[170:171], v[170:171], 0, v[232:233]
	global_load_dwordx2 v[188:189], v[170:171], off
	v_add_f32_e32 v164, v44, v148
	v_mul_f32_e32 v164, 0xbfb8aa3b, v164
	v_exp_f32_e32 v164, v164
	s_nop 0
	v_add_f32_e32 v164, 1.0, v164
	s_nop 0
	v_rcp_f32_e32 v164, v164
	s_nop 0
	v_mul_f32_e32 v164, 0xc1000000, v164
	v_mul_f32_e32 v168, v144, v164
	v_add_f32_e32 v170, v168, v168
	v_cmp_nlt_f32_e32 vcc, s51, v170
	s_and_saveexec_b64 s[0:1], vcc
	s_xor_b64 s[0:1], exec, s[0:1]
	v_mul_f32_e32 v164, 0x3fb8aa3b, v170
	v_exp_f32_e32 v164, v164
	s_nop 0
	v_sub_f32_e32 v171, 1.0, v164
	s_andn2_saveexec_b64 s[0:1], s[0:1]
	v_fma_f32 v164, v170, s14, 0.5
	v_fma_f32 v164, v170, v164, 1.0
	v_mul_f32_e64 v171, v164, -v170
	s_or_b64 exec, exec, s[0:1]
	v_add_f32_e32 v164, v45, v149
	v_mul_f32_e32 v164, 0xbfb8aa3b, v164
	v_exp_f32_e32 v164, v164
	s_nop 0
	v_add_f32_e32 v164, 1.0, v164
	v_rcp_f32_e32 v164, v164
	s_nop 0
	v_mul_f32_e32 v164, 0xc1000000, v164
	v_mul_f32_e32 v170, v145, v164
	v_add_f32_e32 v192, v170, v170
	v_cmp_nlt_f32_e32 vcc, s51, v192
	s_and_saveexec_b64 s[0:1], vcc
	s_xor_b64 s[0:1], exec, s[0:1]
	v_mul_f32_e32 v164, 0x3fb8aa3b, v192
	v_exp_f32_e32 v164, v164
	s_nop 0
	v_sub_f32_e32 v195, 1.0, v164
	s_andn2_saveexec_b64 s[0:1], s[0:1]
	v_fma_f32 v164, v192, s14, 0.5
	v_fma_f32 v164, v192, v164, 1.0
	v_mul_f32_e64 v195, v164, -v192
	s_or_b64 exec, exec, s[0:1]
	v_add_f32_e32 v164, v46, v150
	v_mul_f32_e32 v164, 0xbfb8aa3b, v164
	v_exp_f32_e32 v164, v164
	s_nop 0
	v_add_f32_e32 v164, 1.0, v164
	v_rcp_f32_e32 v164, v164
	s_nop 0
	v_mul_f32_e32 v164, 0xc1000000, v164
	v_mul_f32_e32 v192, v146, v164
	v_add_f32_e32 v193, v192, v192
	v_cmp_nlt_f32_e32 vcc, s51, v193
	s_and_saveexec_b64 s[0:1], vcc
	s_xor_b64 s[0:1], exec, s[0:1]
	v_mul_f32_e32 v164, 0x3fb8aa3b, v193
	v_exp_f32_e32 v164, v164
	s_nop 0
	v_sub_f32_e32 v196, 1.0, v164
	s_andn2_saveexec_b64 s[0:1], s[0:1]
	v_fma_f32 v164, v193, s14, 0.5
	v_fma_f32 v164, v193, v164, 1.0
	v_mul_f32_e64 v196, v164, -v193
	s_or_b64 exec, exec, s[0:1]
	v_add_f32_e32 v164, v47, v151
	v_mul_f32_e32 v164, 0xbfb8aa3b, v164
	v_exp_f32_e32 v164, v164
	s_nop 0
	v_add_f32_e32 v164, 1.0, v164
	v_rcp_f32_e32 v164, v164
	s_nop 0
	v_mul_f32_e32 v164, 0xc1000000, v164
	v_mul_f32_e32 v193, v147, v164
	v_add_f32_e32 v197, v193, v193
	v_cmp_nlt_f32_e32 vcc, s51, v197
	s_and_saveexec_b64 s[0:1], vcc
	s_xor_b64 s[0:1], exec, s[0:1]
	v_mul_f32_e32 v164, 0x3fb8aa3b, v197
	v_exp_f32_e32 v164, v164
	s_nop 0
	v_sub_f32_e32 v194, 1.0, v164
	s_andn2_saveexec_b64 s[0:1], s[0:1]
	v_fma_f32 v164, v197, s14, 0.5
	v_fma_f32 v164, v197, v164, 1.0
	v_mul_f32_e64 v194, v164, -v197
	s_or_b64 exec, exec, s[0:1]
	v_add_f32_e32 v164, v42, v142
	v_mul_f32_e32 v164, 0xbfb8aa3b, v164
	v_exp_f32_e32 v164, v164
	v_max_f32_e32 v171, 0, v171
	v_cvt_pk_bf16_f32 v170, v168, v170
	v_add_f32_e32 v164, 1.0, v164
	s_nop 0
	v_max_f32_e32 v166, 0, v196
	v_rcp_f32_e32 v164, v164
	s_waitcnt vmcnt(0)
	v_lshlrev_b32_e32 v165, 16, v191
	v_sqrt_f32_e32 v166, v166
	s_nop 0
	v_mul_f32_e32 v164, v164, v166
	v_mul_f32_e32 v164, v164, v165
	v_add_f32_e32 v165, v43, v143
	v_mul_f32_e32 v165, 0xbfb8aa3b, v165
	v_exp_f32_e32 v165, v165
	s_nop 0
	v_add_f32_e32 v165, 1.0, v165
	s_nop 0
	v_rcp_f32_e32 v165, v165
	v_add_f32_e32 v166, v41, v141
	v_mul_f32_e32 v166, 0xbfb8aa3b, v166
	v_exp_f32_e32 v166, v166
	s_nop 0
	v_add_f32_e32 v166, 1.0, v166
	s_nop 0
	v_max_f32_e32 v169, 0, v195
	v_rcp_f32_e32 v166, v166
	v_and_b32_e32 v167, 0xffff0000, v190
	v_sqrt_f32_e32 v169, v169
	s_nop 0
	v_mul_f32_e32 v166, v166, v169
	v_add_f32_e32 v169, v40, v140
	v_mul_f32_e32 v169, 0xbfb8aa3b, v169
	v_exp_f32_e32 v169, v169
	v_mul_f32_e32 v166, v166, v167
	v_lshlrev_b32_e32 v167, 16, v190
	v_add_f32_e32 v169, 1.0, v169
	s_nop 0
	v_rcp_f32_e32 v169, v169
	s_nop 0
	v_sqrt_f32_e32 v171, v171
	s_nop 0
	v_mul_f32_e32 v169, v169, v171
	v_max_f32_e32 v171, 0, v194
	v_mul_f32_e32 v167, v169, v167
	v_and_b32_e32 v169, 0xffff0000, v191
	v_sqrt_f32_e32 v171, v171
	s_nop 0
	v_mul_f32_e32 v165, v165, v171
	v_cvt_pk_bf16_f32 v171, v192, v193
	v_mul_f32_e32 v165, v165, v169
	global_store_dwordx2 v[202:203], v[170:171], off offset:128
	v_cvt_pk_bf16_f32 v170, v167, v166
	v_cvt_pk_bf16_f32 v171, v164, v165
	v_add_f32_e32 v164, v36, v148
	v_mul_f32_e32 v164, 0xbfb8aa3b, v164
	v_exp_f32_e32 v164, v164
	global_store_dwordx2 v[206:207], v[170:171], off offset:128
	v_add_f32_e32 v164, 1.0, v164
	s_nop 0
	v_rcp_f32_e32 v164, v164
	s_nop 0
	v_mul_f32_e32 v164, 0xc1000000, v164
	v_mul_f32_e32 v168, v144, v164
	v_add_f32_e32 v170, v168, v168
	v_cmp_nlt_f32_e32 vcc, s51, v170
	s_and_saveexec_b64 s[0:1], vcc
	s_xor_b64 s[0:1], exec, s[0:1]
	v_mul_f32_e32 v164, 0x3fb8aa3b, v170
	v_exp_f32_e32 v164, v164
	s_nop 0
	v_sub_f32_e32 v171, 1.0, v164
	s_andn2_saveexec_b64 s[0:1], s[0:1]
	v_fma_f32 v164, v170, s14, 0.5
	v_fma_f32 v164, v170, v164, 1.0
	v_mul_f32_e64 v171, v164, -v170
	s_or_b64 exec, exec, s[0:1]
	v_add_f32_e32 v164, v37, v149
	v_mul_f32_e32 v164, 0xbfb8aa3b, v164
	v_exp_f32_e32 v164, v164
	s_nop 0
	v_add_f32_e32 v164, 1.0, v164
	v_rcp_f32_e32 v164, v164
	s_nop 0
	v_mul_f32_e32 v164, 0xc1000000, v164
	v_mul_f32_e32 v170, v145, v164
	v_add_f32_e32 v190, v170, v170
	v_cmp_nlt_f32_e32 vcc, s51, v190
	s_and_saveexec_b64 s[0:1], vcc
	s_xor_b64 s[0:1], exec, s[0:1]
	v_mul_f32_e32 v164, 0x3fb8aa3b, v190
	v_exp_f32_e32 v164, v164
	s_nop 0
	v_sub_f32_e32 v193, 1.0, v164
	s_andn2_saveexec_b64 s[0:1], s[0:1]
	v_fma_f32 v164, v190, s14, 0.5
	v_fma_f32 v164, v190, v164, 1.0
	v_mul_f32_e64 v193, v164, -v190
	s_or_b64 exec, exec, s[0:1]
	v_add_f32_e32 v164, v38, v150
	v_mul_f32_e32 v164, 0xbfb8aa3b, v164
	v_exp_f32_e32 v164, v164
	s_nop 0
	v_add_f32_e32 v164, 1.0, v164
	v_rcp_f32_e32 v164, v164
	s_nop 0
	v_mul_f32_e32 v164, 0xc1000000, v164
	v_mul_f32_e32 v190, v146, v164
	v_add_f32_e32 v191, v190, v190
	v_cmp_nlt_f32_e32 vcc, s51, v191
	s_and_saveexec_b64 s[0:1], vcc
	s_xor_b64 s[0:1], exec, s[0:1]
	v_mul_f32_e32 v164, 0x3fb8aa3b, v191
	v_exp_f32_e32 v164, v164
	s_nop 0
	v_sub_f32_e32 v194, 1.0, v164
	s_andn2_saveexec_b64 s[0:1], s[0:1]
	v_fma_f32 v164, v191, s14, 0.5
	v_fma_f32 v164, v191, v164, 1.0
	v_mul_f32_e64 v194, v164, -v191
	s_or_b64 exec, exec, s[0:1]
	v_add_f32_e32 v164, v39, v151
	v_mul_f32_e32 v164, 0xbfb8aa3b, v164
	v_exp_f32_e32 v164, v164
	s_nop 0
	v_add_f32_e32 v164, 1.0, v164
	v_rcp_f32_e32 v164, v164
	s_nop 0
	v_mul_f32_e32 v164, 0xc1000000, v164
	v_mul_f32_e32 v191, v147, v164
	v_add_f32_e32 v195, v191, v191
	v_cmp_nlt_f32_e32 vcc, s51, v195
	s_and_saveexec_b64 s[0:1], vcc
	s_xor_b64 s[0:1], exec, s[0:1]
	v_mul_f32_e32 v164, 0x3fb8aa3b, v195
	v_exp_f32_e32 v164, v164
	s_nop 0
	v_sub_f32_e32 v192, 1.0, v164
	s_andn2_saveexec_b64 s[0:1], s[0:1]
	v_fma_f32 v164, v195, s14, 0.5
	v_fma_f32 v164, v195, v164, 1.0
	v_mul_f32_e64 v192, v164, -v195
	s_or_b64 exec, exec, s[0:1]
	v_add_f32_e32 v164, v34, v142
	v_mul_f32_e32 v164, 0xbfb8aa3b, v164
	v_exp_f32_e32 v164, v164
	v_max_f32_e32 v171, 0, v171
	v_cvt_pk_bf16_f32 v170, v168, v170
	v_add_f32_e32 v164, 1.0, v164
	s_nop 0
	v_max_f32_e32 v166, 0, v194
	v_rcp_f32_e32 v164, v164
	v_lshlrev_b32_e32 v165, 16, v189
	v_sqrt_f32_e32 v166, v166
	s_nop 0
	v_mul_f32_e32 v164, v164, v166
	v_mul_f32_e32 v164, v164, v165
	v_add_f32_e32 v165, v35, v143
	v_mul_f32_e32 v165, 0xbfb8aa3b, v165
	v_exp_f32_e32 v165, v165
	s_nop 0
	v_add_f32_e32 v165, 1.0, v165
	s_nop 0
	v_rcp_f32_e32 v165, v165
	v_add_f32_e32 v166, v33, v141
	v_mul_f32_e32 v166, 0xbfb8aa3b, v166
	v_exp_f32_e32 v166, v166
	s_nop 0
	v_add_f32_e32 v166, 1.0, v166
	s_nop 0
	v_max_f32_e32 v169, 0, v193
	v_rcp_f32_e32 v166, v166
	v_and_b32_e32 v167, 0xffff0000, v188
	v_sqrt_f32_e32 v169, v169
	s_nop 0
	v_mul_f32_e32 v166, v166, v169
	v_add_f32_e32 v169, v32, v140
	v_mul_f32_e32 v169, 0xbfb8aa3b, v169
	v_exp_f32_e32 v169, v169
	v_mul_f32_e32 v166, v166, v167
	v_lshlrev_b32_e32 v167, 16, v188
	v_add_f32_e32 v169, 1.0, v169
	s_nop 0
	v_rcp_f32_e32 v169, v169
	s_nop 0
	v_sqrt_f32_e32 v171, v171
	s_nop 0
	v_mul_f32_e32 v169, v169, v171
	v_max_f32_e32 v171, 0, v192
	v_mul_f32_e32 v167, v169, v167
	v_and_b32_e32 v169, 0xffff0000, v189
	v_sqrt_f32_e32 v171, v171
	s_nop 0
	v_mul_f32_e32 v165, v165, v171
	v_cvt_pk_bf16_f32 v171, v190, v191
	v_mul_f32_e32 v165, v165, v169
	global_store_dwordx2 v[200:201], v[170:171], off offset:128
	v_cvt_pk_bf16_f32 v170, v167, v166
	v_cvt_pk_bf16_f32 v171, v164, v165
	global_store_dwordx2 v[204:205], v[170:171], off offset:128
	v_lshl_add_u64 v[170:171], s[28:29], 0, v[208:209]
	v_lshl_add_u64 v[170:171], v[170:171], 0, v[232:233]
	global_load_dwordx2 v[190:191], v[170:171], off
	v_lshl_add_u64 v[170:171], s[28:29], 0, v[210:211]
	v_lshl_add_u64 v[170:171], v[170:171], 0, v[232:233]
	global_load_dwordx2 v[188:189], v[170:171], off
	v_add_f32_e32 v164, v28, v148
	v_mul_f32_e32 v164, 0xbfb8aa3b, v164
	v_exp_f32_e32 v164, v164
	s_nop 0
	v_add_f32_e32 v164, 1.0, v164
	s_nop 0
	v_rcp_f32_e32 v164, v164
	s_nop 0
	v_mul_f32_e32 v164, 0xc1000000, v164
	v_mul_f32_e32 v168, v144, v164
	v_add_f32_e32 v170, v168, v168
	v_cmp_nlt_f32_e32 vcc, s51, v170
	s_and_saveexec_b64 s[0:1], vcc
	s_xor_b64 s[0:1], exec, s[0:1]
	v_mul_f32_e32 v164, 0x3fb8aa3b, v170
	v_exp_f32_e32 v164, v164
	s_nop 0
	v_sub_f32_e32 v171, 1.0, v164
	s_andn2_saveexec_b64 s[0:1], s[0:1]
	v_fma_f32 v164, v170, s14, 0.5
	v_fma_f32 v164, v170, v164, 1.0
	v_mul_f32_e64 v171, v164, -v170
	s_or_b64 exec, exec, s[0:1]
	v_add_f32_e32 v164, v29, v149
	v_mul_f32_e32 v164, 0xbfb8aa3b, v164
	v_exp_f32_e32 v164, v164
	s_nop 0
	v_add_f32_e32 v164, 1.0, v164
	v_rcp_f32_e32 v164, v164
	s_nop 0
	v_mul_f32_e32 v164, 0xc1000000, v164
	v_mul_f32_e32 v170, v145, v164
	v_add_f32_e32 v192, v170, v170
	v_cmp_nlt_f32_e32 vcc, s51, v192
	s_and_saveexec_b64 s[0:1], vcc
	s_xor_b64 s[0:1], exec, s[0:1]
	v_mul_f32_e32 v164, 0x3fb8aa3b, v192
	v_exp_f32_e32 v164, v164
	s_nop 0
	v_sub_f32_e32 v195, 1.0, v164
	s_andn2_saveexec_b64 s[0:1], s[0:1]
	v_fma_f32 v164, v192, s14, 0.5
	v_fma_f32 v164, v192, v164, 1.0
	v_mul_f32_e64 v195, v164, -v192
	s_or_b64 exec, exec, s[0:1]
	v_add_f32_e32 v164, v30, v150
	v_mul_f32_e32 v164, 0xbfb8aa3b, v164
	v_exp_f32_e32 v164, v164
	s_nop 0
	v_add_f32_e32 v164, 1.0, v164
	v_rcp_f32_e32 v164, v164
	s_nop 0
	v_mul_f32_e32 v164, 0xc1000000, v164
	v_mul_f32_e32 v192, v146, v164
	v_add_f32_e32 v193, v192, v192
	v_cmp_nlt_f32_e32 vcc, s51, v193
	s_and_saveexec_b64 s[0:1], vcc
	s_xor_b64 s[0:1], exec, s[0:1]
	v_mul_f32_e32 v164, 0x3fb8aa3b, v193
	v_exp_f32_e32 v164, v164
	s_nop 0
	v_sub_f32_e32 v196, 1.0, v164
	s_andn2_saveexec_b64 s[0:1], s[0:1]
	v_fma_f32 v164, v193, s14, 0.5
	v_fma_f32 v164, v193, v164, 1.0
	v_mul_f32_e64 v196, v164, -v193
	s_or_b64 exec, exec, s[0:1]
	v_add_f32_e32 v164, v31, v151
	v_mul_f32_e32 v164, 0xbfb8aa3b, v164
	v_exp_f32_e32 v164, v164
	s_nop 0
	v_add_f32_e32 v164, 1.0, v164
	v_rcp_f32_e32 v164, v164
	s_nop 0
	v_mul_f32_e32 v164, 0xc1000000, v164
	v_mul_f32_e32 v193, v147, v164
	v_add_f32_e32 v197, v193, v193
	v_cmp_nlt_f32_e32 vcc, s51, v197
	s_and_saveexec_b64 s[0:1], vcc
	s_xor_b64 s[0:1], exec, s[0:1]
	v_mul_f32_e32 v164, 0x3fb8aa3b, v197
	v_exp_f32_e32 v164, v164
	s_nop 0
	v_sub_f32_e32 v194, 1.0, v164
	s_andn2_saveexec_b64 s[0:1], s[0:1]
	v_fma_f32 v164, v197, s14, 0.5
	v_fma_f32 v164, v197, v164, 1.0
	v_mul_f32_e64 v194, v164, -v197
	s_or_b64 exec, exec, s[0:1]
	v_add_f32_e32 v164, v26, v142
	v_mul_f32_e32 v164, 0xbfb8aa3b, v164
	v_exp_f32_e32 v164, v164
	v_max_f32_e32 v171, 0, v171
	v_cvt_pk_bf16_f32 v170, v168, v170
	v_add_f32_e32 v164, 1.0, v164
	s_nop 0
	v_max_f32_e32 v166, 0, v196
	v_rcp_f32_e32 v164, v164
	s_waitcnt vmcnt(0)
	v_lshlrev_b32_e32 v165, 16, v191
	v_sqrt_f32_e32 v166, v166
	s_nop 0
	v_mul_f32_e32 v164, v164, v166
	v_mul_f32_e32 v164, v164, v165
	v_add_f32_e32 v165, v27, v143
	v_mul_f32_e32 v165, 0xbfb8aa3b, v165
	v_exp_f32_e32 v165, v165
	s_nop 0
	v_add_f32_e32 v165, 1.0, v165
	s_nop 0
	v_rcp_f32_e32 v165, v165
	v_add_f32_e32 v166, v25, v141
	v_mul_f32_e32 v166, 0xbfb8aa3b, v166
	v_exp_f32_e32 v166, v166
	s_nop 0
	v_add_f32_e32 v166, 1.0, v166
	s_nop 0
	v_max_f32_e32 v169, 0, v195
	v_rcp_f32_e32 v166, v166
	v_and_b32_e32 v167, 0xffff0000, v190
	v_sqrt_f32_e32 v169, v169
	s_nop 0
	v_mul_f32_e32 v166, v166, v169
	v_add_f32_e32 v169, v24, v140
	v_mul_f32_e32 v169, 0xbfb8aa3b, v169
	v_exp_f32_e32 v169, v169
	v_mul_f32_e32 v166, v166, v167
	v_lshlrev_b32_e32 v167, 16, v190
	v_add_f32_e32 v169, 1.0, v169
	s_nop 0
	v_rcp_f32_e32 v169, v169
	s_nop 0
	v_sqrt_f32_e32 v171, v171
	s_nop 0
	v_mul_f32_e32 v169, v169, v171
	v_max_f32_e32 v171, 0, v194
	v_mul_f32_e32 v167, v169, v167
	v_and_b32_e32 v169, 0xffff0000, v191
	v_sqrt_f32_e32 v171, v171
	s_nop 0
	v_mul_f32_e32 v165, v165, v171
	v_cvt_pk_bf16_f32 v171, v192, v193
	v_mul_f32_e32 v165, v165, v169
	global_store_dwordx2 v[214:215], v[170:171], off offset:128
	v_cvt_pk_bf16_f32 v170, v167, v166
	v_cvt_pk_bf16_f32 v171, v164, v165
	v_add_f32_e32 v164, v20, v148
	v_mul_f32_e32 v164, 0xbfb8aa3b, v164
	v_exp_f32_e32 v164, v164
	global_store_dwordx2 v[218:219], v[170:171], off offset:128
	v_add_f32_e32 v164, 1.0, v164
	s_nop 0
	v_rcp_f32_e32 v164, v164
	s_nop 0
	v_mul_f32_e32 v164, 0xc1000000, v164
	v_mul_f32_e32 v168, v144, v164
	v_add_f32_e32 v170, v168, v168
	v_cmp_nlt_f32_e32 vcc, s51, v170
	s_and_saveexec_b64 s[0:1], vcc
	s_xor_b64 s[0:1], exec, s[0:1]
	v_mul_f32_e32 v164, 0x3fb8aa3b, v170
	v_exp_f32_e32 v164, v164
	s_nop 0
	v_sub_f32_e32 v171, 1.0, v164
	s_andn2_saveexec_b64 s[0:1], s[0:1]
	v_fma_f32 v164, v170, s14, 0.5
	v_fma_f32 v164, v170, v164, 1.0
	v_mul_f32_e64 v171, v164, -v170
	s_or_b64 exec, exec, s[0:1]
	v_add_f32_e32 v164, v21, v149
	v_mul_f32_e32 v164, 0xbfb8aa3b, v164
	v_exp_f32_e32 v164, v164
	s_nop 0
	v_add_f32_e32 v164, 1.0, v164
	v_rcp_f32_e32 v164, v164
	s_nop 0
	v_mul_f32_e32 v164, 0xc1000000, v164
	v_mul_f32_e32 v170, v145, v164
	v_add_f32_e32 v190, v170, v170
	v_cmp_nlt_f32_e32 vcc, s51, v190
	s_and_saveexec_b64 s[0:1], vcc
	s_xor_b64 s[0:1], exec, s[0:1]
	v_mul_f32_e32 v164, 0x3fb8aa3b, v190
	v_exp_f32_e32 v164, v164
	s_nop 0
	v_sub_f32_e32 v193, 1.0, v164
	s_andn2_saveexec_b64 s[0:1], s[0:1]
	v_fma_f32 v164, v190, s14, 0.5
	v_fma_f32 v164, v190, v164, 1.0
	v_mul_f32_e64 v193, v164, -v190
	s_or_b64 exec, exec, s[0:1]
	v_add_f32_e32 v164, v22, v150
	v_mul_f32_e32 v164, 0xbfb8aa3b, v164
	v_exp_f32_e32 v164, v164
	s_nop 0
	v_add_f32_e32 v164, 1.0, v164
	v_rcp_f32_e32 v164, v164
	s_nop 0
	v_mul_f32_e32 v164, 0xc1000000, v164
	v_mul_f32_e32 v190, v146, v164
	v_add_f32_e32 v191, v190, v190
	v_cmp_nlt_f32_e32 vcc, s51, v191
	s_and_saveexec_b64 s[0:1], vcc
	s_xor_b64 s[0:1], exec, s[0:1]
	v_mul_f32_e32 v164, 0x3fb8aa3b, v191
	v_exp_f32_e32 v164, v164
	s_nop 0
	v_sub_f32_e32 v194, 1.0, v164
	s_andn2_saveexec_b64 s[0:1], s[0:1]
	v_fma_f32 v164, v191, s14, 0.5
	v_fma_f32 v164, v191, v164, 1.0
	v_mul_f32_e64 v194, v164, -v191
	s_or_b64 exec, exec, s[0:1]
	v_add_f32_e32 v164, v23, v151
	v_mul_f32_e32 v164, 0xbfb8aa3b, v164
	v_exp_f32_e32 v164, v164
	s_nop 0
	v_add_f32_e32 v164, 1.0, v164
	v_rcp_f32_e32 v164, v164
	s_nop 0
	v_mul_f32_e32 v164, 0xc1000000, v164
	v_mul_f32_e32 v191, v147, v164
	v_add_f32_e32 v195, v191, v191
	v_cmp_nlt_f32_e32 vcc, s51, v195
	s_and_saveexec_b64 s[0:1], vcc
	s_xor_b64 s[0:1], exec, s[0:1]
	v_mul_f32_e32 v164, 0x3fb8aa3b, v195
	v_exp_f32_e32 v164, v164
	s_nop 0
	v_sub_f32_e32 v192, 1.0, v164
	s_andn2_saveexec_b64 s[0:1], s[0:1]
	v_fma_f32 v164, v195, s14, 0.5
	v_fma_f32 v164, v195, v164, 1.0
	v_mul_f32_e64 v192, v164, -v195
	s_or_b64 exec, exec, s[0:1]
	v_add_f32_e32 v164, v18, v142
	v_mul_f32_e32 v164, 0xbfb8aa3b, v164
	v_exp_f32_e32 v164, v164
	v_max_f32_e32 v171, 0, v171
	v_cvt_pk_bf16_f32 v170, v168, v170
	v_add_f32_e32 v164, 1.0, v164
	s_nop 0
	v_max_f32_e32 v166, 0, v194
	v_rcp_f32_e32 v164, v164
	v_lshlrev_b32_e32 v165, 16, v189
	v_sqrt_f32_e32 v166, v166
	s_nop 0
	v_mul_f32_e32 v164, v164, v166
	v_mul_f32_e32 v164, v164, v165
	v_add_f32_e32 v165, v19, v143
	v_mul_f32_e32 v165, 0xbfb8aa3b, v165
	v_exp_f32_e32 v165, v165
	s_nop 0
	v_add_f32_e32 v165, 1.0, v165
	s_nop 0
	v_rcp_f32_e32 v165, v165
	v_add_f32_e32 v166, v17, v141
	v_mul_f32_e32 v166, 0xbfb8aa3b, v166
	v_exp_f32_e32 v166, v166
	s_nop 0
	v_add_f32_e32 v166, 1.0, v166
	s_nop 0
	v_max_f32_e32 v169, 0, v193
	v_rcp_f32_e32 v166, v166
	v_and_b32_e32 v167, 0xffff0000, v188
	v_sqrt_f32_e32 v169, v169
	s_nop 0
	v_mul_f32_e32 v166, v166, v169
	v_add_f32_e32 v169, v16, v140
	v_mul_f32_e32 v169, 0xbfb8aa3b, v169
	v_exp_f32_e32 v169, v169
	v_mul_f32_e32 v166, v166, v167
	v_lshlrev_b32_e32 v167, 16, v188
	v_add_f32_e32 v169, 1.0, v169
	s_nop 0
	v_rcp_f32_e32 v169, v169
	s_nop 0
	v_sqrt_f32_e32 v171, v171
	s_nop 0
	v_mul_f32_e32 v169, v169, v171
	v_max_f32_e32 v171, 0, v192
	v_mul_f32_e32 v167, v169, v167
	v_and_b32_e32 v169, 0xffff0000, v189
	v_sqrt_f32_e32 v171, v171
	s_nop 0
	v_mul_f32_e32 v165, v165, v171
	v_cvt_pk_bf16_f32 v171, v190, v191
	v_mul_f32_e32 v165, v165, v169
	global_store_dwordx2 v[212:213], v[170:171], off offset:128
	v_cvt_pk_bf16_f32 v170, v167, v166
	v_cvt_pk_bf16_f32 v171, v164, v165
	global_store_dwordx2 v[216:217], v[170:171], off offset:128
	v_lshl_add_u64 v[170:171], s[28:29], 0, v[220:221]
	v_lshl_add_u64 v[170:171], v[170:171], 0, v[232:233]
	global_load_dwordx2 v[190:191], v[170:171], off
	v_lshl_add_u64 v[170:171], s[28:29], 0, v[222:223]
	v_lshl_add_u64 v[170:171], v[170:171], 0, v[232:233]
	global_load_dwordx2 v[188:189], v[170:171], off
	v_add_f32_e32 v164, v12, v148
	v_mul_f32_e32 v164, 0xbfb8aa3b, v164
	v_exp_f32_e32 v164, v164
	s_nop 0
	v_add_f32_e32 v164, 1.0, v164
	s_nop 0
	v_rcp_f32_e32 v164, v164
	s_nop 0
	v_mul_f32_e32 v164, 0xc1000000, v164
	v_mul_f32_e32 v168, v144, v164
	v_add_f32_e32 v170, v168, v168
	v_cmp_nlt_f32_e32 vcc, s51, v170
	s_and_saveexec_b64 s[0:1], vcc
	s_xor_b64 s[0:1], exec, s[0:1]
	v_mul_f32_e32 v164, 0x3fb8aa3b, v170
	v_exp_f32_e32 v164, v164
	s_nop 0
	v_sub_f32_e32 v171, 1.0, v164
	s_andn2_saveexec_b64 s[0:1], s[0:1]
	v_fma_f32 v164, v170, s14, 0.5
	v_fma_f32 v164, v170, v164, 1.0
	v_mul_f32_e64 v171, v164, -v170
	s_or_b64 exec, exec, s[0:1]
	v_add_f32_e32 v164, v13, v149
	v_mul_f32_e32 v164, 0xbfb8aa3b, v164
	v_exp_f32_e32 v164, v164
	s_nop 0
	v_add_f32_e32 v164, 1.0, v164
	v_rcp_f32_e32 v164, v164
	s_nop 0
	v_mul_f32_e32 v164, 0xc1000000, v164
	v_mul_f32_e32 v170, v145, v164
	v_add_f32_e32 v192, v170, v170
	v_cmp_nlt_f32_e32 vcc, s51, v192
	s_and_saveexec_b64 s[0:1], vcc
	s_xor_b64 s[0:1], exec, s[0:1]
	v_mul_f32_e32 v164, 0x3fb8aa3b, v192
	v_exp_f32_e32 v164, v164
	s_nop 0
	v_sub_f32_e32 v195, 1.0, v164
	s_andn2_saveexec_b64 s[0:1], s[0:1]
	v_fma_f32 v164, v192, s14, 0.5
	v_fma_f32 v164, v192, v164, 1.0
	v_mul_f32_e64 v195, v164, -v192
	s_or_b64 exec, exec, s[0:1]
	v_add_f32_e32 v164, v14, v150
	v_mul_f32_e32 v164, 0xbfb8aa3b, v164
	v_exp_f32_e32 v164, v164
	s_nop 0
	v_add_f32_e32 v164, 1.0, v164
	v_rcp_f32_e32 v164, v164
	s_nop 0
	v_mul_f32_e32 v164, 0xc1000000, v164
	v_mul_f32_e32 v192, v146, v164
	v_add_f32_e32 v193, v192, v192
	v_cmp_nlt_f32_e32 vcc, s51, v193
	s_and_saveexec_b64 s[0:1], vcc
	s_xor_b64 s[0:1], exec, s[0:1]
	v_mul_f32_e32 v164, 0x3fb8aa3b, v193
	v_exp_f32_e32 v164, v164
	s_nop 0
	v_sub_f32_e32 v196, 1.0, v164
	s_andn2_saveexec_b64 s[0:1], s[0:1]
	v_fma_f32 v164, v193, s14, 0.5
	v_fma_f32 v164, v193, v164, 1.0
	v_mul_f32_e64 v196, v164, -v193
	s_or_b64 exec, exec, s[0:1]
	v_add_f32_e32 v164, v15, v151
	v_mul_f32_e32 v164, 0xbfb8aa3b, v164
	v_exp_f32_e32 v164, v164
	s_nop 0
	v_add_f32_e32 v164, 1.0, v164
	v_rcp_f32_e32 v164, v164
	s_nop 0
	v_mul_f32_e32 v164, 0xc1000000, v164
	v_mul_f32_e32 v193, v147, v164
	v_add_f32_e32 v197, v193, v193
	v_cmp_nlt_f32_e32 vcc, s51, v197
	s_and_saveexec_b64 s[0:1], vcc
	s_xor_b64 s[0:1], exec, s[0:1]
	v_mul_f32_e32 v164, 0x3fb8aa3b, v197
	v_exp_f32_e32 v164, v164
	s_nop 0
	v_sub_f32_e32 v194, 1.0, v164
	s_andn2_saveexec_b64 s[0:1], s[0:1]
	v_fma_f32 v164, v197, s14, 0.5
	v_fma_f32 v164, v197, v164, 1.0
	v_mul_f32_e64 v194, v164, -v197
	s_or_b64 exec, exec, s[0:1]
	v_add_f32_e32 v164, v10, v142
	v_mul_f32_e32 v164, 0xbfb8aa3b, v164
	v_exp_f32_e32 v164, v164
	v_max_f32_e32 v171, 0, v171
	v_add_f32_e32 v148, v4, v148
	v_add_f32_e32 v164, 1.0, v164
	v_mul_f32_e32 v148, 0xbfb8aa3b, v148
	v_exp_f32_e32 v148, v148
	v_cvt_pk_bf16_f32 v170, v168, v170
	v_max_f32_e32 v166, 0, v196
	v_rcp_f32_e32 v164, v164
	s_waitcnt vmcnt(0)
	v_lshlrev_b32_e32 v165, 16, v191
	v_sqrt_f32_e32 v166, v166
	v_add_f32_e32 v148, 1.0, v148
	v_mul_f32_e32 v164, v164, v166
	v_mul_f32_e32 v164, v164, v165
	v_add_f32_e32 v165, v11, v143
	v_mul_f32_e32 v165, 0xbfb8aa3b, v165
	v_exp_f32_e32 v165, v165
	s_nop 0
	v_add_f32_e32 v165, 1.0, v165
	s_nop 0
	v_rcp_f32_e32 v165, v165
	v_add_f32_e32 v166, v9, v141
	v_mul_f32_e32 v166, 0xbfb8aa3b, v166
	v_exp_f32_e32 v166, v166
	s_nop 0
	v_add_f32_e32 v166, 1.0, v166
	s_nop 0
	v_max_f32_e32 v169, 0, v195
	v_rcp_f32_e32 v166, v166
	v_and_b32_e32 v167, 0xffff0000, v190
	v_sqrt_f32_e32 v169, v169
	s_nop 0
	v_mul_f32_e32 v166, v166, v169
	v_add_f32_e32 v169, v8, v140
	v_mul_f32_e32 v169, 0xbfb8aa3b, v169
	v_exp_f32_e32 v169, v169
	v_mul_f32_e32 v166, v166, v167
	v_lshlrev_b32_e32 v167, 16, v190
	v_add_f32_e32 v169, 1.0, v169
	s_nop 0
	v_rcp_f32_e32 v169, v169
	s_nop 0
	v_sqrt_f32_e32 v171, v171
	s_nop 0
	v_mul_f32_e32 v169, v169, v171
	v_max_f32_e32 v171, 0, v194
	v_mul_f32_e32 v167, v169, v167
	v_and_b32_e32 v169, 0xffff0000, v191
	v_sqrt_f32_e32 v171, v171
	s_nop 0
	v_mul_f32_e32 v165, v165, v171
	v_cvt_pk_bf16_f32 v171, v192, v193
	v_mul_f32_e32 v165, v165, v169
	global_store_dwordx2 v[224:225], v[170:171], off offset:128
	v_cvt_pk_bf16_f32 v170, v167, v166
	v_cvt_pk_bf16_f32 v171, v164, v165
	global_store_dwordx2 v[226:227], v[170:171], off offset:128
	v_rcp_f32_e32 v148, v148
	s_nop 0
	v_mul_f32_e32 v148, 0xc1000000, v148
	v_mul_f32_e32 v144, v144, v148
	v_add_f32_e32 v168, v144, v144
	v_cmp_nlt_f32_e32 vcc, s51, v168
	s_and_saveexec_b64 s[0:1], vcc
	s_xor_b64 s[0:1], exec, s[0:1]
	v_mul_f32_e32 v148, 0x3fb8aa3b, v168
	v_exp_f32_e32 v148, v148
	s_nop 0
	v_sub_f32_e32 v148, 1.0, v148
	s_andn2_saveexec_b64 s[0:1], s[0:1]
	v_fma_f32 v148, v168, s14, 0.5
	v_fma_f32 v148, v168, v148, 1.0
	v_mul_f32_e64 v148, v148, -v168
	s_or_b64 exec, exec, s[0:1]
	v_add_f32_e32 v149, v5, v149
	v_mul_f32_e32 v149, 0xbfb8aa3b, v149
	v_exp_f32_e32 v149, v149
	s_nop 0
	v_add_f32_e32 v149, 1.0, v149
	v_rcp_f32_e32 v149, v149
	s_nop 0
	v_mul_f32_e32 v149, 0xc1000000, v149
	v_mul_f32_e32 v145, v145, v149
	v_add_f32_e32 v149, v145, v145
	v_cmp_nlt_f32_e32 vcc, s51, v149
	s_and_saveexec_b64 s[0:1], vcc
	s_xor_b64 s[0:1], exec, s[0:1]
	v_mul_f32_e32 v149, 0x3fb8aa3b, v149
	v_exp_f32_e32 v149, v149
	s_nop 0
	v_sub_f32_e32 v168, 1.0, v149
	s_andn2_saveexec_b64 s[0:1], s[0:1]
	v_fma_f32 v164, v149, s14, 0.5
	v_fma_f32 v164, v149, v164, 1.0
	v_mul_f32_e64 v168, v164, -v149
	s_or_b64 exec, exec, s[0:1]
	v_add_f32_e32 v149, v6, v150
	v_mul_f32_e32 v149, 0xbfb8aa3b, v149
	v_exp_f32_e32 v149, v149
	s_nop 0
	v_add_f32_e32 v149, 1.0, v149
	v_rcp_f32_e32 v149, v149
	s_nop 0
	v_mul_f32_e32 v149, 0xc1000000, v149
	v_mul_f32_e32 v146, v146, v149
	v_add_f32_e32 v149, v146, v146
	v_cmp_nlt_f32_e32 vcc, s51, v149
	s_and_saveexec_b64 s[0:1], vcc
	s_xor_b64 s[0:1], exec, s[0:1]
	v_mul_f32_e32 v149, 0x3fb8aa3b, v149
	v_exp_f32_e32 v149, v149
	s_nop 0
	v_sub_f32_e32 v150, 1.0, v149
	s_andn2_saveexec_b64 s[0:1], s[0:1]
	v_fma_f32 v150, v149, s14, 0.5
	v_fma_f32 v150, v149, v150, 1.0
	v_mul_f32_e64 v150, v150, -v149
	s_or_b64 exec, exec, s[0:1]
	v_add_f32_e32 v149, v7, v151
	v_mul_f32_e32 v149, 0xbfb8aa3b, v149
	v_exp_f32_e32 v149, v149
	s_nop 0
	v_add_f32_e32 v149, 1.0, v149
	v_rcp_f32_e32 v149, v149
	s_nop 0
	v_mul_f32_e32 v149, 0xc1000000, v149
	v_mul_f32_e32 v147, v147, v149
	v_add_f32_e32 v151, v147, v147
	v_cmp_nlt_f32_e32 vcc, s51, v151
	s_and_saveexec_b64 s[0:1], vcc
	s_xor_b64 s[0:1], exec, s[0:1]
	v_mul_f32_e32 v149, 0x3fb8aa3b, v151
	v_exp_f32_e32 v149, v149
	s_nop 0
	v_sub_f32_e32 v149, 1.0, v149
	s_andn2_saveexec_b64 s[0:1], s[0:1]
	v_fma_f32 v149, v151, s14, 0.5
	v_fma_f32 v149, v151, v149, 1.0
	v_mul_f32_e64 v149, v149, -v151
	s_or_b64 exec, exec, s[0:1]
	v_add_f32_e32 v143, v3, v143
	v_mul_f32_e32 v143, 0xbfb8aa3b, v143
	v_exp_f32_e32 v143, v143
	v_add_f32_e32 v142, v2, v142
	v_mul_f32_e32 v142, 0xbfb8aa3b, v142
	v_exp_f32_e32 v142, v142
	v_add_f32_e32 v143, 1.0, v143
	v_add_f32_e32 v142, 1.0, v142
	v_add_f32_e32 v141, v1, v141
	v_mul_f32_e32 v141, 0xbfb8aa3b, v141
	v_exp_f32_e32 v141, v141
	v_max_f32_e32 v150, 0, v150
	v_add_f32_e32 v141, 1.0, v141
	v_cmp_gt_f32_e32 vcc, s53, v150
	v_rcp_f32_e32 v142, v142
	v_add_f32_e32 v140, v0, v140
	v_cndmask_b32_e64 v164, 0, 32, vcc
	v_ldexp_f32 v150, v150, v164
	v_cndmask_b32_e64 v164, 0, -16, vcc
	v_rcp_f32_e32 v141, v141
	v_max_f32_e32 v165, 0, v168
	v_sqrt_f32_e32 v150, v150
	v_mul_f32_e32 v140, 0xbfb8aa3b, v140
	v_sqrt_f32_e32 v165, v165
	v_exp_f32_e32 v140, v140
	v_ldexp_f32 v150, v150, v164
	v_rcp_f32_e32 v143, v143
	v_lshlrev_b32_e32 v151, 16, v189
	v_mul_f32_e32 v142, v142, v150
	v_mul_f32_e32 v142, v142, v151
	v_and_b32_e32 v151, 0xffff0000, v188
	v_mul_f32_e32 v141, v141, v165
	v_add_f32_e32 v140, 1.0, v140
	v_mul_f32_e32 v151, v141, v151
	v_lshlrev_b32_e32 v150, 16, v188
	v_and_b32_e32 v164, 0xffff0000, v189
	s_mov_b64 s[0:1], 0
	v_rcp_f32_e32 v140, v140
	v_max_f32_e32 v141, 0, v148
	s_nop 1
	v_sqrt_f32_e32 v141, v141
	s_nop 0
	v_mul_f32_e32 v140, v140, v141
	v_mul_f32_e32 v148, v140, v150
	v_max_f32_e32 v140, 0, v149
	s_nop 1
	v_sqrt_f32_e32 v140, v140
	s_nop 0
	v_mul_f32_e32 v140, v143, v140
	v_mul_f32_e32 v143, v140, v164
	v_cvt_pk_bf16_f32 v140, v144, v145
	v_cvt_pk_bf16_f32 v141, v146, v147
	global_store_dwordx2 v[228:229], v[140:141], off offset:128
	v_cvt_pk_bf16_f32 v140, v148, v151
	v_cvt_pk_bf16_f32 v141, v142, v143
	global_store_dwordx2 v[230:231], v[140:141], off offset:128
.LBB0_712:
	s_and_b64 vcc, exec, s[0:1]
	s_cbranch_vccz .LBB0_447
	v_readlane_b32 s0, v253, 45
	v_readlane_b32 s1, v253, 46
	s_nop 1
	v_lshl_add_u64 v[140:141], v[180:181], 1, s[0:1]
	v_lshl_add_u64 v[142:143], v[140:141], 0, v[178:179]
	v_lshl_add_u64 v[146:147], v[140:141], 0, v[176:177]
	global_load_dwordx2 v[144:145], v[142:143], off
	s_nop 0
	global_load_dwordx2 v[142:143], v[146:147], off
	s_and_saveexec_b64 s[0:1], s[4:5]
	s_xor_b64 s[0:1], exec, s[0:1]
	v_mul_f32_e32 v146, 0x3fb8aa3b, v183
	v_exp_f32_e32 v146, v146
	s_nop 0
	v_sub_f32_e32 v146, 1.0, v146
	s_andn2_saveexec_b64 s[0:1], s[0:1]
	v_fma_f32 v146, v183, s14, 0.5
	v_fma_f32 v146, v183, v146, 1.0
	v_mul_f32_e64 v146, v146, -v183
	s_or_b64 exec, exec, s[0:1]
	v_add_f32_e32 v137, v137, v89
	v_mul_f32_e32 v137, 0xbfb8aa3b, v137
	v_exp_f32_e32 v137, v137
	s_nop 0
	v_add_f32_e32 v137, 1.0, v137
	v_rcp_f32_e32 v137, v137
	s_nop 0
	v_mul_f32_e32 v137, 0xc1000000, v137
	v_mul_f32_e32 v137, v85, v137
	v_add_f32_e32 v148, v137, v137
	v_cmp_nlt_f32_e32 vcc, s51, v148
	s_and_saveexec_b64 s[0:1], vcc
	s_xor_b64 s[0:1], exec, s[0:1]
	v_mul_f32_e32 v147, 0x3fb8aa3b, v148
	v_exp_f32_e32 v147, v147
	s_nop 0
	v_sub_f32_e32 v147, 1.0, v147
	s_andn2_saveexec_b64 s[0:1], s[0:1]
	v_fma_f32 v147, v148, s14, 0.5
	v_fma_f32 v147, v148, v147, 1.0
	v_mul_f32_e64 v147, v147, -v148
	s_or_b64 exec, exec, s[0:1]
	v_add_f32_e32 v138, v138, v90
	v_mul_f32_e32 v138, 0xbfb8aa3b, v138
	v_exp_f32_e32 v138, v138
	s_nop 0
	v_add_f32_e32 v138, 1.0, v138
	v_rcp_f32_e32 v138, v138
	s_nop 0
	v_mul_f32_e32 v138, 0xc1000000, v138
	v_mul_f32_e32 v138, v86, v138
	v_add_f32_e32 v148, v138, v138
	v_cmp_nlt_f32_e32 vcc, s51, v148
	s_and_saveexec_b64 s[0:1], vcc
	s_xor_b64 s[0:1], exec, s[0:1]
	v_mul_f32_e32 v148, 0x3fb8aa3b, v148
	v_exp_f32_e32 v148, v148
	s_nop 0
	v_sub_f32_e32 v149, 1.0, v148
	s_andn2_saveexec_b64 s[0:1], s[0:1]
	v_fma_f32 v149, v148, s14, 0.5
	v_fma_f32 v149, v148, v149, 1.0
	v_mul_f32_e64 v149, v149, -v148
	s_or_b64 exec, exec, s[0:1]
	v_add_f32_e32 v139, v139, v91
	v_mul_f32_e32 v139, 0xbfb8aa3b, v139
	v_exp_f32_e32 v139, v139
	s_nop 0
	v_add_f32_e32 v139, 1.0, v139
	v_rcp_f32_e32 v139, v139
	s_nop 0
	v_mul_f32_e32 v139, 0xc1000000, v139
	v_mul_f32_e32 v139, v87, v139
	v_add_f32_e32 v150, v139, v139
	v_cmp_nlt_f32_e32 vcc, s51, v150
	s_and_saveexec_b64 s[0:1], vcc
	s_xor_b64 s[0:1], exec, s[0:1]
	v_mul_f32_e32 v148, 0x3fb8aa3b, v150
	v_exp_f32_e32 v148, v148
	s_nop 0
	v_sub_f32_e32 v148, 1.0, v148
	s_andn2_saveexec_b64 s[0:1], s[0:1]
	v_fma_f32 v148, v150, s14, 0.5
	v_fma_f32 v148, v150, v148, 1.0
	v_mul_f32_e64 v148, v148, -v150
	s_or_b64 exec, exec, s[0:1]
	v_add_f32_e32 v134, v134, v78
	v_mul_f32_e32 v134, 0xbfb8aa3b, v134
	v_exp_f32_e32 v134, v134
	v_max_f32_e32 v149, 0, v149
	v_add_f32_e32 v133, v133, v77
	v_add_f32_e32 v134, 1.0, v134
	v_mul_f32_e32 v133, 0xbfb8aa3b, v133
	v_exp_f32_e32 v133, v133
	v_rcp_f32_e32 v134, v134
	s_waitcnt vmcnt(0)
	v_lshlrev_b32_e32 v150, 16, v145
	v_sqrt_f32_e32 v149, v149
	v_add_f32_e32 v133, 1.0, v133
	v_max_f32_e32 v147, 0, v147
	v_mul_f32_e32 v134, v134, v149
	v_mul_f32_e32 v149, v134, v150
	v_add_f32_e32 v134, v135, v79
	v_mul_f32_e32 v134, 0xbfb8aa3b, v134
	v_exp_f32_e32 v134, v134
	v_add_f32_e32 v128, v128, v88
	v_mul_f32_e32 v128, 0xbfb8aa3b, v128
	v_exp_f32_e32 v128, v128
	v_add_f32_e32 v134, 1.0, v134
	v_add_f32_e32 v128, 1.0, v128
	v_rcp_f32_e32 v134, v134
	s_lshl_b32 s0, s7, 21
	v_readlane_b32 s1, v251, 24
	s_add_u32 s4, s1, s0
	v_rcp_f32_e32 v133, v133
	v_and_b32_e32 v135, 0xffff0000, v144
	v_sqrt_f32_e32 v147, v147
	v_readlane_b32 s1, v251, 25
	s_addc_u32 s5, s1, 0
	v_mul_f32_e32 v133, v133, v147
	v_mul_f32_e32 v147, v133, v135
	v_max_f32_e32 v135, 0, v146
	v_lshlrev_b32_e32 v133, 16, v144
	v_readlane_b32 s1, v251, 26
	v_sqrt_f32_e32 v135, v135
	s_add_u32 s0, s1, s0
	v_readlane_b32 s1, v251, 27
	v_mul_f32_e32 v135, v136, v135
	v_mul_f32_e32 v144, v135, v133
	v_max_f32_e32 v135, 0, v148
	v_and_b32_e32 v133, 0xffff0000, v145
	s_addc_u32 s1, s1, 0
	v_sqrt_f32_e32 v135, v135
	s_nop 0
	v_mul_f32_e32 v134, v134, v135
	v_mul_f32_e32 v145, v134, v133
	v_lshl_add_u64 v[134:135], v[186:187], 0, v[180:181]
	v_lshlrev_b64 v[134:135], 1, v[134:135]
	v_cvt_pk_bf16_f32 v136, v132, v137
	v_lshl_add_u64 v[132:133], s[4:5], 0, v[134:135]
	v_cvt_pk_bf16_f32 v137, v138, v139
	global_store_dwordx2 v[132:133], v[136:137], off
	v_cvt_pk_bf16_f32 v136, v144, v147
	v_lshl_add_u64 v[134:135], s[0:1], 0, v[134:135]
	v_cvt_pk_bf16_f32 v137, v149, v145
	global_store_dwordx2 v[134:135], v[136:137], off
	s_nop 0
	v_rcp_f32_e32 v128, v128
	s_nop 0
	v_mul_f32_e32 v128, 0xc1000000, v128
	v_mul_f32_e32 v128, v84, v128
	v_add_f32_e32 v137, v128, v128
	v_cmp_nlt_f32_e32 vcc, s51, v137
	s_and_saveexec_b64 s[8:9], vcc
	s_xor_b64 s[8:9], exec, s[8:9]
	v_mul_f32_e32 v136, 0x3fb8aa3b, v137
	v_exp_f32_e32 v136, v136
	s_nop 0
	v_sub_f32_e32 v136, 1.0, v136
	s_andn2_saveexec_b64 s[8:9], s[8:9]
	v_fma_f32 v136, v137, s14, 0.5
	v_fma_f32 v136, v137, v136, 1.0
	v_mul_f32_e64 v136, v136, -v137
	s_or_b64 exec, exec, s[8:9]
	v_add_f32_e32 v129, v129, v89
	v_mul_f32_e32 v129, 0xbfb8aa3b, v129
	v_exp_f32_e32 v129, v129
	s_nop 0
	v_add_f32_e32 v129, 1.0, v129
	v_rcp_f32_e32 v129, v129
	s_nop 0
	v_mul_f32_e32 v129, 0xc1000000, v129
	v_mul_f32_e32 v129, v85, v129
	v_add_f32_e32 v137, v129, v129
	v_cmp_nlt_f32_e32 vcc, s51, v137
	s_and_saveexec_b64 s[8:9], vcc
	s_xor_b64 s[8:9], exec, s[8:9]
	v_mul_f32_e32 v137, 0x3fb8aa3b, v137
	v_exp_f32_e32 v137, v137
	s_nop 0
	v_sub_f32_e32 v138, 1.0, v137
	s_andn2_saveexec_b64 s[8:9], s[8:9]
	v_fma_f32 v138, v137, s14, 0.5
	v_fma_f32 v138, v137, v138, 1.0
	v_mul_f32_e64 v138, v138, -v137
	s_or_b64 exec, exec, s[8:9]
	v_add_f32_e32 v130, v130, v90
	v_mul_f32_e32 v130, 0xbfb8aa3b, v130
	v_exp_f32_e32 v130, v130
	s_nop 0
	v_add_f32_e32 v130, 1.0, v130
	v_rcp_f32_e32 v130, v130
	s_nop 0
	v_mul_f32_e32 v130, 0xc1000000, v130
	v_mul_f32_e32 v130, v86, v130
	v_add_f32_e32 v137, v130, v130
	v_cmp_nlt_f32_e32 vcc, s51, v137
	s_and_saveexec_b64 s[8:9], vcc
	s_xor_b64 s[8:9], exec, s[8:9]
	v_mul_f32_e32 v137, 0x3fb8aa3b, v137
	v_exp_f32_e32 v137, v137
	s_nop 0
	v_sub_f32_e32 v139, 1.0, v137
	s_andn2_saveexec_b64 s[8:9], s[8:9]
	v_fma_f32 v139, v137, s14, 0.5
	v_fma_f32 v139, v137, v139, 1.0
	v_mul_f32_e64 v139, v139, -v137
	s_or_b64 exec, exec, s[8:9]
	v_add_f32_e32 v131, v131, v91
	v_mul_f32_e32 v131, 0xbfb8aa3b, v131
	v_exp_f32_e32 v131, v131
	s_nop 0
	v_add_f32_e32 v131, 1.0, v131
	v_rcp_f32_e32 v131, v131
	s_nop 0
	v_mul_f32_e32 v131, 0xc1000000, v131
	v_mul_f32_e32 v131, v87, v131
	v_add_f32_e32 v144, v131, v131
	v_cmp_nlt_f32_e32 vcc, s51, v144
	s_and_saveexec_b64 s[8:9], vcc
	s_xor_b64 s[8:9], exec, s[8:9]
	v_mul_f32_e32 v137, 0x3fb8aa3b, v144
	v_exp_f32_e32 v137, v137
	s_nop 0
	v_sub_f32_e32 v137, 1.0, v137
	s_andn2_saveexec_b64 s[8:9], s[8:9]
	v_fma_f32 v137, v144, s14, 0.5
	v_fma_f32 v137, v144, v137, 1.0
	v_mul_f32_e64 v137, v137, -v144
	s_or_b64 exec, exec, s[8:9]
	v_add_f32_e32 v126, v126, v78
	v_mul_f32_e32 v126, 0xbfb8aa3b, v126
	v_exp_f32_e32 v126, v126
	v_max_f32_e32 v139, 0, v139
	v_add_f32_e32 v125, v125, v77
	v_add_f32_e32 v126, 1.0, v126
	v_mul_f32_e32 v125, 0xbfb8aa3b, v125
	v_exp_f32_e32 v125, v125
	v_rcp_f32_e32 v126, v126
	v_lshlrev_b32_e32 v144, 16, v143
	v_sqrt_f32_e32 v139, v139
	v_add_f32_e32 v125, 1.0, v125
	v_max_f32_e32 v138, 0, v138
	v_mul_f32_e32 v126, v126, v139
	v_mul_f32_e32 v139, v126, v144
	v_add_f32_e32 v126, v127, v79
	v_mul_f32_e32 v126, 0xbfb8aa3b, v126
	v_exp_f32_e32 v126, v126
	v_add_f32_e32 v124, v124, v76
	v_mul_f32_e32 v124, 0xbfb8aa3b, v124
	v_exp_f32_e32 v124, v124
	v_add_f32_e32 v126, 1.0, v126
	v_add_f32_e32 v124, 1.0, v124
	v_max_f32_e32 v137, 0, v137
	v_rcp_f32_e32 v126, v126
	v_add_f32_e32 v120, v120, v88
	v_mul_f32_e32 v120, 0xbfb8aa3b, v120
	v_exp_f32_e32 v120, v120
	v_rcp_f32_e32 v125, v125
	v_and_b32_e32 v127, 0xffff0000, v142
	v_sqrt_f32_e32 v138, v138
	v_add_f32_e32 v120, 1.0, v120
	v_mul_f32_e32 v125, v125, v138
	v_mul_f32_e32 v138, v125, v127
	v_lshlrev_b32_e32 v125, 16, v142
	s_nop 0
	v_rcp_f32_e32 v124, v124
	v_max_f32_e32 v127, 0, v136
	v_cmp_gt_f32_e32 vcc, s53, v127
	s_nop 0
	s_nop 0
	v_cndmask_b32_e64 v136, 0, 32, vcc
	v_ldexp_f32 v127, v127, v136
	v_cndmask_b32_e64 v136, 0, -16, vcc
	v_sqrt_f32_e32 v127, v127
	s_nop 0
	v_sqrt_f32_e32 v137, v137
	v_ldexp_f32 v127, v127, v136
	v_mul_f32_e32 v124, v124, v127
	v_mul_f32_e32 v136, v124, v125
	v_lshlrev_b64 v[124:125], 10, v[184:185]
	v_and_b32_e32 v127, 0xffff0000, v143
	v_mul_f32_e32 v126, v126, v137
	v_lshl_add_u64 v[124:125], v[124:125], 0, v[180:181]
	v_mul_f32_e32 v137, v126, v127
	v_cvt_pk_bf16_f32 v126, v128, v129
	v_lshlrev_b64 v[128:129], 1, v[124:125]
	v_or_b32_e32 v142, 32, v182
	v_cvt_pk_bf16_f32 v127, v130, v131
	v_lshl_add_u64 v[124:125], s[4:5], 0, v[128:129]
	v_ashrrev_i32_e32 v143, 31, v142
	global_store_dwordx2 v[124:125], v[126:127], off
	v_cvt_pk_bf16_f32 v130, v136, v138
	v_cvt_pk_bf16_f32 v131, v139, v137
	v_lshl_add_u64 v[126:127], s[0:1], 0, v[128:129]
	v_lshlrev_b64 v[128:129], 11, v[142:143]
	v_or_b32_e32 v136, 48, v182
	global_store_dwordx2 v[126:127], v[130:131], off
	v_lshl_add_u64 v[130:131], v[140:141], 0, v[128:129]
	v_ashrrev_i32_e32 v137, 31, v136
	global_load_dwordx2 v[144:145], v[130:131], off
	v_lshlrev_b64 v[130:131], 11, v[136:137]
	v_lshl_add_u64 v[138:139], v[140:141], 0, v[130:131]
	global_load_dwordx2 v[138:139], v[138:139], off
	v_rcp_f32_e32 v120, v120
	s_nop 0
	v_mul_f32_e32 v120, 0xc1000000, v120
	v_mul_f32_e32 v120, v84, v120
	v_add_f32_e32 v147, v120, v120
	v_cmp_nlt_f32_e32 vcc, s51, v147
	s_and_saveexec_b64 s[8:9], vcc
	s_xor_b64 s[8:9], exec, s[8:9]
	v_mul_f32_e32 v146, 0x3fb8aa3b, v147
	v_exp_f32_e32 v146, v146
	s_nop 0
	v_sub_f32_e32 v146, 1.0, v146
	s_andn2_saveexec_b64 s[8:9], s[8:9]
	v_fma_f32 v146, v147, s14, 0.5
	v_fma_f32 v146, v147, v146, 1.0
	v_mul_f32_e64 v146, v146, -v147
	s_or_b64 exec, exec, s[8:9]
	v_add_f32_e32 v121, v121, v89
	v_mul_f32_e32 v121, 0xbfb8aa3b, v121
	v_exp_f32_e32 v121, v121
	s_nop 0
	v_add_f32_e32 v121, 1.0, v121
	v_rcp_f32_e32 v121, v121
	s_nop 0
	v_mul_f32_e32 v121, 0xc1000000, v121
	v_mul_f32_e32 v121, v85, v121
	v_add_f32_e32 v147, v121, v121
	v_cmp_nlt_f32_e32 vcc, s51, v147
	s_and_saveexec_b64 s[8:9], vcc
	s_xor_b64 s[8:9], exec, s[8:9]
	v_mul_f32_e32 v147, 0x3fb8aa3b, v147
	v_exp_f32_e32 v147, v147
	s_nop 0
	v_sub_f32_e32 v148, 1.0, v147
	s_andn2_saveexec_b64 s[8:9], s[8:9]
	v_fma_f32 v148, v147, s14, 0.5
	v_fma_f32 v148, v147, v148, 1.0
	v_mul_f32_e64 v148, v148, -v147
	s_or_b64 exec, exec, s[8:9]
	v_add_f32_e32 v122, v122, v90
	v_mul_f32_e32 v122, 0xbfb8aa3b, v122
	v_exp_f32_e32 v122, v122
	s_nop 0
	v_add_f32_e32 v122, 1.0, v122
	v_rcp_f32_e32 v122, v122
	s_nop 0
	v_mul_f32_e32 v122, 0xc1000000, v122
	v_mul_f32_e32 v122, v86, v122
	v_add_f32_e32 v147, v122, v122
	v_cmp_nlt_f32_e32 vcc, s51, v147
	s_and_saveexec_b64 s[8:9], vcc
	s_xor_b64 s[8:9], exec, s[8:9]
	v_mul_f32_e32 v147, 0x3fb8aa3b, v147
	v_exp_f32_e32 v147, v147
	s_nop 0
	v_sub_f32_e32 v149, 1.0, v147
	s_andn2_saveexec_b64 s[8:9], s[8:9]
	v_fma_f32 v149, v147, s14, 0.5
	v_fma_f32 v149, v147, v149, 1.0
	v_mul_f32_e64 v149, v149, -v147
	s_or_b64 exec, exec, s[8:9]
	v_add_f32_e32 v123, v123, v91
	v_mul_f32_e32 v123, 0xbfb8aa3b, v123
	v_exp_f32_e32 v123, v123
	s_nop 0
	v_add_f32_e32 v123, 1.0, v123
	v_rcp_f32_e32 v123, v123
	s_nop 0
	v_mul_f32_e32 v123, 0xc1000000, v123
	v_mul_f32_e32 v123, v87, v123
	v_add_f32_e32 v150, v123, v123
	v_cmp_nlt_f32_e32 vcc, s51, v150
	s_and_saveexec_b64 s[8:9], vcc
	s_xor_b64 s[8:9], exec, s[8:9]
	v_mul_f32_e32 v147, 0x3fb8aa3b, v150
	v_exp_f32_e32 v147, v147
	s_nop 0
	v_sub_f32_e32 v147, 1.0, v147
	s_andn2_saveexec_b64 s[8:9], s[8:9]
	v_fma_f32 v147, v150, s14, 0.5
	v_fma_f32 v147, v150, v147, 1.0
	v_mul_f32_e64 v147, v147, -v150
	s_or_b64 exec, exec, s[8:9]
	v_add_f32_e32 v118, v118, v78
	v_mul_f32_e32 v118, 0xbfb8aa3b, v118
	v_exp_f32_e32 v118, v118
	v_max_f32_e32 v149, 0, v149
	v_add_f32_e32 v117, v117, v77
	v_add_f32_e32 v118, 1.0, v118
	v_mul_f32_e32 v117, 0xbfb8aa3b, v117
	v_exp_f32_e32 v117, v117
	v_rcp_f32_e32 v118, v118
	s_waitcnt vmcnt(0)
	v_lshlrev_b32_e32 v150, 16, v145
	v_sqrt_f32_e32 v149, v149
	v_add_f32_e32 v117, 1.0, v117
	v_max_f32_e32 v148, 0, v148
	v_mul_f32_e32 v118, v118, v149
	v_mul_f32_e32 v149, v118, v150
	v_add_f32_e32 v118, v119, v79
	v_mul_f32_e32 v118, 0xbfb8aa3b, v118
	v_exp_f32_e32 v118, v118
	v_add_f32_e32 v116, v116, v76
	v_mul_f32_e32 v116, 0xbfb8aa3b, v116
	v_exp_f32_e32 v116, v116
	v_add_f32_e32 v118, 1.0, v118
	v_add_f32_e32 v116, 1.0, v116
	v_add_f32_e32 v112, v112, v88
	v_mul_f32_e32 v112, 0xbfb8aa3b, v112
	v_rcp_f32_e32 v118, v118
	v_exp_f32_e32 v112, v112
	v_rcp_f32_e32 v117, v117
	v_and_b32_e32 v119, 0xffff0000, v144
	v_sqrt_f32_e32 v148, v148
	v_add_f32_e32 v112, 1.0, v112
	v_mul_f32_e32 v117, v117, v148
	v_mul_f32_e32 v148, v117, v119
	v_lshlrev_b32_e32 v117, 16, v144
	s_nop 0
	v_rcp_f32_e32 v116, v116
	v_max_f32_e32 v119, 0, v146
	s_nop 1
	v_sqrt_f32_e32 v119, v119
	s_nop 0
	v_mul_f32_e32 v116, v116, v119
	v_mul_f32_e32 v144, v116, v117
	v_lshlrev_b64 v[116:117], 10, v[142:143]
	v_max_f32_e32 v142, 0, v147
	v_and_b32_e32 v119, 0xffff0000, v145
	v_lshl_add_u64 v[116:117], v[116:117], 0, v[180:181]
	v_sqrt_f32_e32 v142, v142
	s_nop 0
	v_mul_f32_e32 v118, v118, v142
	v_mul_f32_e32 v142, v118, v119
	v_cvt_pk_bf16_f32 v118, v120, v121
	v_lshlrev_b64 v[120:121], 1, v[116:117]
	v_cvt_pk_bf16_f32 v119, v122, v123
	v_lshl_add_u64 v[116:117], s[4:5], 0, v[120:121]
	global_store_dwordx2 v[116:117], v[118:119], off
	v_lshl_add_u64 v[118:119], s[0:1], 0, v[120:121]
	v_cvt_pk_bf16_f32 v122, v144, v148
	v_cvt_pk_bf16_f32 v123, v149, v142
	global_store_dwordx2 v[118:119], v[122:123], off
	v_rcp_f32_e32 v112, v112
	s_nop 0
	v_mul_f32_e32 v112, 0xc1000000, v112
	v_mul_f32_e32 v112, v84, v112
	v_add_f32_e32 v121, v112, v112
	v_cmp_nlt_f32_e32 vcc, s51, v121
	s_and_saveexec_b64 s[8:9], vcc
	s_xor_b64 s[8:9], exec, s[8:9]
	v_mul_f32_e32 v120, 0x3fb8aa3b, v121
	v_exp_f32_e32 v120, v120
	s_nop 0
	v_sub_f32_e32 v120, 1.0, v120
	s_andn2_saveexec_b64 s[8:9], s[8:9]
	v_fma_f32 v120, v121, s14, 0.5
	v_fma_f32 v120, v121, v120, 1.0
	v_mul_f32_e64 v120, v120, -v121
	s_or_b64 exec, exec, s[8:9]
	v_add_f32_e32 v113, v113, v89
	v_mul_f32_e32 v113, 0xbfb8aa3b, v113
	v_exp_f32_e32 v113, v113
	s_nop 0
	v_add_f32_e32 v113, 1.0, v113
	v_rcp_f32_e32 v113, v113
	s_nop 0
	v_mul_f32_e32 v113, 0xc1000000, v113
	v_mul_f32_e32 v113, v85, v113
	v_add_f32_e32 v121, v113, v113
	v_cmp_nlt_f32_e32 vcc, s51, v121
	s_and_saveexec_b64 s[8:9], vcc
	s_xor_b64 s[8:9], exec, s[8:9]
	v_mul_f32_e32 v121, 0x3fb8aa3b, v121
	v_exp_f32_e32 v121, v121
	s_nop 0
	v_sub_f32_e32 v122, 1.0, v121
	s_andn2_saveexec_b64 s[8:9], s[8:9]
	v_fma_f32 v122, v121, s14, 0.5
	v_fma_f32 v122, v121, v122, 1.0
	v_mul_f32_e64 v122, v122, -v121
	s_or_b64 exec, exec, s[8:9]
	v_add_f32_e32 v114, v114, v90
	v_mul_f32_e32 v114, 0xbfb8aa3b, v114
	v_exp_f32_e32 v114, v114
	s_nop 0
	v_add_f32_e32 v114, 1.0, v114
	v_rcp_f32_e32 v114, v114
	s_nop 0
	v_mul_f32_e32 v114, 0xc1000000, v114
	v_mul_f32_e32 v114, v86, v114
	v_add_f32_e32 v121, v114, v114
	v_cmp_nlt_f32_e32 vcc, s51, v121
	s_and_saveexec_b64 s[8:9], vcc
	s_xor_b64 s[8:9], exec, s[8:9]
	v_mul_f32_e32 v121, 0x3fb8aa3b, v121
	v_exp_f32_e32 v121, v121
	s_nop 0
	v_sub_f32_e32 v123, 1.0, v121
	s_andn2_saveexec_b64 s[8:9], s[8:9]
	v_fma_f32 v123, v121, s14, 0.5
	v_fma_f32 v123, v121, v123, 1.0
	v_mul_f32_e64 v123, v123, -v121
	s_or_b64 exec, exec, s[8:9]
	v_add_f32_e32 v115, v115, v91
	v_mul_f32_e32 v115, 0xbfb8aa3b, v115
	v_exp_f32_e32 v115, v115
	s_nop 0
	v_add_f32_e32 v115, 1.0, v115
	v_rcp_f32_e32 v115, v115
	s_nop 0
	v_mul_f32_e32 v115, 0xc1000000, v115
	v_mul_f32_e32 v115, v87, v115
	v_add_f32_e32 v142, v115, v115
	v_cmp_nlt_f32_e32 vcc, s51, v142
	s_and_saveexec_b64 s[8:9], vcc
	s_xor_b64 s[8:9], exec, s[8:9]
	v_mul_f32_e32 v121, 0x3fb8aa3b, v142
	v_exp_f32_e32 v121, v121
	s_nop 0
	v_sub_f32_e32 v121, 1.0, v121
	s_andn2_saveexec_b64 s[8:9], s[8:9]
	v_fma_f32 v121, v142, s14, 0.5
	v_fma_f32 v121, v142, v121, 1.0
	v_mul_f32_e64 v121, v121, -v142
	s_or_b64 exec, exec, s[8:9]
	v_add_f32_e32 v110, v110, v78
	v_mul_f32_e32 v110, 0xbfb8aa3b, v110
	v_exp_f32_e32 v110, v110
	v_max_f32_e32 v123, 0, v123
	v_add_f32_e32 v109, v109, v77
	v_add_f32_e32 v110, 1.0, v110
	v_mul_f32_e32 v109, 0xbfb8aa3b, v109
	v_exp_f32_e32 v109, v109
	v_rcp_f32_e32 v110, v110
	v_lshlrev_b32_e32 v142, 16, v139
	v_sqrt_f32_e32 v123, v123
	v_add_f32_e32 v109, 1.0, v109
	v_max_f32_e32 v122, 0, v122
	v_mul_f32_e32 v110, v110, v123
	v_mul_f32_e32 v123, v110, v142
	v_add_f32_e32 v110, v111, v79
	v_mul_f32_e32 v110, 0xbfb8aa3b, v110
	v_exp_f32_e32 v110, v110
	v_add_f32_e32 v108, v108, v76
	v_mul_f32_e32 v108, 0xbfb8aa3b, v108
	v_exp_f32_e32 v108, v108
	v_add_f32_e32 v110, 1.0, v110
	v_add_f32_e32 v108, 1.0, v108
	v_max_f32_e32 v121, 0, v121
	v_rcp_f32_e32 v110, v110
	v_add_f32_e32 v104, v104, v88
	v_mul_f32_e32 v104, 0xbfb8aa3b, v104
	v_exp_f32_e32 v104, v104
	v_rcp_f32_e32 v109, v109
	v_and_b32_e32 v111, 0xffff0000, v138
	v_sqrt_f32_e32 v122, v122
	v_add_f32_e32 v104, 1.0, v104
	v_mul_f32_e32 v109, v109, v122
	v_mul_f32_e32 v122, v109, v111
	v_lshlrev_b32_e32 v109, 16, v138
	s_nop 0
	v_rcp_f32_e32 v108, v108
	v_max_f32_e32 v111, 0, v120
	s_nop 0
	s_nop 0
	v_sqrt_f32_e32 v111, v111
	s_nop 0
	v_mul_f32_e32 v108, v108, v111
	v_mul_f32_e32 v120, v108, v109
	v_lshlrev_b64 v[108:109], 10, v[136:137]
	v_sqrt_f32_e32 v121, v121
	v_and_b32_e32 v111, 0xffff0000, v139
	v_lshl_add_u64 v[108:109], v[108:109], 0, v[180:181]
	v_mul_f32_e32 v110, v110, v121
	v_mul_f32_e32 v121, v110, v111
	v_cvt_pk_bf16_f32 v110, v112, v113
	v_lshlrev_b64 v[112:113], 1, v[108:109]
	v_add_u32_e32 v136, 0x80, v182
	v_cvt_pk_bf16_f32 v111, v114, v115
	v_lshl_add_u64 v[108:109], s[4:5], 0, v[112:113]
	v_ashrrev_i32_e32 v137, 31, v136
	global_store_dwordx2 v[108:109], v[110:111], off
	v_cvt_pk_bf16_f32 v114, v120, v122
	v_cvt_pk_bf16_f32 v115, v123, v121
	v_lshl_add_u64 v[110:111], s[0:1], 0, v[112:113]
	v_lshlrev_b64 v[112:113], 11, v[136:137]
	v_add_u32_e32 v120, 0x90, v182
	global_store_dwordx2 v[110:111], v[114:115], off
	v_lshl_add_u64 v[114:115], v[140:141], 0, v[112:113]
	v_ashrrev_i32_e32 v121, 31, v120
	global_load_dwordx2 v[138:139], v[114:115], off
	v_lshlrev_b64 v[114:115], 11, v[120:121]
	v_lshl_add_u64 v[122:123], v[140:141], 0, v[114:115]
	global_load_dwordx2 v[122:123], v[122:123], off
	v_rcp_f32_e32 v104, v104
	s_nop 0
	v_mul_f32_e32 v104, 0xc1000000, v104
	v_mul_f32_e32 v104, v84, v104
	v_add_f32_e32 v143, v104, v104
	v_cmp_nlt_f32_e32 vcc, s51, v143
	s_and_saveexec_b64 s[8:9], vcc
	s_xor_b64 s[8:9], exec, s[8:9]
	v_mul_f32_e32 v142, 0x3fb8aa3b, v143
	v_exp_f32_e32 v142, v142
	s_nop 0
	v_sub_f32_e32 v142, 1.0, v142
	s_andn2_saveexec_b64 s[8:9], s[8:9]
	v_fma_f32 v142, v143, s14, 0.5
	v_fma_f32 v142, v143, v142, 1.0
	v_mul_f32_e64 v142, v142, -v143
	s_or_b64 exec, exec, s[8:9]
	v_add_f32_e32 v105, v105, v89
	v_mul_f32_e32 v105, 0xbfb8aa3b, v105
	v_exp_f32_e32 v105, v105
	s_nop 0
	v_add_f32_e32 v105, 1.0, v105
	v_rcp_f32_e32 v105, v105
	s_nop 0
	v_mul_f32_e32 v105, 0xc1000000, v105
	v_mul_f32_e32 v105, v85, v105
	v_add_f32_e32 v143, v105, v105
	v_cmp_nlt_f32_e32 vcc, s51, v143
	s_and_saveexec_b64 s[8:9], vcc
	s_xor_b64 s[8:9], exec, s[8:9]
	v_mul_f32_e32 v143, 0x3fb8aa3b, v143
	v_exp_f32_e32 v143, v143
	s_nop 0
	v_sub_f32_e32 v144, 1.0, v143
	s_andn2_saveexec_b64 s[8:9], s[8:9]
	v_fma_f32 v144, v143, s14, 0.5
	v_fma_f32 v144, v143, v144, 1.0
	v_mul_f32_e64 v144, v144, -v143
	s_or_b64 exec, exec, s[8:9]
	v_add_f32_e32 v106, v106, v90
	v_mul_f32_e32 v106, 0xbfb8aa3b, v106
	v_exp_f32_e32 v106, v106
	s_nop 0
	v_add_f32_e32 v106, 1.0, v106
	v_rcp_f32_e32 v106, v106
	s_nop 0
	v_mul_f32_e32 v106, 0xc1000000, v106
	v_mul_f32_e32 v106, v86, v106
	v_add_f32_e32 v143, v106, v106
	v_cmp_nlt_f32_e32 vcc, s51, v143
	s_and_saveexec_b64 s[8:9], vcc
	s_xor_b64 s[8:9], exec, s[8:9]
	v_mul_f32_e32 v143, 0x3fb8aa3b, v143
	v_exp_f32_e32 v143, v143
	s_nop 0
	v_sub_f32_e32 v145, 1.0, v143
	s_andn2_saveexec_b64 s[8:9], s[8:9]
	v_fma_f32 v145, v143, s14, 0.5
	v_fma_f32 v145, v143, v145, 1.0
	v_mul_f32_e64 v145, v145, -v143
	s_or_b64 exec, exec, s[8:9]
	v_add_f32_e32 v107, v107, v91
	v_mul_f32_e32 v107, 0xbfb8aa3b, v107
	v_exp_f32_e32 v107, v107
	s_nop 0
	v_add_f32_e32 v107, 1.0, v107
	v_rcp_f32_e32 v107, v107
	s_nop 0
	v_mul_f32_e32 v107, 0xc1000000, v107
	v_mul_f32_e32 v107, v87, v107
	v_add_f32_e32 v146, v107, v107
	v_cmp_nlt_f32_e32 vcc, s51, v146
	s_and_saveexec_b64 s[8:9], vcc
	s_xor_b64 s[8:9], exec, s[8:9]
	v_mul_f32_e32 v143, 0x3fb8aa3b, v146
	v_exp_f32_e32 v143, v143
	s_nop 0
	v_sub_f32_e32 v143, 1.0, v143
	s_andn2_saveexec_b64 s[8:9], s[8:9]
	v_fma_f32 v143, v146, s14, 0.5
	v_fma_f32 v143, v146, v143, 1.0
	v_mul_f32_e64 v143, v143, -v146
	s_or_b64 exec, exec, s[8:9]
	v_add_f32_e32 v102, v102, v78
	v_mul_f32_e32 v102, 0xbfb8aa3b, v102
	v_exp_f32_e32 v102, v102
	v_max_f32_e32 v145, 0, v145
	v_add_f32_e32 v101, v101, v77
	v_add_f32_e32 v102, 1.0, v102
	v_mul_f32_e32 v101, 0xbfb8aa3b, v101
	v_exp_f32_e32 v101, v101
	v_rcp_f32_e32 v102, v102
	s_waitcnt vmcnt(0)
	v_lshlrev_b32_e32 v146, 16, v139
	v_sqrt_f32_e32 v145, v145
	v_add_f32_e32 v101, 1.0, v101
	v_max_f32_e32 v144, 0, v144
	v_mul_f32_e32 v102, v102, v145
	v_mul_f32_e32 v145, v102, v146
	v_add_f32_e32 v102, v103, v79
	v_mul_f32_e32 v102, 0xbfb8aa3b, v102
	v_exp_f32_e32 v102, v102
	v_add_f32_e32 v100, v100, v76
	v_mul_f32_e32 v100, 0xbfb8aa3b, v100
	v_exp_f32_e32 v100, v100
	v_add_f32_e32 v102, 1.0, v102
	v_add_f32_e32 v100, 1.0, v100
	v_add_f32_e32 v96, v96, v88
	v_mul_f32_e32 v96, 0xbfb8aa3b, v96
	v_rcp_f32_e32 v102, v102
	v_exp_f32_e32 v96, v96
	v_rcp_f32_e32 v101, v101
	v_and_b32_e32 v103, 0xffff0000, v138
	v_sqrt_f32_e32 v144, v144
	v_add_f32_e32 v96, 1.0, v96
	v_mul_f32_e32 v101, v101, v144
	v_mul_f32_e32 v144, v101, v103
	v_lshlrev_b32_e32 v101, 16, v138
	s_nop 0
	v_rcp_f32_e32 v100, v100
	v_max_f32_e32 v103, 0, v142
	s_nop 1
	v_sqrt_f32_e32 v103, v103
	s_nop 0
	v_mul_f32_e32 v100, v100, v103
	v_mul_f32_e32 v138, v100, v101
	v_lshlrev_b64 v[100:101], 10, v[136:137]
	v_max_f32_e32 v136, 0, v143
	v_and_b32_e32 v103, 0xffff0000, v139
	v_lshl_add_u64 v[100:101], v[100:101], 0, v[180:181]
	v_sqrt_f32_e32 v136, v136
	s_nop 0
	v_mul_f32_e32 v102, v102, v136
	v_mul_f32_e32 v136, v102, v103
	v_cvt_pk_bf16_f32 v102, v104, v105
	v_lshlrev_b64 v[104:105], 1, v[100:101]
	v_cvt_pk_bf16_f32 v103, v106, v107
	v_lshl_add_u64 v[100:101], s[4:5], 0, v[104:105]
	global_store_dwordx2 v[100:101], v[102:103], off
	v_lshl_add_u64 v[102:103], s[0:1], 0, v[104:105]
	v_cvt_pk_bf16_f32 v106, v138, v144
	v_cvt_pk_bf16_f32 v107, v145, v136
	global_store_dwordx2 v[102:103], v[106:107], off
	v_rcp_f32_e32 v96, v96
	s_nop 0
	v_mul_f32_e32 v96, 0xc1000000, v96
	v_mul_f32_e32 v96, v84, v96
	v_add_f32_e32 v105, v96, v96
	v_cmp_nlt_f32_e32 vcc, s51, v105
	s_and_saveexec_b64 s[8:9], vcc
	s_xor_b64 s[8:9], exec, s[8:9]
	v_mul_f32_e32 v104, 0x3fb8aa3b, v105
	v_exp_f32_e32 v104, v104
	s_nop 0
	v_sub_f32_e32 v104, 1.0, v104
	s_andn2_saveexec_b64 s[8:9], s[8:9]
	v_fma_f32 v104, v105, s14, 0.5
	v_fma_f32 v104, v105, v104, 1.0
	v_mul_f32_e64 v104, v104, -v105
	s_or_b64 exec, exec, s[8:9]
	v_add_f32_e32 v97, v97, v89
	v_mul_f32_e32 v97, 0xbfb8aa3b, v97
	v_exp_f32_e32 v97, v97
	s_nop 0
	v_add_f32_e32 v97, 1.0, v97
	v_rcp_f32_e32 v97, v97
	s_nop 0
	v_mul_f32_e32 v97, 0xc1000000, v97
	v_mul_f32_e32 v97, v85, v97
	v_add_f32_e32 v105, v97, v97
	v_cmp_nlt_f32_e32 vcc, s51, v105
	s_and_saveexec_b64 s[8:9], vcc
	s_xor_b64 s[8:9], exec, s[8:9]
	v_mul_f32_e32 v105, 0x3fb8aa3b, v105
	v_exp_f32_e32 v105, v105
	s_nop 0
	v_sub_f32_e32 v106, 1.0, v105
	s_andn2_saveexec_b64 s[8:9], s[8:9]
	v_fma_f32 v106, v105, s14, 0.5
	v_fma_f32 v106, v105, v106, 1.0
	v_mul_f32_e64 v106, v106, -v105
	s_or_b64 exec, exec, s[8:9]
	v_add_f32_e32 v98, v98, v90
	v_mul_f32_e32 v98, 0xbfb8aa3b, v98
	v_exp_f32_e32 v98, v98
	s_nop 0
	v_add_f32_e32 v98, 1.0, v98
	v_rcp_f32_e32 v98, v98
	s_nop 0
	v_mul_f32_e32 v98, 0xc1000000, v98
	v_mul_f32_e32 v98, v86, v98
	v_add_f32_e32 v105, v98, v98
	v_cmp_nlt_f32_e32 vcc, s51, v105
	s_and_saveexec_b64 s[8:9], vcc
	s_xor_b64 s[8:9], exec, s[8:9]
	v_mul_f32_e32 v105, 0x3fb8aa3b, v105
	v_exp_f32_e32 v105, v105
	s_nop 0
	v_sub_f32_e32 v107, 1.0, v105
	s_andn2_saveexec_b64 s[8:9], s[8:9]
	v_fma_f32 v107, v105, s14, 0.5
	v_fma_f32 v107, v105, v107, 1.0
	v_mul_f32_e64 v107, v107, -v105
	s_or_b64 exec, exec, s[8:9]
	v_add_f32_e32 v99, v99, v91
	v_mul_f32_e32 v99, 0xbfb8aa3b, v99
	v_exp_f32_e32 v99, v99
	s_nop 0
	v_add_f32_e32 v99, 1.0, v99
	v_rcp_f32_e32 v99, v99
	s_nop 0
	v_mul_f32_e32 v99, 0xc1000000, v99
	v_mul_f32_e32 v99, v87, v99
	v_add_f32_e32 v136, v99, v99
	v_cmp_nlt_f32_e32 vcc, s51, v136
	s_and_saveexec_b64 s[8:9], vcc
	s_xor_b64 s[8:9], exec, s[8:9]
	v_mul_f32_e32 v105, 0x3fb8aa3b, v136
	v_exp_f32_e32 v105, v105
	s_nop 0
	v_sub_f32_e32 v105, 1.0, v105
	s_andn2_saveexec_b64 s[8:9], s[8:9]
	v_fma_f32 v105, v136, s14, 0.5
	v_fma_f32 v105, v136, v105, 1.0
	v_mul_f32_e64 v105, v105, -v136
	s_or_b64 exec, exec, s[8:9]
	v_add_f32_e32 v94, v94, v78
	v_mul_f32_e32 v94, 0xbfb8aa3b, v94
	v_exp_f32_e32 v94, v94
	v_max_f32_e32 v107, 0, v107
	v_add_f32_e32 v93, v93, v77
	v_add_f32_e32 v94, 1.0, v94
	v_mul_f32_e32 v93, 0xbfb8aa3b, v93
	v_exp_f32_e32 v93, v93
	v_rcp_f32_e32 v94, v94
	v_lshlrev_b32_e32 v136, 16, v123
	v_sqrt_f32_e32 v107, v107
	v_add_f32_e32 v93, 1.0, v93
	v_max_f32_e32 v106, 0, v106
	v_mul_f32_e32 v94, v94, v107
	v_mul_f32_e32 v107, v94, v136
	v_add_f32_e32 v94, v95, v79
	v_mul_f32_e32 v94, 0xbfb8aa3b, v94
	v_exp_f32_e32 v94, v94
	v_add_f32_e32 v92, v92, v76
	v_mul_f32_e32 v92, 0xbfb8aa3b, v92
	v_exp_f32_e32 v92, v92
	v_add_f32_e32 v94, 1.0, v94
	v_add_f32_e32 v92, 1.0, v92
	v_max_f32_e32 v105, 0, v105
	v_rcp_f32_e32 v94, v94
	v_add_f32_e32 v80, v80, v88
	v_mul_f32_e32 v80, 0xbfb8aa3b, v80
	v_exp_f32_e32 v80, v80
	v_rcp_f32_e32 v93, v93
	v_and_b32_e32 v95, 0xffff0000, v122
	v_sqrt_f32_e32 v106, v106
	v_add_f32_e32 v80, 1.0, v80
	v_mul_f32_e32 v93, v93, v106
	v_mul_f32_e32 v106, v93, v95
	v_lshlrev_b32_e32 v93, 16, v122
	s_nop 0
	v_rcp_f32_e32 v92, v92
	v_max_f32_e32 v95, 0, v104
	s_nop 0
	s_nop 0
	v_sqrt_f32_e32 v95, v95
	s_nop 0
	v_mul_f32_e32 v92, v92, v95
	v_mul_f32_e32 v104, v92, v93
	v_lshlrev_b64 v[92:93], 10, v[120:121]
	v_sqrt_f32_e32 v105, v105
	v_and_b32_e32 v95, 0xffff0000, v123
	v_lshl_add_u64 v[92:93], v[92:93], 0, v[180:181]
	v_mul_f32_e32 v94, v94, v105
	v_mul_f32_e32 v105, v94, v95
	v_cvt_pk_bf16_f32 v94, v96, v97
	v_lshlrev_b64 v[96:97], 1, v[92:93]
	v_add_u32_e32 v120, 0xa0, v182
	v_cvt_pk_bf16_f32 v95, v98, v99
	v_lshl_add_u64 v[92:93], s[4:5], 0, v[96:97]
	v_ashrrev_i32_e32 v121, 31, v120
	global_store_dwordx2 v[92:93], v[94:95], off
	v_cvt_pk_bf16_f32 v98, v104, v106
	v_cvt_pk_bf16_f32 v99, v107, v105
	v_lshl_add_u64 v[94:95], s[0:1], 0, v[96:97]
	v_lshlrev_b64 v[96:97], 11, v[120:121]
	v_add_u32_e32 v104, 0xb0, v182
	global_store_dwordx2 v[94:95], v[98:99], off
	v_lshl_add_u64 v[98:99], v[140:141], 0, v[96:97]
	v_ashrrev_i32_e32 v105, 31, v104
	global_load_dwordx2 v[122:123], v[98:99], off
	v_lshlrev_b64 v[98:99], 11, v[104:105]
	v_lshl_add_u64 v[106:107], v[140:141], 0, v[98:99]
	global_load_dwordx2 v[106:107], v[106:107], off
	v_rcp_f32_e32 v80, v80
	s_nop 0
	v_mul_f32_e32 v80, 0xc1000000, v80
	v_mul_f32_e32 v80, v84, v80
	v_add_f32_e32 v137, v80, v80
	v_cmp_nlt_f32_e32 vcc, s51, v137
	s_and_saveexec_b64 s[8:9], vcc
	s_xor_b64 s[8:9], exec, s[8:9]
	v_mul_f32_e32 v136, 0x3fb8aa3b, v137
	v_exp_f32_e32 v136, v136
	s_nop 0
	v_sub_f32_e32 v136, 1.0, v136
	s_andn2_saveexec_b64 s[8:9], s[8:9]
	v_fma_f32 v136, v137, s14, 0.5
	v_fma_f32 v136, v137, v136, 1.0
	v_mul_f32_e64 v136, v136, -v137
	s_or_b64 exec, exec, s[8:9]
	v_add_f32_e32 v81, v81, v89
	v_mul_f32_e32 v81, 0xbfb8aa3b, v81
	v_exp_f32_e32 v81, v81
	s_nop 0
	v_add_f32_e32 v81, 1.0, v81
	v_rcp_f32_e32 v81, v81
	s_nop 0
	v_mul_f32_e32 v81, 0xc1000000, v81
	v_mul_f32_e32 v81, v85, v81
	v_add_f32_e32 v137, v81, v81
	v_cmp_nlt_f32_e32 vcc, s51, v137
	s_and_saveexec_b64 s[8:9], vcc
	s_xor_b64 s[8:9], exec, s[8:9]
	v_mul_f32_e32 v137, 0x3fb8aa3b, v137
	v_exp_f32_e32 v137, v137
	s_nop 0
	v_sub_f32_e32 v138, 1.0, v137
	s_andn2_saveexec_b64 s[8:9], s[8:9]
	v_fma_f32 v138, v137, s14, 0.5
	v_fma_f32 v138, v137, v138, 1.0
	v_mul_f32_e64 v138, v138, -v137
	s_or_b64 exec, exec, s[8:9]
	v_add_f32_e32 v82, v82, v90
	v_mul_f32_e32 v82, 0xbfb8aa3b, v82
	v_exp_f32_e32 v82, v82
	s_nop 0
	v_add_f32_e32 v82, 1.0, v82
	v_rcp_f32_e32 v82, v82
	s_nop 0
	v_mul_f32_e32 v82, 0xc1000000, v82
	v_mul_f32_e32 v82, v86, v82
	v_add_f32_e32 v137, v82, v82
	v_cmp_nlt_f32_e32 vcc, s51, v137
	s_and_saveexec_b64 s[8:9], vcc
	s_xor_b64 s[8:9], exec, s[8:9]
	v_mul_f32_e32 v137, 0x3fb8aa3b, v137
	v_exp_f32_e32 v137, v137
	s_nop 0
	v_sub_f32_e32 v139, 1.0, v137
	s_andn2_saveexec_b64 s[8:9], s[8:9]
	v_fma_f32 v139, v137, s14, 0.5
	v_fma_f32 v139, v137, v139, 1.0
	v_mul_f32_e64 v139, v139, -v137
	s_or_b64 exec, exec, s[8:9]
	v_add_f32_e32 v83, v83, v91
	v_mul_f32_e32 v83, 0xbfb8aa3b, v83
	v_exp_f32_e32 v83, v83
	s_nop 0
	v_add_f32_e32 v83, 1.0, v83
	v_rcp_f32_e32 v83, v83
	s_nop 0
	v_mul_f32_e32 v83, 0xc1000000, v83
	v_mul_f32_e32 v83, v87, v83
	v_add_f32_e32 v140, v83, v83
	v_cmp_nlt_f32_e32 vcc, s51, v140
	s_and_saveexec_b64 s[8:9], vcc
	s_xor_b64 s[8:9], exec, s[8:9]
	v_mul_f32_e32 v137, 0x3fb8aa3b, v140
	v_exp_f32_e32 v137, v137
	s_nop 0
	v_sub_f32_e32 v137, 1.0, v137
	s_andn2_saveexec_b64 s[8:9], s[8:9]
	v_fma_f32 v137, v140, s14, 0.5
	v_fma_f32 v137, v140, v137, 1.0
	v_mul_f32_e64 v137, v137, -v140
	s_or_b64 exec, exec, s[8:9]
	v_add_f32_e32 v74, v74, v78
	v_mul_f32_e32 v74, 0xbfb8aa3b, v74
	v_exp_f32_e32 v74, v74
	v_max_f32_e32 v139, 0, v139
	v_add_f32_e32 v73, v73, v77
	v_add_f32_e32 v74, 1.0, v74
	v_mul_f32_e32 v73, 0xbfb8aa3b, v73
	v_exp_f32_e32 v73, v73
	v_rcp_f32_e32 v74, v74
	s_waitcnt vmcnt(0)
	v_lshlrev_b32_e32 v140, 16, v123
	v_sqrt_f32_e32 v139, v139
	v_add_f32_e32 v73, 1.0, v73
	v_max_f32_e32 v138, 0, v138
	v_mul_f32_e32 v74, v74, v139
	v_mul_f32_e32 v139, v74, v140
	v_add_f32_e32 v74, v75, v79
	v_mul_f32_e32 v74, 0xbfb8aa3b, v74
	v_exp_f32_e32 v74, v74
	v_add_f32_e32 v72, v72, v76
	v_mul_f32_e32 v72, 0xbfb8aa3b, v72
	v_exp_f32_e32 v72, v72
	v_add_f32_e32 v74, 1.0, v74
	v_add_f32_e32 v72, 1.0, v72
	v_add_f32_e32 v68, v68, v88
	v_mul_f32_e32 v68, 0xbfb8aa3b, v68
	v_rcp_f32_e32 v74, v74
	v_exp_f32_e32 v68, v68
	v_rcp_f32_e32 v73, v73
	v_and_b32_e32 v75, 0xffff0000, v122
	v_sqrt_f32_e32 v138, v138
	v_add_f32_e32 v68, 1.0, v68
	v_mul_f32_e32 v73, v73, v138
	v_mul_f32_e32 v138, v73, v75
	v_lshlrev_b32_e32 v73, 16, v122
	s_nop 0
	v_rcp_f32_e32 v72, v72
	v_max_f32_e32 v75, 0, v136
	s_nop 1
	v_sqrt_f32_e32 v75, v75
	s_nop 0
	v_mul_f32_e32 v72, v72, v75
	v_mul_f32_e32 v122, v72, v73
	v_lshlrev_b64 v[72:73], 10, v[120:121]
	v_max_f32_e32 v120, 0, v137
	v_lshl_add_u64 v[72:73], v[72:73], 0, v[180:181]
	v_and_b32_e32 v75, 0xffff0000, v123
	v_sqrt_f32_e32 v120, v120
	v_lshlrev_b64 v[72:73], 1, v[72:73]
	v_mul_f32_e32 v74, v74, v120
	v_mul_f32_e32 v120, v74, v75
	v_cvt_pk_bf16_f32 v74, v80, v81
	v_cvt_pk_bf16_f32 v75, v82, v83
	v_lshl_add_u64 v[80:81], s[4:5], 0, v[72:73]
	v_lshl_add_u64 v[82:83], s[0:1], 0, v[72:73]
	global_store_dwordx2 v[80:81], v[74:75], off
	v_cvt_pk_bf16_f32 v74, v122, v138
	v_cvt_pk_bf16_f32 v75, v139, v120
	global_store_dwordx2 v[82:83], v[74:75], off
	v_rcp_f32_e32 v68, v68
	s_nop 0
	v_mul_f32_e32 v68, 0xc1000000, v68
	v_mul_f32_e32 v68, v84, v68
	v_add_f32_e32 v73, v68, v68
	v_cmp_nlt_f32_e32 vcc, s51, v73
	s_and_saveexec_b64 s[8:9], vcc
	s_xor_b64 s[8:9], exec, s[8:9]
	v_mul_f32_e32 v72, 0x3fb8aa3b, v73
	v_exp_f32_e32 v72, v72
	s_nop 0
	v_sub_f32_e32 v72, 1.0, v72
	s_andn2_saveexec_b64 s[8:9], s[8:9]
	v_fma_f32 v72, v73, s14, 0.5
	v_fma_f32 v72, v73, v72, 1.0
	v_mul_f32_e64 v72, v72, -v73
	s_or_b64 exec, exec, s[8:9]
	v_add_f32_e32 v69, v69, v89
	v_mul_f32_e32 v69, 0xbfb8aa3b, v69
	v_exp_f32_e32 v69, v69
	s_nop 0
	v_add_f32_e32 v69, 1.0, v69
	v_rcp_f32_e32 v69, v69
	s_nop 0
	v_mul_f32_e32 v69, 0xc1000000, v69
	v_mul_f32_e32 v69, v85, v69
	v_add_f32_e32 v73, v69, v69
	v_cmp_nlt_f32_e32 vcc, s51, v73
	s_and_saveexec_b64 s[8:9], vcc
	s_xor_b64 s[8:9], exec, s[8:9]
	v_mul_f32_e32 v73, 0x3fb8aa3b, v73
	v_exp_f32_e32 v73, v73
	s_nop 0
	v_sub_f32_e32 v74, 1.0, v73
	s_andn2_saveexec_b64 s[8:9], s[8:9]
	v_fma_f32 v74, v73, s14, 0.5
	v_fma_f32 v74, v73, v74, 1.0
	v_mul_f32_e64 v74, v74, -v73
	s_or_b64 exec, exec, s[8:9]
	v_add_f32_e32 v70, v70, v90
	v_mul_f32_e32 v70, 0xbfb8aa3b, v70
	v_exp_f32_e32 v70, v70
	s_nop 0
	v_add_f32_e32 v70, 1.0, v70
	v_rcp_f32_e32 v70, v70
	s_nop 0
	v_mul_f32_e32 v70, 0xc1000000, v70
	v_mul_f32_e32 v70, v86, v70
	v_add_f32_e32 v73, v70, v70
	v_cmp_nlt_f32_e32 vcc, s51, v73
	s_and_saveexec_b64 s[8:9], vcc
	s_xor_b64 s[8:9], exec, s[8:9]
	v_mul_f32_e32 v73, 0x3fb8aa3b, v73
	v_exp_f32_e32 v73, v73
	s_nop 0
	v_sub_f32_e32 v75, 1.0, v73
	s_andn2_saveexec_b64 s[8:9], s[8:9]
	v_fma_f32 v75, v73, s14, 0.5
	v_fma_f32 v75, v73, v75, 1.0
	v_mul_f32_e64 v75, v75, -v73
	s_or_b64 exec, exec, s[8:9]
	v_add_f32_e32 v71, v71, v91
	v_mul_f32_e32 v71, 0xbfb8aa3b, v71
	v_exp_f32_e32 v71, v71
	s_nop 0
	v_add_f32_e32 v71, 1.0, v71
	v_rcp_f32_e32 v71, v71
	s_nop 0
	v_mul_f32_e32 v71, 0xc1000000, v71
	v_mul_f32_e32 v71, v87, v71
	v_add_f32_e32 v84, v71, v71
	v_cmp_nlt_f32_e32 vcc, s51, v84
	s_and_saveexec_b64 s[8:9], vcc
	s_xor_b64 s[8:9], exec, s[8:9]
	v_mul_f32_e32 v73, 0x3fb8aa3b, v84
	v_exp_f32_e32 v73, v73
	s_nop 0
	v_sub_f32_e32 v73, 1.0, v73
	s_andn2_saveexec_b64 s[8:9], s[8:9]
	v_fma_f32 v73, v84, s14, 0.5
	v_fma_f32 v73, v84, v73, 1.0
	v_mul_f32_e64 v73, v73, -v84
	s_or_b64 exec, exec, s[8:9]
	v_add_f32_e32 v66, v66, v78
	v_mul_f32_e32 v66, 0xbfb8aa3b, v66
	v_exp_f32_e32 v66, v66
	v_max_f32_e32 v75, 0, v75
	v_add_f32_e32 v65, v65, v77
	v_add_f32_e32 v66, 1.0, v66
	v_mul_f32_e32 v65, 0xbfb8aa3b, v65
	v_exp_f32_e32 v65, v65
	v_rcp_f32_e32 v66, v66
	v_lshlrev_b32_e32 v78, 16, v107
	v_sqrt_f32_e32 v75, v75
	v_add_f32_e32 v65, 1.0, v65
	v_max_f32_e32 v74, 0, v74
	v_mul_f32_e32 v66, v66, v75
	v_mul_f32_e32 v75, v66, v78
	v_add_f32_e32 v66, v67, v79
	v_mul_f32_e32 v66, 0xbfb8aa3b, v66
	v_exp_f32_e32 v66, v66
	v_add_f32_e32 v64, v64, v76
	v_mul_f32_e32 v64, 0xbfb8aa3b, v64
	v_exp_f32_e32 v64, v64
	v_add_f32_e32 v66, 1.0, v66
	v_add_f32_e32 v64, 1.0, v64
	v_max_f32_e32 v73, 0, v73
	v_rcp_f32_e32 v66, v66
	s_nop 0
	v_rcp_f32_e32 v65, v65
	v_and_b32_e32 v67, 0xffff0000, v106
	v_sqrt_f32_e32 v74, v74
	v_or_b32_e32 v84, 64, v180
	v_ashrrev_i32_e32 v85, 31, v84
	v_mul_f32_e32 v65, v65, v74
	v_mul_f32_e32 v74, v65, v67
	v_lshlrev_b32_e32 v65, 16, v106
	v_lshlrev_b64 v[84:85], 1, v[84:85]
	v_rcp_f32_e32 v64, v64
	v_max_f32_e32 v67, 0, v72
	s_nop 1
	v_sqrt_f32_e32 v67, v67
	s_nop 0
	v_sqrt_f32_e32 v73, v73
	v_mul_f32_e32 v64, v64, v67
	v_mul_f32_e32 v72, v64, v65
	v_lshlrev_b64 v[64:65], 10, v[104:105]
	v_lshl_add_u64 v[64:65], v[64:65], 0, v[180:181]
	v_and_b32_e32 v67, 0xffff0000, v107
	v_mul_f32_e32 v66, v66, v73
	v_lshlrev_b64 v[64:65], 1, v[64:65]
	v_mul_f32_e32 v73, v66, v67
	v_cvt_pk_bf16_f32 v66, v68, v69
	v_cvt_pk_bf16_f32 v67, v70, v71
	v_lshl_add_u64 v[76:77], s[4:5], 0, v[64:65]
	v_lshl_add_u64 v[78:79], s[0:1], 0, v[64:65]
	global_store_dwordx2 v[76:77], v[66:67], off
	v_cvt_pk_bf16_f32 v66, v72, v74
	v_cvt_pk_bf16_f32 v67, v75, v73
	global_store_dwordx2 v[78:79], v[66:67], off
	global_load_dwordx4 v[72:75], v[172:173], off offset:256
	s_nop 0
	global_load_dwordx4 v[64:67], v[158:159], off offset:256
	global_load_dwordx4 v[68:71], v[174:175], off offset:256
	v_readlane_b32 s0, v253, 45
	v_readlane_b32 s1, v253, 46
	s_waitcnt vmcnt(0)
	v_add_f32_e32 v60, v60, v72
	v_lshl_add_u64 v[86:87], s[0:1], 0, v[178:179]
	v_lshl_add_u64 v[86:87], v[86:87], 0, v[84:85]
	global_load_dwordx2 v[88:89], v[86:87], off
	v_lshl_add_u64 v[86:87], s[0:1], 0, v[176:177]
	v_lshl_add_u64 v[86:87], v[86:87], 0, v[84:85]
	global_load_dwordx2 v[86:87], v[86:87], off
	v_mul_f32_e32 v60, 0xbfb8aa3b, v60
	v_exp_f32_e32 v60, v60
	s_nop 0
	v_add_f32_e32 v60, 1.0, v60
	s_nop 0
	v_rcp_f32_e32 v60, v60
	s_nop 0
	v_mul_f32_e32 v60, 0xc1000000, v60
	v_mul_f32_e32 v60, v68, v60
	v_add_f32_e32 v91, v60, v60
	v_cmp_nlt_f32_e32 vcc, s51, v91
	s_and_saveexec_b64 s[0:1], vcc
	s_xor_b64 s[0:1], exec, s[0:1]
	v_mul_f32_e32 v90, 0x3fb8aa3b, v91
	v_exp_f32_e32 v90, v90
	s_nop 0
	v_sub_f32_e32 v90, 1.0, v90
	s_andn2_saveexec_b64 s[0:1], s[0:1]
	v_fma_f32 v90, v91, s14, 0.5
	v_fma_f32 v90, v91, v90, 1.0
	v_mul_f32_e64 v90, v90, -v91
	s_or_b64 exec, exec, s[0:1]
	v_add_f32_e32 v61, v61, v73
	v_mul_f32_e32 v61, 0xbfb8aa3b, v61
	v_exp_f32_e32 v61, v61
	s_nop 0
	v_add_f32_e32 v61, 1.0, v61
	v_rcp_f32_e32 v61, v61
	s_nop 0
	v_mul_f32_e32 v61, 0xc1000000, v61
	v_mul_f32_e32 v61, v69, v61
	v_add_f32_e32 v91, v61, v61
	v_cmp_nlt_f32_e32 vcc, s51, v91
	s_and_saveexec_b64 s[0:1], vcc
	s_xor_b64 s[0:1], exec, s[0:1]
	v_mul_f32_e32 v91, 0x3fb8aa3b, v91
	v_exp_f32_e32 v91, v91
	s_nop 0
	v_sub_f32_e32 v104, 1.0, v91
	s_andn2_saveexec_b64 s[0:1], s[0:1]
	v_fma_f32 v104, v91, s14, 0.5
	v_fma_f32 v104, v91, v104, 1.0
	v_mul_f32_e64 v104, v104, -v91
	s_or_b64 exec, exec, s[0:1]
	v_add_f32_e32 v62, v62, v74
	v_mul_f32_e32 v62, 0xbfb8aa3b, v62
	v_exp_f32_e32 v62, v62
	s_nop 0
	v_add_f32_e32 v62, 1.0, v62
	v_rcp_f32_e32 v62, v62
	s_nop 0
	v_mul_f32_e32 v62, 0xc1000000, v62
	v_mul_f32_e32 v62, v70, v62
	v_add_f32_e32 v91, v62, v62
	v_cmp_nlt_f32_e32 vcc, s51, v91
	s_and_saveexec_b64 s[0:1], vcc
	s_xor_b64 s[0:1], exec, s[0:1]
	v_mul_f32_e32 v91, 0x3fb8aa3b, v91
	v_exp_f32_e32 v91, v91
	s_nop 0
	v_sub_f32_e32 v105, 1.0, v91
	s_andn2_saveexec_b64 s[0:1], s[0:1]
	v_fma_f32 v105, v91, s14, 0.5
	v_fma_f32 v105, v91, v105, 1.0
	v_mul_f32_e64 v105, v105, -v91
	s_or_b64 exec, exec, s[0:1]
	v_add_f32_e32 v63, v63, v75
	v_mul_f32_e32 v63, 0xbfb8aa3b, v63
	v_exp_f32_e32 v63, v63
	s_nop 0
	v_add_f32_e32 v63, 1.0, v63
	v_rcp_f32_e32 v63, v63
	s_nop 0
	v_mul_f32_e32 v63, 0xc1000000, v63
	v_mul_f32_e32 v63, v71, v63
	v_add_f32_e32 v106, v63, v63
	v_cmp_nlt_f32_e32 vcc, s51, v106
	s_and_saveexec_b64 s[0:1], vcc
	s_xor_b64 s[0:1], exec, s[0:1]
	v_mul_f32_e32 v91, 0x3fb8aa3b, v106
	v_exp_f32_e32 v91, v91
	s_nop 0
	v_sub_f32_e32 v91, 1.0, v91
	s_andn2_saveexec_b64 s[0:1], s[0:1]
	v_fma_f32 v91, v106, s14, 0.5
	v_fma_f32 v91, v106, v91, 1.0
	v_mul_f32_e64 v91, v91, -v106
	s_or_b64 exec, exec, s[0:1]
	v_add_f32_e32 v58, v58, v66
	v_mul_f32_e32 v58, 0xbfb8aa3b, v58
	v_exp_f32_e32 v58, v58
	v_max_f32_e32 v105, 0, v105
	v_add_f32_e32 v59, v59, v67
	v_add_f32_e32 v58, 1.0, v58
	v_mul_f32_e32 v59, 0xbfb8aa3b, v59
	v_exp_f32_e32 v59, v59
	v_add_f32_e32 v57, v57, v65
	v_rcp_f32_e32 v58, v58
	v_add_f32_e32 v59, 1.0, v59
	v_sqrt_f32_e32 v105, v105
	s_waitcnt vmcnt(0)
	v_lshlrev_b32_e32 v106, 16, v89
	v_mul_f32_e32 v57, 0xbfb8aa3b, v57
	v_mul_f32_e32 v58, v58, v105
	v_mul_f32_e32 v58, v58, v106
	v_exp_f32_e32 v57, v57
	v_max_f32_e32 v104, 0, v104
	v_add_f32_e32 v57, 1.0, v57
	v_rcp_f32_e32 v59, v59
	v_add_f32_e32 v56, v56, v64
	v_mul_f32_e32 v56, 0xbfb8aa3b, v56
	v_exp_f32_e32 v56, v56
	v_rcp_f32_e32 v57, v57
	v_and_b32_e32 v105, 0xffff0000, v88
	v_sqrt_f32_e32 v104, v104
	v_add_f32_e32 v56, 1.0, v56
	v_add_f32_e32 v52, v52, v72
	v_mul_f32_e32 v57, v57, v104
	v_mul_f32_e32 v104, v57, v105
	v_lshlrev_b32_e32 v57, 16, v88
	v_mul_f32_e32 v52, 0xbfb8aa3b, v52
	v_exp_f32_e32 v52, v52
	v_rcp_f32_e32 v56, v56
	v_max_f32_e32 v88, 0, v90
	v_add_f32_e32 v52, 1.0, v52
	s_nop 0
	v_sqrt_f32_e32 v88, v88
	s_nop 0
	v_mul_f32_e32 v56, v56, v88
	v_mul_f32_e32 v88, v56, v57
	v_max_f32_e32 v57, 0, v91
	v_and_b32_e32 v56, 0xffff0000, v89
	s_nop 0
	v_sqrt_f32_e32 v57, v57
	s_nop 0
	v_mul_f32_e32 v57, v59, v57
	v_mul_f32_e32 v59, v57, v56
	v_cvt_pk_bf16_f32 v56, v60, v61
	v_cvt_pk_bf16_f32 v57, v62, v63
	global_store_dwordx2 v[132:133], v[56:57], off offset:128
	v_cvt_pk_bf16_f32 v56, v88, v104
	v_cvt_pk_bf16_f32 v57, v58, v59
	global_store_dwordx2 v[134:135], v[56:57], off offset:128
	s_nop 0
	v_rcp_f32_e32 v52, v52
	s_nop 0
	v_mul_f32_e32 v52, 0xc1000000, v52
	v_mul_f32_e32 v52, v68, v52
	v_add_f32_e32 v57, v52, v52
	v_cmp_nlt_f32_e32 vcc, s51, v57
	s_and_saveexec_b64 s[0:1], vcc
	s_xor_b64 s[0:1], exec, s[0:1]
	v_mul_f32_e32 v56, 0x3fb8aa3b, v57
	v_exp_f32_e32 v56, v56
	s_nop 0
	v_sub_f32_e32 v56, 1.0, v56
	s_andn2_saveexec_b64 s[0:1], s[0:1]
	v_fma_f32 v56, v57, s14, 0.5
	v_fma_f32 v56, v57, v56, 1.0
	v_mul_f32_e64 v56, v56, -v57
	s_or_b64 exec, exec, s[0:1]
	v_add_f32_e32 v53, v53, v73
	v_mul_f32_e32 v53, 0xbfb8aa3b, v53
	v_exp_f32_e32 v53, v53
	s_nop 0
	v_add_f32_e32 v53, 1.0, v53
	v_rcp_f32_e32 v53, v53
	s_nop 0
	v_mul_f32_e32 v53, 0xc1000000, v53
	v_mul_f32_e32 v53, v69, v53
	v_add_f32_e32 v57, v53, v53
	v_cmp_nlt_f32_e32 vcc, s51, v57
	s_and_saveexec_b64 s[0:1], vcc
	s_xor_b64 s[0:1], exec, s[0:1]
	v_mul_f32_e32 v57, 0x3fb8aa3b, v57
	v_exp_f32_e32 v57, v57
	s_nop 0
	v_sub_f32_e32 v58, 1.0, v57
	s_andn2_saveexec_b64 s[0:1], s[0:1]
	v_fma_f32 v58, v57, s14, 0.5
	v_fma_f32 v58, v57, v58, 1.0
	v_mul_f32_e64 v58, v58, -v57
	s_or_b64 exec, exec, s[0:1]
	v_add_f32_e32 v54, v54, v74
	v_mul_f32_e32 v54, 0xbfb8aa3b, v54
	v_exp_f32_e32 v54, v54
	s_nop 0
	v_add_f32_e32 v54, 1.0, v54
	v_rcp_f32_e32 v54, v54
	s_nop 0
	v_mul_f32_e32 v54, 0xc1000000, v54
	v_mul_f32_e32 v54, v70, v54
	v_add_f32_e32 v57, v54, v54
	v_cmp_nlt_f32_e32 vcc, s51, v57
	s_and_saveexec_b64 s[0:1], vcc
	s_xor_b64 s[0:1], exec, s[0:1]
	v_mul_f32_e32 v57, 0x3fb8aa3b, v57
	v_exp_f32_e32 v57, v57
	s_nop 0
	v_sub_f32_e32 v59, 1.0, v57
	s_andn2_saveexec_b64 s[0:1], s[0:1]
	v_fma_f32 v59, v57, s14, 0.5
	v_fma_f32 v59, v57, v59, 1.0
	v_mul_f32_e64 v59, v59, -v57
	s_or_b64 exec, exec, s[0:1]
	v_add_f32_e32 v55, v55, v75
	v_mul_f32_e32 v55, 0xbfb8aa3b, v55
	v_exp_f32_e32 v55, v55
	s_nop 0
	v_add_f32_e32 v55, 1.0, v55
	v_rcp_f32_e32 v55, v55
	s_nop 0
	v_mul_f32_e32 v55, 0xc1000000, v55
	v_mul_f32_e32 v55, v71, v55
	v_add_f32_e32 v60, v55, v55
	v_cmp_nlt_f32_e32 vcc, s51, v60
	s_and_saveexec_b64 s[0:1], vcc
	s_xor_b64 s[0:1], exec, s[0:1]
	v_mul_f32_e32 v57, 0x3fb8aa3b, v60
	v_exp_f32_e32 v57, v57
	s_nop 0
	v_sub_f32_e32 v57, 1.0, v57
	s_andn2_saveexec_b64 s[0:1], s[0:1]
	v_fma_f32 v57, v60, s14, 0.5
	v_fma_f32 v57, v60, v57, 1.0
	v_mul_f32_e64 v57, v57, -v60
	s_or_b64 exec, exec, s[0:1]
	v_add_f32_e32 v50, v50, v66
	v_mul_f32_e32 v50, 0xbfb8aa3b, v50
	v_exp_f32_e32 v50, v50
	v_max_f32_e32 v59, 0, v59
	v_add_f32_e32 v51, v51, v67
	v_add_f32_e32 v50, 1.0, v50
	v_mul_f32_e32 v51, 0xbfb8aa3b, v51
	v_exp_f32_e32 v51, v51
	v_add_f32_e32 v49, v49, v65
	v_rcp_f32_e32 v50, v50
	v_add_f32_e32 v51, 1.0, v51
	v_sqrt_f32_e32 v59, v59
	v_lshlrev_b32_e32 v60, 16, v87
	v_mul_f32_e32 v49, 0xbfb8aa3b, v49
	v_mul_f32_e32 v50, v50, v59
	v_mul_f32_e32 v50, v50, v60
	v_exp_f32_e32 v49, v49
	v_max_f32_e32 v58, 0, v58
	v_add_f32_e32 v49, 1.0, v49
	v_rcp_f32_e32 v51, v51
	v_add_f32_e32 v48, v48, v64
	v_mul_f32_e32 v48, 0xbfb8aa3b, v48
	v_exp_f32_e32 v48, v48
	v_rcp_f32_e32 v49, v49
	v_and_b32_e32 v59, 0xffff0000, v86
	v_sqrt_f32_e32 v58, v58
	v_add_f32_e32 v48, 1.0, v48
	v_mul_f32_e32 v49, v49, v58
	v_mul_f32_e32 v58, v49, v59
	v_max_f32_e32 v56, 0, v56
	v_lshlrev_b32_e32 v49, 16, v86
	v_readlane_b32 s0, v253, 45
	v_rcp_f32_e32 v48, v48
	v_readlane_b32 s1, v253, 46
	v_sqrt_f32_e32 v56, v56
	v_add_f32_e32 v44, v44, v72
	v_mul_f32_e32 v44, 0xbfb8aa3b, v44
	v_mul_f32_e32 v48, v48, v56
	v_mul_f32_e32 v56, v48, v49
	v_max_f32_e32 v49, 0, v57
	v_and_b32_e32 v48, 0xffff0000, v87
	v_exp_f32_e32 v44, v44
	v_sqrt_f32_e32 v49, v49
	v_add_f32_e32 v44, 1.0, v44
	v_mul_f32_e32 v49, v51, v49
	v_mul_f32_e32 v51, v49, v48
	v_cvt_pk_bf16_f32 v48, v52, v53
	v_cvt_pk_bf16_f32 v49, v54, v55
	global_store_dwordx2 v[124:125], v[48:49], off offset:128
	v_cvt_pk_bf16_f32 v48, v56, v58
	v_cvt_pk_bf16_f32 v49, v50, v51
	global_store_dwordx2 v[126:127], v[48:49], off offset:128
	v_lshl_add_u64 v[48:49], s[0:1], 0, v[128:129]
	v_lshl_add_u64 v[48:49], v[48:49], 0, v[84:85]
	global_load_dwordx2 v[50:51], v[48:49], off
	v_lshl_add_u64 v[48:49], s[0:1], 0, v[130:131]
	v_lshl_add_u64 v[48:49], v[48:49], 0, v[84:85]
	global_load_dwordx2 v[48:49], v[48:49], off
	s_nop 0
	v_rcp_f32_e32 v44, v44
	s_nop 0
	v_mul_f32_e32 v44, 0xc1000000, v44
	v_mul_f32_e32 v44, v68, v44
	v_add_f32_e32 v53, v44, v44
	v_cmp_nlt_f32_e32 vcc, s51, v53
	s_and_saveexec_b64 s[0:1], vcc
	s_xor_b64 s[0:1], exec, s[0:1]
	v_mul_f32_e32 v52, 0x3fb8aa3b, v53
	v_exp_f32_e32 v52, v52
	s_nop 0
	v_sub_f32_e32 v52, 1.0, v52
	s_andn2_saveexec_b64 s[0:1], s[0:1]
	v_fma_f32 v52, v53, s14, 0.5
	v_fma_f32 v52, v53, v52, 1.0
	v_mul_f32_e64 v52, v52, -v53
	s_or_b64 exec, exec, s[0:1]
	v_add_f32_e32 v45, v45, v73
	v_mul_f32_e32 v45, 0xbfb8aa3b, v45
	v_exp_f32_e32 v45, v45
	s_nop 0
	v_add_f32_e32 v45, 1.0, v45
	v_rcp_f32_e32 v45, v45
	s_nop 0
	v_mul_f32_e32 v45, 0xc1000000, v45
	v_mul_f32_e32 v45, v69, v45
	v_add_f32_e32 v53, v45, v45
	v_cmp_nlt_f32_e32 vcc, s51, v53
	s_and_saveexec_b64 s[0:1], vcc
	s_xor_b64 s[0:1], exec, s[0:1]
	v_mul_f32_e32 v53, 0x3fb8aa3b, v53
	v_exp_f32_e32 v53, v53
	s_nop 0
	v_sub_f32_e32 v54, 1.0, v53
	s_andn2_saveexec_b64 s[0:1], s[0:1]
	v_fma_f32 v54, v53, s14, 0.5
	v_fma_f32 v54, v53, v54, 1.0
	v_mul_f32_e64 v54, v54, -v53
	s_or_b64 exec, exec, s[0:1]
	v_add_f32_e32 v46, v46, v74
	v_mul_f32_e32 v46, 0xbfb8aa3b, v46
	v_exp_f32_e32 v46, v46
	s_nop 0
	v_add_f32_e32 v46, 1.0, v46
	v_rcp_f32_e32 v46, v46
	s_nop 0
	v_mul_f32_e32 v46, 0xc1000000, v46
	v_mul_f32_e32 v46, v70, v46
	v_add_f32_e32 v53, v46, v46
	v_cmp_nlt_f32_e32 vcc, s51, v53
	s_and_saveexec_b64 s[0:1], vcc
	s_xor_b64 s[0:1], exec, s[0:1]
	v_mul_f32_e32 v53, 0x3fb8aa3b, v53
	v_exp_f32_e32 v53, v53
	s_nop 0
	v_sub_f32_e32 v55, 1.0, v53
	s_andn2_saveexec_b64 s[0:1], s[0:1]
	v_fma_f32 v55, v53, s14, 0.5
	v_fma_f32 v55, v53, v55, 1.0
	v_mul_f32_e64 v55, v55, -v53
	s_or_b64 exec, exec, s[0:1]
	v_add_f32_e32 v47, v47, v75
	v_mul_f32_e32 v47, 0xbfb8aa3b, v47
	v_exp_f32_e32 v47, v47
	s_nop 0
	v_add_f32_e32 v47, 1.0, v47
	v_rcp_f32_e32 v47, v47
	s_nop 0
	v_mul_f32_e32 v47, 0xc1000000, v47
	v_mul_f32_e32 v47, v71, v47
	v_add_f32_e32 v56, v47, v47
	v_cmp_nlt_f32_e32 vcc, s51, v56
	s_and_saveexec_b64 s[0:1], vcc
	s_xor_b64 s[0:1], exec, s[0:1]
	v_mul_f32_e32 v53, 0x3fb8aa3b, v56
	v_exp_f32_e32 v53, v53
	s_nop 0
	v_sub_f32_e32 v53, 1.0, v53
	s_andn2_saveexec_b64 s[0:1], s[0:1]
	v_fma_f32 v53, v56, s14, 0.5
	v_fma_f32 v53, v56, v53, 1.0
	v_mul_f32_e64 v53, v53, -v56
	s_or_b64 exec, exec, s[0:1]
	v_add_f32_e32 v42, v42, v66
	v_mul_f32_e32 v42, 0xbfb8aa3b, v42
	v_exp_f32_e32 v42, v42
	v_max_f32_e32 v55, 0, v55
	v_add_f32_e32 v43, v43, v67
	v_add_f32_e32 v42, 1.0, v42
	v_mul_f32_e32 v43, 0xbfb8aa3b, v43
	v_exp_f32_e32 v43, v43
	v_add_f32_e32 v41, v41, v65
	v_rcp_f32_e32 v42, v42
	v_add_f32_e32 v43, 1.0, v43
	v_sqrt_f32_e32 v55, v55
	s_waitcnt vmcnt(0)
	v_lshlrev_b32_e32 v56, 16, v51
	v_mul_f32_e32 v41, 0xbfb8aa3b, v41
	v_mul_f32_e32 v42, v42, v55
	v_mul_f32_e32 v42, v42, v56
	v_exp_f32_e32 v41, v41
	v_max_f32_e32 v54, 0, v54
	v_add_f32_e32 v41, 1.0, v41
	v_rcp_f32_e32 v43, v43
	v_add_f32_e32 v40, v40, v64
	v_mul_f32_e32 v40, 0xbfb8aa3b, v40
	v_exp_f32_e32 v40, v40
	v_rcp_f32_e32 v41, v41
	v_and_b32_e32 v55, 0xffff0000, v50
	v_sqrt_f32_e32 v54, v54
	v_add_f32_e32 v40, 1.0, v40
	v_add_f32_e32 v36, v36, v72
	v_mul_f32_e32 v41, v41, v54
	v_mul_f32_e32 v54, v41, v55
	v_lshlrev_b32_e32 v41, 16, v50
	v_mul_f32_e32 v36, 0xbfb8aa3b, v36
	v_exp_f32_e32 v36, v36
	v_rcp_f32_e32 v40, v40
	v_max_f32_e32 v50, 0, v52
	v_add_f32_e32 v36, 1.0, v36
	s_nop 0
	v_sqrt_f32_e32 v50, v50
	s_nop 0
	v_mul_f32_e32 v40, v40, v50
	v_mul_f32_e32 v50, v40, v41
	v_max_f32_e32 v41, 0, v53
	v_and_b32_e32 v40, 0xffff0000, v51
	s_nop 0
	v_sqrt_f32_e32 v41, v41
	s_nop 0
	v_mul_f32_e32 v41, v43, v41
	v_mul_f32_e32 v43, v41, v40
	v_cvt_pk_bf16_f32 v40, v44, v45
	v_cvt_pk_bf16_f32 v41, v46, v47
	global_store_dwordx2 v[116:117], v[40:41], off offset:128
	v_cvt_pk_bf16_f32 v40, v50, v54
	v_cvt_pk_bf16_f32 v41, v42, v43
	global_store_dwordx2 v[118:119], v[40:41], off offset:128
	s_nop 0
	v_rcp_f32_e32 v36, v36
	s_nop 0
	v_mul_f32_e32 v36, 0xc1000000, v36
	v_mul_f32_e32 v36, v68, v36
	v_add_f32_e32 v41, v36, v36
	v_cmp_nlt_f32_e32 vcc, s51, v41
	s_and_saveexec_b64 s[0:1], vcc
	s_xor_b64 s[0:1], exec, s[0:1]
	v_mul_f32_e32 v40, 0x3fb8aa3b, v41
	v_exp_f32_e32 v40, v40
	s_nop 0
	v_sub_f32_e32 v40, 1.0, v40
	s_andn2_saveexec_b64 s[0:1], s[0:1]
	v_fma_f32 v40, v41, s14, 0.5
	v_fma_f32 v40, v41, v40, 1.0
	v_mul_f32_e64 v40, v40, -v41
	s_or_b64 exec, exec, s[0:1]
	v_add_f32_e32 v37, v37, v73
	v_mul_f32_e32 v37, 0xbfb8aa3b, v37
	v_exp_f32_e32 v37, v37
	s_nop 0
	v_add_f32_e32 v37, 1.0, v37
	v_rcp_f32_e32 v37, v37
	s_nop 0
	v_mul_f32_e32 v37, 0xc1000000, v37
	v_mul_f32_e32 v37, v69, v37
	v_add_f32_e32 v41, v37, v37
	v_cmp_nlt_f32_e32 vcc, s51, v41
	s_and_saveexec_b64 s[0:1], vcc
	s_xor_b64 s[0:1], exec, s[0:1]
	v_mul_f32_e32 v41, 0x3fb8aa3b, v41
	v_exp_f32_e32 v41, v41
	s_nop 0
	v_sub_f32_e32 v42, 1.0, v41
	s_andn2_saveexec_b64 s[0:1], s[0:1]
	v_fma_f32 v42, v41, s14, 0.5
	v_fma_f32 v42, v41, v42, 1.0
	v_mul_f32_e64 v42, v42, -v41
	s_or_b64 exec, exec, s[0:1]
	v_add_f32_e32 v38, v38, v74
	v_mul_f32_e32 v38, 0xbfb8aa3b, v38
	v_exp_f32_e32 v38, v38
	s_nop 0
	v_add_f32_e32 v38, 1.0, v38
	v_rcp_f32_e32 v38, v38
	s_nop 0
	v_mul_f32_e32 v38, 0xc1000000, v38
	v_mul_f32_e32 v38, v70, v38
	v_add_f32_e32 v41, v38, v38
	v_cmp_nlt_f32_e32 vcc, s51, v41
	s_and_saveexec_b64 s[0:1], vcc
	s_xor_b64 s[0:1], exec, s[0:1]
	v_mul_f32_e32 v41, 0x3fb8aa3b, v41
	v_exp_f32_e32 v41, v41
	s_nop 0
	v_sub_f32_e32 v43, 1.0, v41
	s_andn2_saveexec_b64 s[0:1], s[0:1]
	v_fma_f32 v43, v41, s14, 0.5
	v_fma_f32 v43, v41, v43, 1.0
	v_mul_f32_e64 v43, v43, -v41
	s_or_b64 exec, exec, s[0:1]
	v_add_f32_e32 v39, v39, v75
	v_mul_f32_e32 v39, 0xbfb8aa3b, v39
	v_exp_f32_e32 v39, v39
	s_nop 0
	v_add_f32_e32 v39, 1.0, v39
	v_rcp_f32_e32 v39, v39
	s_nop 0
	v_mul_f32_e32 v39, 0xc1000000, v39
	v_mul_f32_e32 v39, v71, v39
	v_add_f32_e32 v44, v39, v39
	v_cmp_nlt_f32_e32 vcc, s51, v44
	s_and_saveexec_b64 s[0:1], vcc
	s_xor_b64 s[0:1], exec, s[0:1]
	v_mul_f32_e32 v41, 0x3fb8aa3b, v44
	v_exp_f32_e32 v41, v41
	s_nop 0
	v_sub_f32_e32 v41, 1.0, v41
	s_andn2_saveexec_b64 s[0:1], s[0:1]
	v_fma_f32 v41, v44, s14, 0.5
	v_fma_f32 v41, v44, v41, 1.0
	v_mul_f32_e64 v41, v41, -v44
	s_or_b64 exec, exec, s[0:1]
	v_add_f32_e32 v34, v34, v66
	v_mul_f32_e32 v34, 0xbfb8aa3b, v34
	v_exp_f32_e32 v34, v34
	v_max_f32_e32 v43, 0, v43
	v_add_f32_e32 v35, v35, v67
	v_add_f32_e32 v34, 1.0, v34
	v_mul_f32_e32 v35, 0xbfb8aa3b, v35
	v_exp_f32_e32 v35, v35
	v_add_f32_e32 v33, v33, v65
	v_rcp_f32_e32 v34, v34
	v_add_f32_e32 v35, 1.0, v35
	v_sqrt_f32_e32 v43, v43
	v_lshlrev_b32_e32 v44, 16, v49
	v_mul_f32_e32 v33, 0xbfb8aa3b, v33
	v_mul_f32_e32 v34, v34, v43
	v_mul_f32_e32 v34, v34, v44
	v_exp_f32_e32 v33, v33
	v_max_f32_e32 v42, 0, v42
	v_add_f32_e32 v33, 1.0, v33
	v_rcp_f32_e32 v35, v35
	v_add_f32_e32 v32, v32, v64
	v_mul_f32_e32 v32, 0xbfb8aa3b, v32
	v_exp_f32_e32 v32, v32
	v_rcp_f32_e32 v33, v33
	v_and_b32_e32 v43, 0xffff0000, v48
	v_sqrt_f32_e32 v42, v42
	v_add_f32_e32 v32, 1.0, v32
	v_mul_f32_e32 v33, v33, v42
	v_mul_f32_e32 v42, v33, v43
	v_max_f32_e32 v40, 0, v40
	v_lshlrev_b32_e32 v33, 16, v48
	v_readlane_b32 s0, v253, 45
	v_rcp_f32_e32 v32, v32
	v_readlane_b32 s1, v253, 46
	v_sqrt_f32_e32 v40, v40
	v_add_f32_e32 v28, v28, v72
	v_mul_f32_e32 v28, 0xbfb8aa3b, v28
	v_mul_f32_e32 v32, v32, v40
	v_mul_f32_e32 v40, v32, v33
	v_max_f32_e32 v33, 0, v41
	v_and_b32_e32 v32, 0xffff0000, v49
	v_exp_f32_e32 v28, v28
	v_sqrt_f32_e32 v33, v33
	v_add_f32_e32 v28, 1.0, v28
	v_mul_f32_e32 v33, v35, v33
	v_mul_f32_e32 v35, v33, v32
	v_cvt_pk_bf16_f32 v32, v36, v37
	v_cvt_pk_bf16_f32 v33, v38, v39
	global_store_dwordx2 v[108:109], v[32:33], off offset:128
	v_cvt_pk_bf16_f32 v32, v40, v42
	v_cvt_pk_bf16_f32 v33, v34, v35
	global_store_dwordx2 v[110:111], v[32:33], off offset:128
	v_lshl_add_u64 v[32:33], s[0:1], 0, v[112:113]
	v_lshl_add_u64 v[32:33], v[32:33], 0, v[84:85]
	global_load_dwordx2 v[34:35], v[32:33], off
	v_lshl_add_u64 v[32:33], s[0:1], 0, v[114:115]
	v_lshl_add_u64 v[32:33], v[32:33], 0, v[84:85]
	global_load_dwordx2 v[32:33], v[32:33], off
	s_nop 0
	v_rcp_f32_e32 v28, v28
	s_nop 0
	v_mul_f32_e32 v28, 0xc1000000, v28
	v_mul_f32_e32 v28, v68, v28
	v_add_f32_e32 v37, v28, v28
	v_cmp_nlt_f32_e32 vcc, s51, v37
	s_and_saveexec_b64 s[0:1], vcc
	s_xor_b64 s[0:1], exec, s[0:1]
	v_mul_f32_e32 v36, 0x3fb8aa3b, v37
	v_exp_f32_e32 v36, v36
	s_nop 0
	v_sub_f32_e32 v36, 1.0, v36
	s_andn2_saveexec_b64 s[0:1], s[0:1]
	v_fma_f32 v36, v37, s14, 0.5
	v_fma_f32 v36, v37, v36, 1.0
	v_mul_f32_e64 v36, v36, -v37
	s_or_b64 exec, exec, s[0:1]
	v_add_f32_e32 v29, v29, v73
	v_mul_f32_e32 v29, 0xbfb8aa3b, v29
	v_exp_f32_e32 v29, v29
	s_nop 0
	v_add_f32_e32 v29, 1.0, v29
	v_rcp_f32_e32 v29, v29
	s_nop 0
	v_mul_f32_e32 v29, 0xc1000000, v29
	v_mul_f32_e32 v29, v69, v29
	v_add_f32_e32 v37, v29, v29
	v_cmp_nlt_f32_e32 vcc, s51, v37
	s_and_saveexec_b64 s[0:1], vcc
	s_xor_b64 s[0:1], exec, s[0:1]
	v_mul_f32_e32 v37, 0x3fb8aa3b, v37
	v_exp_f32_e32 v37, v37
	s_nop 0
	v_sub_f32_e32 v38, 1.0, v37
	s_andn2_saveexec_b64 s[0:1], s[0:1]
	v_fma_f32 v38, v37, s14, 0.5
	v_fma_f32 v38, v37, v38, 1.0
	v_mul_f32_e64 v38, v38, -v37
	s_or_b64 exec, exec, s[0:1]
	v_add_f32_e32 v30, v30, v74
	v_mul_f32_e32 v30, 0xbfb8aa3b, v30
	v_exp_f32_e32 v30, v30
	s_nop 0
	v_add_f32_e32 v30, 1.0, v30
	v_rcp_f32_e32 v30, v30
	s_nop 0
	v_mul_f32_e32 v30, 0xc1000000, v30
	v_mul_f32_e32 v30, v70, v30
	v_add_f32_e32 v37, v30, v30
	v_cmp_nlt_f32_e32 vcc, s51, v37
	s_and_saveexec_b64 s[0:1], vcc
	s_xor_b64 s[0:1], exec, s[0:1]
	v_mul_f32_e32 v37, 0x3fb8aa3b, v37
	v_exp_f32_e32 v37, v37
	s_nop 0
	v_sub_f32_e32 v39, 1.0, v37
	s_andn2_saveexec_b64 s[0:1], s[0:1]
	v_fma_f32 v39, v37, s14, 0.5
	v_fma_f32 v39, v37, v39, 1.0
	v_mul_f32_e64 v39, v39, -v37
	s_or_b64 exec, exec, s[0:1]
	v_add_f32_e32 v31, v31, v75
	v_mul_f32_e32 v31, 0xbfb8aa3b, v31
	v_exp_f32_e32 v31, v31
	s_nop 0
	v_add_f32_e32 v31, 1.0, v31
	v_rcp_f32_e32 v31, v31
	s_nop 0
	v_mul_f32_e32 v31, 0xc1000000, v31
	v_mul_f32_e32 v31, v71, v31
	v_add_f32_e32 v40, v31, v31
	v_cmp_nlt_f32_e32 vcc, s51, v40
	s_and_saveexec_b64 s[0:1], vcc
	s_xor_b64 s[0:1], exec, s[0:1]
	v_mul_f32_e32 v37, 0x3fb8aa3b, v40
	v_exp_f32_e32 v37, v37
	s_nop 0
	v_sub_f32_e32 v37, 1.0, v37
	s_andn2_saveexec_b64 s[0:1], s[0:1]
	v_fma_f32 v37, v40, s14, 0.5
	v_fma_f32 v37, v40, v37, 1.0
	v_mul_f32_e64 v37, v37, -v40
	s_or_b64 exec, exec, s[0:1]
	v_add_f32_e32 v26, v26, v66
	v_mul_f32_e32 v26, 0xbfb8aa3b, v26
	v_exp_f32_e32 v26, v26
	v_max_f32_e32 v39, 0, v39
	v_add_f32_e32 v27, v27, v67
	v_add_f32_e32 v26, 1.0, v26
	v_mul_f32_e32 v27, 0xbfb8aa3b, v27
	v_exp_f32_e32 v27, v27
	v_add_f32_e32 v25, v25, v65
	v_rcp_f32_e32 v26, v26
	v_add_f32_e32 v27, 1.0, v27
	v_sqrt_f32_e32 v39, v39
	s_waitcnt vmcnt(0)
	v_lshlrev_b32_e32 v40, 16, v35
	v_mul_f32_e32 v25, 0xbfb8aa3b, v25
	v_mul_f32_e32 v26, v26, v39
	v_mul_f32_e32 v26, v26, v40
	v_exp_f32_e32 v25, v25
	v_max_f32_e32 v38, 0, v38
	v_add_f32_e32 v25, 1.0, v25
	v_rcp_f32_e32 v27, v27
	v_add_f32_e32 v24, v24, v64
	v_mul_f32_e32 v24, 0xbfb8aa3b, v24
	v_exp_f32_e32 v24, v24
	v_rcp_f32_e32 v25, v25
	v_and_b32_e32 v39, 0xffff0000, v34
	v_sqrt_f32_e32 v38, v38
	v_add_f32_e32 v24, 1.0, v24
	v_add_f32_e32 v20, v20, v72
	v_mul_f32_e32 v25, v25, v38
	v_mul_f32_e32 v38, v25, v39
	v_lshlrev_b32_e32 v25, 16, v34
	v_mul_f32_e32 v20, 0xbfb8aa3b, v20
	v_exp_f32_e32 v20, v20
	v_rcp_f32_e32 v24, v24
	v_max_f32_e32 v34, 0, v36
	v_add_f32_e32 v20, 1.0, v20
	s_nop 0
	v_sqrt_f32_e32 v34, v34
	s_nop 0
	v_mul_f32_e32 v24, v24, v34
	v_mul_f32_e32 v34, v24, v25
	v_max_f32_e32 v25, 0, v37
	v_and_b32_e32 v24, 0xffff0000, v35
	s_nop 0
	v_sqrt_f32_e32 v25, v25
	s_nop 0
	v_mul_f32_e32 v25, v27, v25
	v_mul_f32_e32 v27, v25, v24
	v_cvt_pk_bf16_f32 v24, v28, v29
	v_cvt_pk_bf16_f32 v25, v30, v31
	global_store_dwordx2 v[100:101], v[24:25], off offset:128
	v_cvt_pk_bf16_f32 v24, v34, v38
	v_cvt_pk_bf16_f32 v25, v26, v27
	global_store_dwordx2 v[102:103], v[24:25], off offset:128
	s_nop 0
	v_rcp_f32_e32 v20, v20
	s_nop 0
	v_mul_f32_e32 v20, 0xc1000000, v20
	v_mul_f32_e32 v20, v68, v20
	v_add_f32_e32 v25, v20, v20
	v_cmp_nlt_f32_e32 vcc, s51, v25
	s_and_saveexec_b64 s[0:1], vcc
	s_xor_b64 s[0:1], exec, s[0:1]
	v_mul_f32_e32 v24, 0x3fb8aa3b, v25
	v_exp_f32_e32 v24, v24
	s_nop 0
	v_sub_f32_e32 v24, 1.0, v24
	s_andn2_saveexec_b64 s[0:1], s[0:1]
	v_fma_f32 v24, v25, s14, 0.5
	v_fma_f32 v24, v25, v24, 1.0
	v_mul_f32_e64 v24, v24, -v25
	s_or_b64 exec, exec, s[0:1]
	v_add_f32_e32 v21, v21, v73
	v_mul_f32_e32 v21, 0xbfb8aa3b, v21
	v_exp_f32_e32 v21, v21
	s_nop 0
	v_add_f32_e32 v21, 1.0, v21
	v_rcp_f32_e32 v21, v21
	s_nop 0
	v_mul_f32_e32 v21, 0xc1000000, v21
	v_mul_f32_e32 v21, v69, v21
	v_add_f32_e32 v25, v21, v21
	v_cmp_nlt_f32_e32 vcc, s51, v25
	s_and_saveexec_b64 s[0:1], vcc
	s_xor_b64 s[0:1], exec, s[0:1]
	v_mul_f32_e32 v25, 0x3fb8aa3b, v25
	v_exp_f32_e32 v25, v25
	s_nop 0
	v_sub_f32_e32 v26, 1.0, v25
	s_andn2_saveexec_b64 s[0:1], s[0:1]
	v_fma_f32 v26, v25, s14, 0.5
	v_fma_f32 v26, v25, v26, 1.0
	v_mul_f32_e64 v26, v26, -v25
	s_or_b64 exec, exec, s[0:1]
	v_add_f32_e32 v22, v22, v74
	v_mul_f32_e32 v22, 0xbfb8aa3b, v22
	v_exp_f32_e32 v22, v22
	s_nop 0
	v_add_f32_e32 v22, 1.0, v22
	v_rcp_f32_e32 v22, v22
	s_nop 0
	v_mul_f32_e32 v22, 0xc1000000, v22
	v_mul_f32_e32 v22, v70, v22
	v_add_f32_e32 v25, v22, v22
	v_cmp_nlt_f32_e32 vcc, s51, v25
	s_and_saveexec_b64 s[0:1], vcc
	s_xor_b64 s[0:1], exec, s[0:1]
	v_mul_f32_e32 v25, 0x3fb8aa3b, v25
	v_exp_f32_e32 v25, v25
	s_nop 0
	v_sub_f32_e32 v27, 1.0, v25
	s_andn2_saveexec_b64 s[0:1], s[0:1]
	v_fma_f32 v27, v25, s14, 0.5
	v_fma_f32 v27, v25, v27, 1.0
	v_mul_f32_e64 v27, v27, -v25
	s_or_b64 exec, exec, s[0:1]
	v_add_f32_e32 v23, v23, v75
	v_mul_f32_e32 v23, 0xbfb8aa3b, v23
	v_exp_f32_e32 v23, v23
	s_nop 0
	v_add_f32_e32 v23, 1.0, v23
	v_rcp_f32_e32 v23, v23
	s_nop 0
	v_mul_f32_e32 v23, 0xc1000000, v23
	v_mul_f32_e32 v23, v71, v23
	v_add_f32_e32 v28, v23, v23
	v_cmp_nlt_f32_e32 vcc, s51, v28
	s_and_saveexec_b64 s[0:1], vcc
	s_xor_b64 s[0:1], exec, s[0:1]
	v_mul_f32_e32 v25, 0x3fb8aa3b, v28
	v_exp_f32_e32 v25, v25
	s_nop 0
	v_sub_f32_e32 v25, 1.0, v25
	s_andn2_saveexec_b64 s[0:1], s[0:1]
	v_fma_f32 v25, v28, s14, 0.5
	v_fma_f32 v25, v28, v25, 1.0
	v_mul_f32_e64 v25, v25, -v28
	s_or_b64 exec, exec, s[0:1]
	v_add_f32_e32 v18, v18, v66
	v_mul_f32_e32 v18, 0xbfb8aa3b, v18
	v_exp_f32_e32 v18, v18
	v_max_f32_e32 v27, 0, v27
	v_add_f32_e32 v19, v19, v67
	v_add_f32_e32 v18, 1.0, v18
	v_mul_f32_e32 v19, 0xbfb8aa3b, v19
	v_exp_f32_e32 v19, v19
	v_add_f32_e32 v17, v17, v65
	v_rcp_f32_e32 v18, v18
	v_add_f32_e32 v19, 1.0, v19
	v_sqrt_f32_e32 v27, v27
	v_lshlrev_b32_e32 v28, 16, v33
	v_mul_f32_e32 v17, 0xbfb8aa3b, v17
	v_mul_f32_e32 v18, v18, v27
	v_mul_f32_e32 v18, v18, v28
	v_exp_f32_e32 v17, v17
	v_max_f32_e32 v26, 0, v26
	v_add_f32_e32 v17, 1.0, v17
	v_rcp_f32_e32 v19, v19
	v_add_f32_e32 v16, v16, v64
	v_mul_f32_e32 v16, 0xbfb8aa3b, v16
	v_exp_f32_e32 v16, v16
	v_rcp_f32_e32 v17, v17
	v_and_b32_e32 v27, 0xffff0000, v32
	v_sqrt_f32_e32 v26, v26
	v_add_f32_e32 v16, 1.0, v16
	v_mul_f32_e32 v17, v17, v26
	v_mul_f32_e32 v26, v17, v27
	v_max_f32_e32 v24, 0, v24
	v_lshlrev_b32_e32 v17, 16, v32
	v_readlane_b32 s0, v253, 45
	v_rcp_f32_e32 v16, v16
	v_readlane_b32 s1, v253, 46
	v_sqrt_f32_e32 v24, v24
	v_add_f32_e32 v12, v12, v72
	v_mul_f32_e32 v12, 0xbfb8aa3b, v12
	v_mul_f32_e32 v16, v16, v24
	v_mul_f32_e32 v24, v16, v17
	v_max_f32_e32 v17, 0, v25
	v_and_b32_e32 v16, 0xffff0000, v33
	v_exp_f32_e32 v12, v12
	v_sqrt_f32_e32 v17, v17
	v_add_f32_e32 v12, 1.0, v12
	v_mul_f32_e32 v17, v19, v17
	v_mul_f32_e32 v19, v17, v16
	v_cvt_pk_bf16_f32 v16, v20, v21
	v_cvt_pk_bf16_f32 v17, v22, v23
	global_store_dwordx2 v[92:93], v[16:17], off offset:128
	v_cvt_pk_bf16_f32 v16, v24, v26
	v_cvt_pk_bf16_f32 v17, v18, v19
	global_store_dwordx2 v[94:95], v[16:17], off offset:128
	v_lshl_add_u64 v[16:17], s[0:1], 0, v[96:97]
	v_lshl_add_u64 v[16:17], v[16:17], 0, v[84:85]
	global_load_dwordx2 v[18:19], v[16:17], off
	v_lshl_add_u64 v[16:17], s[0:1], 0, v[98:99]
	v_lshl_add_u64 v[16:17], v[16:17], 0, v[84:85]
	global_load_dwordx2 v[16:17], v[16:17], off
	s_nop 0
	v_rcp_f32_e32 v12, v12
	s_nop 0
	v_mul_f32_e32 v12, 0xc1000000, v12
	v_mul_f32_e32 v12, v68, v12
	v_add_f32_e32 v21, v12, v12
	v_cmp_nlt_f32_e32 vcc, s51, v21
	s_and_saveexec_b64 s[0:1], vcc
	s_xor_b64 s[0:1], exec, s[0:1]
	v_mul_f32_e32 v20, 0x3fb8aa3b, v21
	v_exp_f32_e32 v20, v20
	s_nop 0
	v_sub_f32_e32 v20, 1.0, v20
	s_andn2_saveexec_b64 s[0:1], s[0:1]
	v_fma_f32 v20, v21, s14, 0.5
	v_fma_f32 v20, v21, v20, 1.0
	v_mul_f32_e64 v20, v20, -v21
	s_or_b64 exec, exec, s[0:1]
	v_add_f32_e32 v13, v13, v73
	v_mul_f32_e32 v13, 0xbfb8aa3b, v13
	v_exp_f32_e32 v13, v13
	s_nop 0
	v_add_f32_e32 v13, 1.0, v13
	v_rcp_f32_e32 v13, v13
	s_nop 0
	v_mul_f32_e32 v13, 0xc1000000, v13
	v_mul_f32_e32 v13, v69, v13
	v_add_f32_e32 v21, v13, v13
	v_cmp_nlt_f32_e32 vcc, s51, v21
	s_and_saveexec_b64 s[0:1], vcc
	s_xor_b64 s[0:1], exec, s[0:1]
	v_mul_f32_e32 v21, 0x3fb8aa3b, v21
	v_exp_f32_e32 v21, v21
	s_nop 0
	v_sub_f32_e32 v22, 1.0, v21
	s_andn2_saveexec_b64 s[0:1], s[0:1]
	v_fma_f32 v22, v21, s14, 0.5
	v_fma_f32 v22, v21, v22, 1.0
	v_mul_f32_e64 v22, v22, -v21
	s_or_b64 exec, exec, s[0:1]
	v_add_f32_e32 v14, v14, v74
	v_mul_f32_e32 v14, 0xbfb8aa3b, v14
	v_exp_f32_e32 v14, v14
	s_nop 0
	v_add_f32_e32 v14, 1.0, v14
	v_rcp_f32_e32 v14, v14
	s_nop 0
	v_mul_f32_e32 v14, 0xc1000000, v14
	v_mul_f32_e32 v14, v70, v14
	v_add_f32_e32 v21, v14, v14
	v_cmp_nlt_f32_e32 vcc, s51, v21
	s_and_saveexec_b64 s[0:1], vcc
	s_xor_b64 s[0:1], exec, s[0:1]
	v_mul_f32_e32 v21, 0x3fb8aa3b, v21
	v_exp_f32_e32 v21, v21
	s_nop 0
	v_sub_f32_e32 v23, 1.0, v21
	s_andn2_saveexec_b64 s[0:1], s[0:1]
	v_fma_f32 v23, v21, s14, 0.5
	v_fma_f32 v23, v21, v23, 1.0
	v_mul_f32_e64 v23, v23, -v21
	s_or_b64 exec, exec, s[0:1]
	v_add_f32_e32 v15, v15, v75
	v_mul_f32_e32 v15, 0xbfb8aa3b, v15
	v_exp_f32_e32 v15, v15
	s_nop 0
	v_add_f32_e32 v15, 1.0, v15
	v_rcp_f32_e32 v15, v15
	s_nop 0
	v_mul_f32_e32 v15, 0xc1000000, v15
	v_mul_f32_e32 v15, v71, v15
	v_add_f32_e32 v24, v15, v15
	v_cmp_nlt_f32_e32 vcc, s51, v24
	s_and_saveexec_b64 s[0:1], vcc
	s_xor_b64 s[0:1], exec, s[0:1]
	v_mul_f32_e32 v21, 0x3fb8aa3b, v24
	v_exp_f32_e32 v21, v21
	s_nop 0
	v_sub_f32_e32 v21, 1.0, v21
	s_andn2_saveexec_b64 s[0:1], s[0:1]
	v_fma_f32 v21, v24, s14, 0.5
	v_fma_f32 v21, v24, v21, 1.0
	v_mul_f32_e64 v21, v21, -v24
	s_or_b64 exec, exec, s[0:1]
	v_add_f32_e32 v10, v10, v66
	v_mul_f32_e32 v10, 0xbfb8aa3b, v10
	v_exp_f32_e32 v10, v10
	v_max_f32_e32 v23, 0, v23
	v_add_f32_e32 v11, v11, v67
	v_add_f32_e32 v10, 1.0, v10
	v_mul_f32_e32 v11, 0xbfb8aa3b, v11
	v_exp_f32_e32 v11, v11
	v_add_f32_e32 v9, v9, v65
	v_rcp_f32_e32 v10, v10
	v_add_f32_e32 v11, 1.0, v11
	v_sqrt_f32_e32 v23, v23
	s_waitcnt vmcnt(0)
	v_lshlrev_b32_e32 v24, 16, v19
	v_mul_f32_e32 v9, 0xbfb8aa3b, v9
	v_mul_f32_e32 v10, v10, v23
	v_mul_f32_e32 v10, v10, v24
	v_exp_f32_e32 v9, v9
	v_max_f32_e32 v22, 0, v22
	v_add_f32_e32 v9, 1.0, v9
	v_rcp_f32_e32 v11, v11
	v_add_f32_e32 v8, v8, v64
	v_mul_f32_e32 v8, 0xbfb8aa3b, v8
	v_exp_f32_e32 v8, v8
	v_rcp_f32_e32 v9, v9
	v_and_b32_e32 v23, 0xffff0000, v18
	v_sqrt_f32_e32 v22, v22
	v_add_f32_e32 v8, 1.0, v8
	v_add_f32_e32 v4, v4, v72
	v_mul_f32_e32 v9, v9, v22
	v_mul_f32_e32 v22, v9, v23
	v_lshlrev_b32_e32 v9, 16, v18
	v_mul_f32_e32 v4, 0xbfb8aa3b, v4
	v_exp_f32_e32 v4, v4
	v_rcp_f32_e32 v8, v8
	v_max_f32_e32 v18, 0, v20
	v_add_f32_e32 v4, 1.0, v4
	s_nop 0
	v_sqrt_f32_e32 v18, v18
	s_nop 0
	v_mul_f32_e32 v8, v8, v18
	v_mul_f32_e32 v18, v8, v9
	v_max_f32_e32 v9, 0, v21
	v_and_b32_e32 v8, 0xffff0000, v19
	s_nop 0
	v_sqrt_f32_e32 v9, v9
	s_nop 0
	v_mul_f32_e32 v9, v11, v9
	v_mul_f32_e32 v11, v9, v8
	v_cvt_pk_bf16_f32 v8, v12, v13
	v_cvt_pk_bf16_f32 v9, v14, v15
	global_store_dwordx2 v[80:81], v[8:9], off offset:128
	v_cvt_pk_bf16_f32 v8, v18, v22
	v_cvt_pk_bf16_f32 v9, v10, v11
	global_store_dwordx2 v[82:83], v[8:9], off offset:128
	s_nop 0
	v_rcp_f32_e32 v4, v4
	s_nop 0
	v_mul_f32_e32 v4, 0xc1000000, v4
	v_mul_f32_e32 v4, v68, v4
	v_add_f32_e32 v9, v4, v4
	v_cmp_nlt_f32_e32 vcc, s51, v9
	s_and_saveexec_b64 s[0:1], vcc
	s_xor_b64 s[0:1], exec, s[0:1]
	v_mul_f32_e32 v8, 0x3fb8aa3b, v9
	v_exp_f32_e32 v8, v8
	s_nop 0
	v_sub_f32_e32 v8, 1.0, v8
	s_andn2_saveexec_b64 s[0:1], s[0:1]
	v_fma_f32 v8, v9, s14, 0.5
	v_fma_f32 v8, v9, v8, 1.0
	v_mul_f32_e64 v8, v8, -v9
	s_or_b64 exec, exec, s[0:1]
	v_add_f32_e32 v5, v5, v73
	v_mul_f32_e32 v5, 0xbfb8aa3b, v5
	v_exp_f32_e32 v5, v5
	s_nop 0
	v_add_f32_e32 v5, 1.0, v5
	v_rcp_f32_e32 v5, v5
	s_nop 0
	v_mul_f32_e32 v5, 0xc1000000, v5
	v_mul_f32_e32 v5, v69, v5
	v_add_f32_e32 v9, v5, v5
	v_cmp_nlt_f32_e32 vcc, s51, v9
	s_and_saveexec_b64 s[0:1], vcc
	s_xor_b64 s[0:1], exec, s[0:1]
	v_mul_f32_e32 v9, 0x3fb8aa3b, v9
	v_exp_f32_e32 v9, v9
	s_nop 0
	v_sub_f32_e32 v10, 1.0, v9
	s_andn2_saveexec_b64 s[0:1], s[0:1]
	v_fma_f32 v10, v9, s14, 0.5
	v_fma_f32 v10, v9, v10, 1.0
	v_mul_f32_e64 v10, v10, -v9
	s_or_b64 exec, exec, s[0:1]
	v_add_f32_e32 v6, v6, v74
	v_mul_f32_e32 v6, 0xbfb8aa3b, v6
	v_exp_f32_e32 v6, v6
	s_nop 0
	v_add_f32_e32 v6, 1.0, v6
	v_rcp_f32_e32 v6, v6
	s_nop 0
	v_mul_f32_e32 v6, 0xc1000000, v6
	v_mul_f32_e32 v6, v70, v6
	v_add_f32_e32 v9, v6, v6
	v_cmp_nlt_f32_e32 vcc, s51, v9
	s_and_saveexec_b64 s[0:1], vcc
	s_xor_b64 s[0:1], exec, s[0:1]
	v_mul_f32_e32 v9, 0x3fb8aa3b, v9
	v_exp_f32_e32 v9, v9
	s_nop 0
	v_sub_f32_e32 v11, 1.0, v9
	s_andn2_saveexec_b64 s[0:1], s[0:1]
	v_fma_f32 v11, v9, s14, 0.5
	v_fma_f32 v11, v9, v11, 1.0
	v_mul_f32_e64 v11, v11, -v9
	s_or_b64 exec, exec, s[0:1]
	v_add_f32_e32 v7, v7, v75
	v_mul_f32_e32 v7, 0xbfb8aa3b, v7
	v_exp_f32_e32 v7, v7
	s_nop 0
	v_add_f32_e32 v7, 1.0, v7
	v_rcp_f32_e32 v7, v7
	s_nop 0
	v_mul_f32_e32 v7, 0xc1000000, v7
	v_mul_f32_e32 v7, v71, v7
	v_add_f32_e32 v12, v7, v7
	v_cmp_nlt_f32_e32 vcc, s51, v12
	s_and_saveexec_b64 s[0:1], vcc
	s_xor_b64 s[0:1], exec, s[0:1]
	v_mul_f32_e32 v9, 0x3fb8aa3b, v12
	v_exp_f32_e32 v9, v9
	s_nop 0
	v_sub_f32_e32 v9, 1.0, v9
	s_andn2_saveexec_b64 s[0:1], s[0:1]
	s_cbranch_execz .LBB0_446
	v_fma_f32 v9, v12, s14, 0.5
	v_fma_f32 v9, v12, v9, 1.0
	v_mul_f32_e64 v9, v9, -v12
	s_branch .LBB0_446
